# residual epilogues (down/out-proj): removed the explicit LDS drain between the per-wave tile's ds_write pair and its ds_read (same-wave LDS ops execute in order; data waits before use are kept)
# speedup vs baseline: 1.0143x; 1.0025x over previous
; __device__ __forceinline__ unsigned pkh(float lo, float hi) { if (!RES_FP16) return cvt_pk_bf16(lo, hi); f16x2 v = {(_Float16)lo, (_Float16)hi}; return __builtin_bit_cast(unsigned, v); }
;     __device__ __forceinline__ void operator()(const f32x4 (&acc)[2][2][4][2], const Unit& u, int wr, int wc, int fr, int fq) const {
;     ...
;         RES_LOAD(0, 0);
; #pragma unroll
;         for (int b = 0; b < 4; ++b) {
;             if (b + 1 < 4) RES_LOAD((b + 1) & 1, b + 1);
; #pragma unroll
;             for (int gg = 0; gg < 2; ++gg) {
;                 const int g = 2 * b + gg, ai = g >> 2, m = g & 3;
;                 const int row0 = u.pm * BM + ai * HALF + wr * 64 + m * 16 + rl;
;                 float sq[2] = {0.f, 0.f};
; #pragma unroll
;                 for (int bj = 0; bj < 2; ++bj) {
;                     *(f32x4*)(wl + fr * 36 + fq * 4) = acc[ai][bj][m][0] * alpha; *(f32x4*)(wl + fr * 36 + 16 + fq * 4) = acc[ai][bj][m][1] * alpha;
;                     asm volatile("s_waitcnt lgkmcnt(0)" ::: "memory");
; #pragma unroll
;                     for (int i = 0; i < 2; ++i) {
;                         const f32x4 x = rb[b & 1][gg][bj][i] + *(const f32x4*)(wl + (rl + 8 * i) * 36 + ch * 4);
;                         const size_t off = (size_t)(row0 + 8 * i) * 1024 + cbase + bj * HALF;
;                         u32x2 w; w.x = pkh(x[0], x[1]); w.y = pkh(x[2], x[3]); *(u32x2*)(X16 + off) = w;
;                         sq[i] += (x[0] * x[0] + x[1] * x[1]) + (x[2] * x[2] + x[3] * x[3]);
;                     }
;                     asm volatile("s_waitcnt lgkmcnt(0)" ::: "memory");
;                 }
; #pragma unroll
;                 for (int i = 0; i < 2; ++i) { float t = sq[i]; t += dpp_f(t, 0); t += dpp_f(t, 1); t += dpp_f(t, 2);
;                     if (ch == 0) ss[(size_t)(row0 + 8 * i) * 16 + u.pn * 4 + wc] = t; }
.LBB0_315:
	s_ashr_i32 s29, s28, 31
	s_lshl_b64 s[30:31], s[28:29], 8
	v_mov_b32_e32 v139, s31
	v_or_b32_e32 v138, s30, v130
	v_lshl_add_u32 v142, s84, 8, v196
	v_lshlrev_b64 v[138:139], 1, v[138:139]
	v_ashrrev_i32_e32 v143, 31, v142
	v_lshl_add_u64 v[140:141], s[74:75], 0, v[138:139]
	v_lshlrev_b64 v[200:201], 11, v[142:143]
	v_lshl_add_u64 v[144:145], v[140:141], 0, v[200:201]
	global_load_dwordx2 v[202:203], v[144:145], off
	v_or_b32_e32 v184, 8, v142
	v_ashrrev_i32_e32 v185, 31, v184
	v_lshlrev_b64 v[204:205], 11, v[184:185]
	v_lshl_add_u64 v[146:147], v[140:141], 0, v[204:205]
	global_load_dwordx2 v[206:207], v[146:147], off
	global_load_dwordx2 v[212:213], v[146:147], off offset:256
	global_load_dwordx2 v[214:215], v[144:145], off offset:256
	v_or_b32_e32 v178, 16, v142
	v_or_b32_e32 v176, 24, v142
	v_or_b32_e32 v156, 32, v142
	v_or_b32_e32 v154, 40, v142
	v_or_b32_e32 v146, 48, v142
	v_or_b32_e32 v144, 56, v142
	v_ashrrev_i32_e32 v179, 31, v178
	v_ashrrev_i32_e32 v177, 31, v176
	v_ashrrev_i32_e32 v157, 31, v156
	v_ashrrev_i32_e32 v155, 31, v154
	v_ashrrev_i32_e32 v147, 31, v146
	v_ashrrev_i32_e32 v145, 31, v144
	v_lshlrev_b64 v[182:183], 11, v[178:179]
	v_lshlrev_b64 v[180:181], 11, v[176:177]
	v_lshlrev_b64 v[166:167], 11, v[156:157]
	v_lshlrev_b64 v[164:165], 11, v[154:155]
	v_lshlrev_b64 v[150:151], 11, v[146:147]
	v_lshlrev_b64 v[148:149], 11, v[144:145]
	v_lshl_add_u64 v[152:153], v[140:141], 0, v[182:183]
	v_lshl_add_u64 v[158:159], v[140:141], 0, v[180:181]
	v_lshl_add_u64 v[160:161], v[140:141], 0, v[166:167]
	v_lshl_add_u64 v[162:163], v[140:141], 0, v[164:165]
	v_lshl_add_u64 v[216:217], v[140:141], 0, v[150:151]
	v_lshl_add_u64 v[218:219], v[140:141], 0, v[148:149]
	global_load_dwordx2 v[194:195], v[152:153], off
	global_load_dwordx2 v[190:191], v[158:159], off
	global_load_dwordx2 v[186:187], v[158:159], off offset:256
	global_load_dwordx2 v[188:189], v[152:153], off offset:256
	global_load_dwordx2 v[174:175], v[160:161], off
	global_load_dwordx2 v[172:173], v[162:163], off
	global_load_dwordx2 v[168:169], v[162:163], off offset:256
	global_load_dwordx2 v[170:171], v[160:161], off offset:256
	s_nop 0
	global_load_dwordx2 v[162:163], v[216:217], off
	global_load_dwordx2 v[160:161], v[218:219], off
	global_load_dwordx2 v[152:153], v[218:219], off offset:256
	global_load_dwordx2 v[158:159], v[216:217], off offset:256
	v_mov_b32_e32 v193, v192
	v_pk_mul_f32 v[120:121], v[120:121], v[132:133]
	v_pk_mul_f32 v[122:123], v[122:123], v[192:193]
	v_pk_mul_f32 v[124:125], v[124:125], v[132:133]
	v_pk_mul_f32 v[126:127], v[126:127], v[192:193]
	ds_write_b128 v197, v[120:123]
	ds_write_b128 v197, v[124:127] offset:64
	v_lshl_add_u64 v[120:121], s[74:75], 0, v[200:201]
	v_lshl_add_u64 v[126:127], v[120:121], 0, v[138:139]
	ds_read_b128 v[120:123], v198
	v_lshl_add_u64 v[200:201], s[74:75], 0, v[204:205]
	v_lshl_add_u64 v[200:201], v[200:201], 0, v[138:139]
	v_pk_mul_f32 v[118:119], v[118:119], v[192:193]
	v_pk_mul_f32 v[116:117], v[116:117], v[132:133]
	v_pk_mul_f32 v[114:115], v[114:115], v[192:193]
	v_pk_mul_f32 v[112:113], v[112:113], v[132:133]
	s_lshl_b32 s28, s28, 2
	s_ashr_i32 s29, s28, 31
	s_lshl_b64 s[28:29], s[28:29], 2
	s_add_u32 s28, s67, s28
	s_addc_u32 s29, s68, s29
	s_waitcnt vmcnt(0)
	v_lshlrev_b32_e32 v124, 16, v202
	v_and_b32_e32 v125, 0xffff0000, v202
	v_lshlrev_b32_e32 v202, 16, v203
	v_and_b32_e32 v203, 0xffff0000, v203
	s_waitcnt lgkmcnt(0)
	v_pk_add_f32 v[202:203], v[122:123], v[202:203]
	v_pk_add_f32 v[220:221], v[120:121], v[124:125]
	v_lshlrev_b32_e32 v204, 16, v206
	v_cvt_pk_bf16_f32 v120, v220, v221
	v_cvt_pk_bf16_f32 v121, v202, v203
	ds_read_b128 v[122:125], v198 offset:1152
	v_and_b32_e32 v205, 0xffff0000, v206
	v_lshlrev_b32_e32 v206, 16, v207
	v_and_b32_e32 v207, 0xffff0000, v207
	global_store_dwordx2 v[126:127], v[120:121], off
	s_waitcnt lgkmcnt(0)
	v_pk_add_f32 v[120:121], v[124:125], v[206:207]
	v_pk_add_f32 v[122:123], v[122:123], v[204:205]
	v_lshlrev_b32_e32 v216, 16, v214
	v_cvt_pk_bf16_f32 v124, v122, v123
	v_cvt_pk_bf16_f32 v125, v120, v121
	global_store_dwordx2 v[200:201], v[124:125], off
	s_waitcnt lgkmcnt(0)
	ds_write_b128 v197, v[116:119]
	ds_write_b128 v197, v[112:115] offset:64
	ds_read_b128 v[112:115], v198
	v_and_b32_e32 v217, 0xffff0000, v214
	v_lshlrev_b32_e32 v214, 16, v215
	v_and_b32_e32 v215, 0xffff0000, v215
	v_mul_f32_e32 v211, v221, v221
	v_mul_f32_e32 v116, v203, v203
	v_fmac_f32_e32 v211, v220, v220
	v_fmac_f32_e32 v116, v202, v202
	s_waitcnt lgkmcnt(0)
	v_pk_add_f32 v[118:119], v[114:115], v[214:215]
	v_pk_add_f32 v[112:113], v[112:113], v[216:217]
	v_add_f32_e32 v124, v211, v116
	v_cvt_pk_bf16_f32 v114, v112, v113
	v_cvt_pk_bf16_f32 v115, v118, v119
	global_store_dwordx2 v[126:127], v[114:115], off offset:256
	ds_read_b128 v[114:117], v198 offset:1152
	v_mul_f32_e32 v113, v113, v113
	v_fmac_f32_e32 v113, v112, v112
	v_mul_f32_e32 v112, v119, v119
	v_fmac_f32_e32 v112, v118, v118
	v_lshlrev_b32_e32 v218, 16, v212
	v_and_b32_e32 v219, 0xffff0000, v212
	v_lshlrev_b32_e32 v212, 16, v213
	v_and_b32_e32 v213, 0xffff0000, v213
	v_add_f32_e32 v112, v113, v112
	v_add_f32_e32 v118, v124, v112
	s_waitcnt lgkmcnt(0)
	v_pk_add_f32 v[112:113], v[116:117], v[212:213]
	v_pk_add_f32 v[114:115], v[114:115], v[218:219]
	s_nop 0
	v_cvt_pk_bf16_f32 v116, v114, v115
	v_cvt_pk_bf16_f32 v117, v112, v113
	global_store_dwordx2 v[200:201], v[116:117], off offset:256
	s_waitcnt lgkmcnt(0)
	s_nop 0
	v_add_f32_dpp v116, v118, v118 quad_perm:[1,0,3,2] row_mask:0xf bank_mask:0xf bound_ctrl:1
	s_nop 1
	v_add_f32_dpp v116, v116, v116 quad_perm:[2,3,0,1] row_mask:0xf bank_mask:0xf bound_ctrl:1
	s_nop 1
	v_mov_b32_dpp v117, v116 row_shl:4 row_mask:0xf bank_mask:0xf bound_ctrl:1
	s_and_saveexec_b64 s[30:31], s[38:39]
	s_cbranch_execz .LBB0_317
	v_add_f32_e32 v118, v116, v117
	v_lshlrev_b64 v[116:117], 6, v[142:143]
	v_lshl_add_u64 v[116:117], s[28:29], 0, v[116:117]
	global_store_dword v[116:117], v118, off

; __device__ __forceinline__ unsigned pkh(float lo, float hi) { if (!RES_FP16) return cvt_pk_bf16(lo, hi); f16x2 v = {(_Float16)lo, (_Float16)hi}; return __builtin_bit_cast(unsigned, v); }
;     __device__ __forceinline__ void operator()(const f32x4 (&acc)[2][2][4][2], const Unit& u, int wr, int wc, int fr, int fq) const {
;     ...
;             for (int gg = 0; gg < 2; ++gg) {
;                 const int g = 2 * b + gg, ai = g >> 2, m = g & 3;
;                 const int row0 = u.pm * BM + ai * HALF + wr * 64 + m * 16 + rl;
;                 float sq[2] = {0.f, 0.f};
; #pragma unroll
;                 for (int bj = 0; bj < 2; ++bj) {
;                     *(f32x4*)(wl + fr * 36 + fq * 4) = acc[ai][bj][m][0] * alpha; *(f32x4*)(wl + fr * 36 + 16 + fq * 4) = acc[ai][bj][m][1] * alpha;
;                     asm volatile("s_waitcnt lgkmcnt(0)" ::: "memory");
; #pragma unroll
;                     for (int i = 0; i < 2; ++i) {
;                         const f32x4 x = rb[b & 1][gg][bj][i] + *(const f32x4*)(wl + (rl + 8 * i) * 36 + ch * 4);
;                         const size_t off = (size_t)(row0 + 8 * i) * 1024 + cbase + bj * HALF;
;                         u32x2 w; w.x = pkh(x[0], x[1]); w.y = pkh(x[2], x[3]); *(u32x2*)(X16 + off) = w;
;                         sq[i] += (x[0] * x[0] + x[1] * x[1]) + (x[2] * x[2] + x[3] * x[3]);
;                     }
;                     asm volatile("s_waitcnt lgkmcnt(0)" ::: "memory");
;                 }
; #pragma unroll
;                 for (int i = 0; i < 2; ++i) { float t = sq[i]; t += dpp_f(t, 0); t += dpp_f(t, 1); t += dpp_f(t, 2);
;                     if (ch == 0) ss[(size_t)(row0 + 8 * i) * 16 + u.pn * 4 + wc] = t; }
.LBB0_319:
	s_or_b64 exec, exec, s[30:31]
	v_mov_b32_e32 v193, v192
	v_pk_mul_f32 v[110:111], v[110:111], v[192:193]
	v_pk_mul_f32 v[108:109], v[108:109], v[132:133]
	v_pk_mul_f32 v[106:107], v[106:107], v[192:193]
	v_pk_mul_f32 v[104:105], v[104:105], v[132:133]
	ds_write_b128 v197, v[108:111]
	ds_write_b128 v197, v[104:107] offset:64
	ds_read_b128 v[104:107], v198
	v_lshlrev_b32_e32 v112, 16, v194
	v_and_b32_e32 v113, 0xffff0000, v194
	v_lshlrev_b32_e32 v114, 16, v195
	v_and_b32_e32 v115, 0xffff0000, v195
	s_waitcnt lgkmcnt(0)
	v_pk_add_f32 v[114:115], v[106:107], v[114:115]
	v_pk_add_f32 v[112:113], v[104:105], v[112:113]
	v_lshlrev_b32_e32 v116, 16, v190
	v_cvt_pk_bf16_f32 v104, v112, v113
	v_cvt_pk_bf16_f32 v105, v114, v115
	ds_read_b128 v[106:109], v198 offset:1152
	v_and_b32_e32 v117, 0xffff0000, v190
	v_lshl_add_u64 v[126:127], s[74:75], 0, v[182:183]
	v_lshlrev_b32_e32 v118, 16, v191
	v_and_b32_e32 v119, 0xffff0000, v191
	s_waitcnt lgkmcnt(0)
	v_pk_add_f32 v[106:107], v[106:107], v[116:117]
	v_lshl_add_u64 v[116:117], s[74:75], 0, v[180:181]
	v_lshl_add_u64 v[126:127], v[126:127], 0, v[138:139]
	v_lshl_add_u64 v[116:117], v[116:117], 0, v[138:139]
	global_store_dwordx2 v[126:127], v[104:105], off
	v_pk_add_f32 v[104:105], v[108:109], v[118:119]
	v_cvt_pk_bf16_f32 v108, v106, v107
	v_pk_mul_f32 v[102:103], v[102:103], v[192:193]
	v_cvt_pk_bf16_f32 v109, v104, v105
	global_store_dwordx2 v[116:117], v[108:109], off
	v_pk_mul_f32 v[100:101], v[100:101], v[132:133]
	v_pk_mul_f32 v[98:99], v[98:99], v[192:193]
	v_pk_mul_f32 v[96:97], v[96:97], v[132:133]
	s_waitcnt lgkmcnt(0)
	ds_write_b128 v197, v[100:103]
	ds_write_b128 v197, v[96:99] offset:64
	ds_read_b128 v[96:99], v198
	v_lshlrev_b32_e32 v120, 16, v188
	v_and_b32_e32 v121, 0xffff0000, v188
	v_lshlrev_b32_e32 v122, 16, v189
	v_and_b32_e32 v123, 0xffff0000, v189
	v_mul_f32_e32 v113, v113, v113
	v_mul_f32_e32 v100, v115, v115
	v_fmac_f32_e32 v113, v112, v112
	v_fmac_f32_e32 v100, v114, v114
	s_waitcnt lgkmcnt(0)
	v_pk_add_f32 v[102:103], v[98:99], v[122:123]
	v_pk_add_f32 v[96:97], v[96:97], v[120:121]
	v_add_f32_e32 v108, v113, v100
	v_cvt_pk_bf16_f32 v98, v96, v97
	v_cvt_pk_bf16_f32 v99, v102, v103
	global_store_dwordx2 v[126:127], v[98:99], off offset:256
	ds_read_b128 v[98:101], v198 offset:1152
	v_mul_f32_e32 v97, v97, v97
	v_fmac_f32_e32 v97, v96, v96
	v_mul_f32_e32 v96, v103, v103
	v_fmac_f32_e32 v96, v102, v102
	v_lshlrev_b32_e32 v110, 16, v186
	v_and_b32_e32 v111, 0xffff0000, v186
	v_lshlrev_b32_e32 v124, 16, v187
	v_and_b32_e32 v125, 0xffff0000, v187
	v_add_f32_e32 v96, v97, v96
	v_add_f32_e32 v102, v108, v96
	s_waitcnt lgkmcnt(0)
	v_pk_add_f32 v[96:97], v[100:101], v[124:125]
	v_pk_add_f32 v[98:99], v[98:99], v[110:111]
	s_nop 0
	v_cvt_pk_bf16_f32 v100, v98, v99
	v_cvt_pk_bf16_f32 v101, v96, v97
	global_store_dwordx2 v[116:117], v[100:101], off offset:256
	s_waitcnt lgkmcnt(0)
	s_nop 0
	v_add_f32_dpp v100, v102, v102 quad_perm:[1,0,3,2] row_mask:0xf bank_mask:0xf bound_ctrl:1
	s_nop 1
	v_add_f32_dpp v100, v100, v100 quad_perm:[2,3,0,1] row_mask:0xf bank_mask:0xf bound_ctrl:1
	s_nop 1
	v_mov_b32_dpp v101, v100 row_shl:4 row_mask:0xf bank_mask:0xf bound_ctrl:1
	s_and_saveexec_b64 s[30:31], s[38:39]
	s_cbranch_execz .LBB0_321
	v_add_f32_e32 v102, v100, v101
	v_lshlrev_b64 v[100:101], 6, v[178:179]
	v_lshl_add_u64 v[100:101], s[28:29], 0, v[100:101]
	global_store_dword v[100:101], v102, off

; __device__ __forceinline__ unsigned pkh(float lo, float hi) { if (!RES_FP16) return cvt_pk_bf16(lo, hi); f16x2 v = {(_Float16)lo, (_Float16)hi}; return __builtin_bit_cast(unsigned, v); }
;     __device__ __forceinline__ void operator()(const f32x4 (&acc)[2][2][4][2], const Unit& u, int wr, int wc, int fr, int fq) const {
;     ...
;         RES_LOAD(0, 0);
; #pragma unroll
;         for (int b = 0; b < 4; ++b) {
;             if (b + 1 < 4) RES_LOAD((b + 1) & 1, b + 1);
; #pragma unroll
;             for (int gg = 0; gg < 2; ++gg) {
;                 const int g = 2 * b + gg, ai = g >> 2, m = g & 3;
;                 const int row0 = u.pm * BM + ai * HALF + wr * 64 + m * 16 + rl;
;                 float sq[2] = {0.f, 0.f};
; #pragma unroll
;                 for (int bj = 0; bj < 2; ++bj) {
;                     *(f32x4*)(wl + fr * 36 + fq * 4) = acc[ai][bj][m][0] * alpha; *(f32x4*)(wl + fr * 36 + 16 + fq * 4) = acc[ai][bj][m][1] * alpha;
;                     asm volatile("s_waitcnt lgkmcnt(0)" ::: "memory");
; #pragma unroll
;                     for (int i = 0; i < 2; ++i) {
;                         const f32x4 x = rb[b & 1][gg][bj][i] + *(const f32x4*)(wl + (rl + 8 * i) * 36 + ch * 4);
;                         const size_t off = (size_t)(row0 + 8 * i) * 1024 + cbase + bj * HALF;
;                         u32x2 w; w.x = pkh(x[0], x[1]); w.y = pkh(x[2], x[3]); *(u32x2*)(X16 + off) = w;
;                         sq[i] += (x[0] * x[0] + x[1] * x[1]) + (x[2] * x[2] + x[3] * x[3]);
;                     }
;                     asm volatile("s_waitcnt lgkmcnt(0)" ::: "memory");
;                 }
; #pragma unroll
;                 for (int i = 0; i < 2; ++i) { float t = sq[i]; t += dpp_f(t, 0); t += dpp_f(t, 1); t += dpp_f(t, 2);
;                     if (ch == 0) ss[(size_t)(row0 + 8 * i) * 16 + u.pn * 4 + wc] = t; }
.LBB0_323:
	s_or_b64 exec, exec, s[30:31]
	v_add_u32_e32 v112, 0x80, v142
	v_add_u32_e32 v104, 0x88, v142
	v_ashrrev_i32_e32 v113, 31, v112
	v_ashrrev_i32_e32 v105, 31, v104
	v_lshlrev_b64 v[114:115], 11, v[112:113]
	v_lshlrev_b64 v[98:99], 11, v[104:105]
	v_lshl_add_u64 v[96:97], v[140:141], 0, v[114:115]
	v_lshl_add_u64 v[98:99], v[140:141], 0, v[98:99]
	global_load_dwordx2 v[122:123], v[96:97], off
	global_load_dwordx2 v[120:121], v[98:99], off
	global_load_dwordx2 v[116:117], v[98:99], off offset:256
	global_load_dwordx2 v[118:119], v[96:97], off offset:256
	v_add_u32_e32 v98, 0x90, v142
	v_add_u32_e32 v96, 0x98, v142
	v_ashrrev_i32_e32 v99, 31, v98
	v_ashrrev_i32_e32 v97, 31, v96
	v_lshlrev_b64 v[100:101], 11, v[98:99]
	v_lshlrev_b64 v[102:103], 11, v[96:97]
	v_lshl_add_u64 v[106:107], v[140:141], 0, v[100:101]
	v_lshl_add_u64 v[102:103], v[140:141], 0, v[102:103]
	global_load_dwordx2 v[110:111], v[106:107], off
	global_load_dwordx2 v[108:109], v[102:103], off
	s_nop 0
	global_load_dwordx2 v[102:103], v[102:103], off offset:256
	s_nop 0
	global_load_dwordx2 v[106:107], v[106:107], off offset:256
	v_mov_b32_e32 v193, v192
	v_pk_mul_f32 v[94:95], v[94:95], v[192:193]
	v_pk_mul_f32 v[92:93], v[92:93], v[132:133]
	v_pk_mul_f32 v[90:91], v[90:91], v[192:193]
	v_pk_mul_f32 v[88:89], v[88:89], v[132:133]
	ds_write_b128 v197, v[92:95]
	ds_write_b128 v197, v[88:91] offset:64
	ds_read_b128 v[88:91], v198
	v_lshlrev_b32_e32 v124, 16, v174
	v_and_b32_e32 v125, 0xffff0000, v174
	v_lshlrev_b32_e32 v126, 16, v175
	v_and_b32_e32 v127, 0xffff0000, v175
	s_waitcnt lgkmcnt(0)
	v_pk_add_f32 v[126:127], v[90:91], v[126:127]
	v_pk_add_f32 v[124:125], v[88:89], v[124:125]
	v_lshl_add_u64 v[166:167], s[74:75], 0, v[166:167]
	v_cvt_pk_bf16_f32 v88, v124, v125
	v_cvt_pk_bf16_f32 v89, v126, v127
	ds_read_b128 v[90:93], v198 offset:1152
	v_lshl_add_u64 v[164:165], s[74:75], 0, v[164:165]
	v_lshlrev_b32_e32 v174, 16, v172
	v_and_b32_e32 v175, 0xffff0000, v172
	v_lshlrev_b32_e32 v172, 16, v173
	v_and_b32_e32 v173, 0xffff0000, v173
	v_lshl_add_u64 v[166:167], v[166:167], 0, v[138:139]
	v_lshl_add_u64 v[164:165], v[164:165], 0, v[138:139]
	global_store_dwordx2 v[166:167], v[88:89], off
	s_waitcnt lgkmcnt(0)
	v_pk_add_f32 v[88:89], v[92:93], v[172:173]
	v_pk_add_f32 v[90:91], v[90:91], v[174:175]
	v_pk_mul_f32 v[86:87], v[86:87], v[192:193]
	v_cvt_pk_bf16_f32 v92, v90, v91
	v_cvt_pk_bf16_f32 v93, v88, v89
	global_store_dwordx2 v[164:165], v[92:93], off
	v_pk_mul_f32 v[84:85], v[84:85], v[132:133]
	v_pk_mul_f32 v[82:83], v[82:83], v[192:193]
	v_pk_mul_f32 v[80:81], v[80:81], v[132:133]
	s_waitcnt lgkmcnt(0)
	ds_write_b128 v197, v[84:87]
	ds_write_b128 v197, v[80:83] offset:64
	ds_read_b128 v[80:83], v198
	v_lshlrev_b32_e32 v176, 16, v170
	v_and_b32_e32 v177, 0xffff0000, v170
	v_lshlrev_b32_e32 v170, 16, v171
	v_and_b32_e32 v171, 0xffff0000, v171
	v_mul_f32_e32 v125, v125, v125
	v_mul_f32_e32 v84, v127, v127
	v_fmac_f32_e32 v125, v124, v124
	v_fmac_f32_e32 v84, v126, v126
	s_waitcnt lgkmcnt(0)
	v_pk_add_f32 v[86:87], v[82:83], v[170:171]
	v_pk_add_f32 v[80:81], v[80:81], v[176:177]
	v_add_f32_e32 v92, v125, v84
	v_cvt_pk_bf16_f32 v82, v80, v81
	v_cvt_pk_bf16_f32 v83, v86, v87
	global_store_dwordx2 v[166:167], v[82:83], off offset:256
	ds_read_b128 v[82:85], v198 offset:1152
	v_mul_f32_e32 v81, v81, v81
	v_fmac_f32_e32 v81, v80, v80
	v_mul_f32_e32 v80, v87, v87
	v_fmac_f32_e32 v80, v86, v86
	v_lshlrev_b32_e32 v94, 16, v168
	v_and_b32_e32 v95, 0xffff0000, v168
	v_lshlrev_b32_e32 v168, 16, v169
	v_and_b32_e32 v169, 0xffff0000, v169
	v_add_f32_e32 v80, v81, v80
	v_add_f32_e32 v86, v92, v80
	s_waitcnt lgkmcnt(0)
	v_pk_add_f32 v[80:81], v[84:85], v[168:169]
	v_pk_add_f32 v[82:83], v[82:83], v[94:95]
	s_nop 0
	v_cvt_pk_bf16_f32 v84, v82, v83
	v_cvt_pk_bf16_f32 v85, v80, v81
	global_store_dwordx2 v[164:165], v[84:85], off offset:256
	s_waitcnt lgkmcnt(0)
	s_nop 0
	v_add_f32_dpp v84, v86, v86 quad_perm:[1,0,3,2] row_mask:0xf bank_mask:0xf bound_ctrl:1
	s_nop 1
	v_add_f32_dpp v84, v84, v84 quad_perm:[2,3,0,1] row_mask:0xf bank_mask:0xf bound_ctrl:1
	s_nop 1
	v_mov_b32_dpp v85, v84 row_shl:4 row_mask:0xf bank_mask:0xf bound_ctrl:1
	s_and_saveexec_b64 s[30:31], s[38:39]
	s_cbranch_execz .LBB0_325
	v_add_f32_e32 v86, v84, v85
	v_lshlrev_b64 v[84:85], 6, v[156:157]
	v_lshl_add_u64 v[84:85], s[28:29], 0, v[84:85]
	global_store_dword v[84:85], v86, off

; __device__ __forceinline__ unsigned pkh(float lo, float hi) { if (!RES_FP16) return cvt_pk_bf16(lo, hi); f16x2 v = {(_Float16)lo, (_Float16)hi}; return __builtin_bit_cast(unsigned, v); }
;     __device__ __forceinline__ void operator()(const f32x4 (&acc)[2][2][4][2], const Unit& u, int wr, int wc, int fr, int fq) const {
;     ...
;             for (int gg = 0; gg < 2; ++gg) {
;                 const int g = 2 * b + gg, ai = g >> 2, m = g & 3;
;                 const int row0 = u.pm * BM + ai * HALF + wr * 64 + m * 16 + rl;
;                 float sq[2] = {0.f, 0.f};
; #pragma unroll
;                 for (int bj = 0; bj < 2; ++bj) {
;                     *(f32x4*)(wl + fr * 36 + fq * 4) = acc[ai][bj][m][0] * alpha; *(f32x4*)(wl + fr * 36 + 16 + fq * 4) = acc[ai][bj][m][1] * alpha;
;                     asm volatile("s_waitcnt lgkmcnt(0)" ::: "memory");
; #pragma unroll
;                     for (int i = 0; i < 2; ++i) {
;                         const f32x4 x = rb[b & 1][gg][bj][i] + *(const f32x4*)(wl + (rl + 8 * i) * 36 + ch * 4);
;                         const size_t off = (size_t)(row0 + 8 * i) * 1024 + cbase + bj * HALF;
;                         u32x2 w; w.x = pkh(x[0], x[1]); w.y = pkh(x[2], x[3]); *(u32x2*)(X16 + off) = w;
;                         sq[i] += (x[0] * x[0] + x[1] * x[1]) + (x[2] * x[2] + x[3] * x[3]);
;                     }
;                     asm volatile("s_waitcnt lgkmcnt(0)" ::: "memory");
;                 }
; #pragma unroll
;                 for (int i = 0; i < 2; ++i) { float t = sq[i]; t += dpp_f(t, 0); t += dpp_f(t, 1); t += dpp_f(t, 2);
;                     if (ch == 0) ss[(size_t)(row0 + 8 * i) * 16 + u.pn * 4 + wc] = t; }
.LBB0_327:
	s_or_b64 exec, exec, s[30:31]
	v_mov_b32_e32 v193, v192
	v_pk_mul_f32 v[78:79], v[78:79], v[192:193]
	v_pk_mul_f32 v[76:77], v[76:77], v[132:133]
	v_pk_mul_f32 v[74:75], v[74:75], v[192:193]
	v_pk_mul_f32 v[72:73], v[72:73], v[132:133]
	ds_write_b128 v197, v[76:79]
	ds_write_b128 v197, v[72:75] offset:64
	ds_read_b128 v[72:75], v198
	v_lshlrev_b32_e32 v80, 16, v162
	v_and_b32_e32 v81, 0xffff0000, v162
	v_lshlrev_b32_e32 v82, 16, v163
	v_and_b32_e32 v83, 0xffff0000, v163
	s_waitcnt lgkmcnt(0)
	v_pk_add_f32 v[82:83], v[74:75], v[82:83]
	v_pk_add_f32 v[80:81], v[72:73], v[80:81]
	v_lshlrev_b32_e32 v84, 16, v160
	v_cvt_pk_bf16_f32 v72, v80, v81
	v_cvt_pk_bf16_f32 v73, v82, v83
	ds_read_b128 v[74:77], v198 offset:1152
	v_and_b32_e32 v85, 0xffff0000, v160
	v_lshl_add_u64 v[94:95], s[74:75], 0, v[150:151]
	v_lshlrev_b32_e32 v86, 16, v161
	v_and_b32_e32 v87, 0xffff0000, v161
	s_waitcnt lgkmcnt(0)
	v_pk_add_f32 v[74:75], v[74:75], v[84:85]
	v_lshl_add_u64 v[84:85], s[74:75], 0, v[148:149]
	v_lshl_add_u64 v[94:95], v[94:95], 0, v[138:139]
	v_lshl_add_u64 v[84:85], v[84:85], 0, v[138:139]
	global_store_dwordx2 v[94:95], v[72:73], off
	v_pk_add_f32 v[72:73], v[76:77], v[86:87]
	v_cvt_pk_bf16_f32 v76, v74, v75
	v_pk_mul_f32 v[70:71], v[70:71], v[192:193]
	v_cvt_pk_bf16_f32 v77, v72, v73
	global_store_dwordx2 v[84:85], v[76:77], off
	v_pk_mul_f32 v[68:69], v[68:69], v[132:133]
	v_pk_mul_f32 v[66:67], v[66:67], v[192:193]
	v_pk_mul_f32 v[64:65], v[64:65], v[132:133]
	s_waitcnt lgkmcnt(0)
	ds_write_b128 v197, v[68:71]
	ds_write_b128 v197, v[64:67] offset:64
	ds_read_b128 v[64:67], v198
	v_lshlrev_b32_e32 v88, 16, v158
	v_and_b32_e32 v89, 0xffff0000, v158
	v_lshlrev_b32_e32 v90, 16, v159
	v_and_b32_e32 v91, 0xffff0000, v159
	v_mul_f32_e32 v81, v81, v81
	v_mul_f32_e32 v68, v83, v83
	v_fmac_f32_e32 v81, v80, v80
	v_fmac_f32_e32 v68, v82, v82
	s_waitcnt lgkmcnt(0)
	v_pk_add_f32 v[70:71], v[66:67], v[90:91]
	v_pk_add_f32 v[64:65], v[64:65], v[88:89]
	v_add_f32_e32 v76, v81, v68
	v_cvt_pk_bf16_f32 v66, v64, v65
	v_cvt_pk_bf16_f32 v67, v70, v71
	global_store_dwordx2 v[94:95], v[66:67], off offset:256
	ds_read_b128 v[66:69], v198 offset:1152
	v_mul_f32_e32 v65, v65, v65
	v_fmac_f32_e32 v65, v64, v64
	v_mul_f32_e32 v64, v71, v71
	v_fmac_f32_e32 v64, v70, v70
	v_lshlrev_b32_e32 v78, 16, v152
	v_and_b32_e32 v79, 0xffff0000, v152
	v_lshlrev_b32_e32 v92, 16, v153
	v_and_b32_e32 v93, 0xffff0000, v153
	v_add_f32_e32 v64, v65, v64
	v_add_f32_e32 v70, v76, v64
	s_waitcnt lgkmcnt(0)
	v_pk_add_f32 v[64:65], v[68:69], v[92:93]
	v_pk_add_f32 v[66:67], v[66:67], v[78:79]
	s_nop 0
	v_cvt_pk_bf16_f32 v68, v66, v67
	v_cvt_pk_bf16_f32 v69, v64, v65
	global_store_dwordx2 v[84:85], v[68:69], off offset:256
	s_waitcnt lgkmcnt(0)
	s_nop 0
	v_add_f32_dpp v68, v70, v70 quad_perm:[1,0,3,2] row_mask:0xf bank_mask:0xf bound_ctrl:1
	s_nop 1
	v_add_f32_dpp v68, v68, v68 quad_perm:[2,3,0,1] row_mask:0xf bank_mask:0xf bound_ctrl:1
	s_nop 1
	v_mov_b32_dpp v69, v68 row_shl:4 row_mask:0xf bank_mask:0xf bound_ctrl:1
	s_and_saveexec_b64 s[30:31], s[38:39]
	s_cbranch_execz .LBB0_329
	v_add_f32_e32 v70, v68, v69
	v_lshlrev_b64 v[68:69], 6, v[146:147]
	v_lshl_add_u64 v[68:69], s[28:29], 0, v[68:69]
	global_store_dword v[68:69], v70, off

; __device__ __forceinline__ unsigned pkh(float lo, float hi) { if (!RES_FP16) return cvt_pk_bf16(lo, hi); f16x2 v = {(_Float16)lo, (_Float16)hi}; return __builtin_bit_cast(unsigned, v); }
;     __device__ __forceinline__ void operator()(const f32x4 (&acc)[2][2][4][2], const Unit& u, int wr, int wc, int fr, int fq) const {
;     ...
;         RES_LOAD(0, 0);
; #pragma unroll
;         for (int b = 0; b < 4; ++b) {
;             if (b + 1 < 4) RES_LOAD((b + 1) & 1, b + 1);
; #pragma unroll
;             for (int gg = 0; gg < 2; ++gg) {
;                 const int g = 2 * b + gg, ai = g >> 2, m = g & 3;
;                 const int row0 = u.pm * BM + ai * HALF + wr * 64 + m * 16 + rl;
;                 float sq[2] = {0.f, 0.f};
; #pragma unroll
;                 for (int bj = 0; bj < 2; ++bj) {
;                     *(f32x4*)(wl + fr * 36 + fq * 4) = acc[ai][bj][m][0] * alpha; *(f32x4*)(wl + fr * 36 + 16 + fq * 4) = acc[ai][bj][m][1] * alpha;
;                     asm volatile("s_waitcnt lgkmcnt(0)" ::: "memory");
; #pragma unroll
;                     for (int i = 0; i < 2; ++i) {
;                         const f32x4 x = rb[b & 1][gg][bj][i] + *(const f32x4*)(wl + (rl + 8 * i) * 36 + ch * 4);
;                         const size_t off = (size_t)(row0 + 8 * i) * 1024 + cbase + bj * HALF;
;                         u32x2 w; w.x = pkh(x[0], x[1]); w.y = pkh(x[2], x[3]); *(u32x2*)(X16 + off) = w;
;                         sq[i] += (x[0] * x[0] + x[1] * x[1]) + (x[2] * x[2] + x[3] * x[3]);
;                     }
;                     asm volatile("s_waitcnt lgkmcnt(0)" ::: "memory");
;                 }
; #pragma unroll
;                 for (int i = 0; i < 2; ++i) { float t = sq[i]; t += dpp_f(t, 0); t += dpp_f(t, 1); t += dpp_f(t, 2);
;                     if (ch == 0) ss[(size_t)(row0 + 8 * i) * 16 + u.pn * 4 + wc] = t; }
.LBB0_331:
	s_or_b64 exec, exec, s[30:31]
	v_add_u32_e32 v80, 0xa0, v142
	v_add_u32_e32 v72, 0xa8, v142
	v_ashrrev_i32_e32 v81, 31, v80
	v_ashrrev_i32_e32 v73, 31, v72
	v_lshlrev_b64 v[82:83], 11, v[80:81]
	v_lshlrev_b64 v[66:67], 11, v[72:73]
	v_lshl_add_u64 v[64:65], v[140:141], 0, v[82:83]
	v_lshl_add_u64 v[66:67], v[140:141], 0, v[66:67]
	global_load_dwordx2 v[90:91], v[64:65], off
	global_load_dwordx2 v[88:89], v[66:67], off
	global_load_dwordx2 v[84:85], v[66:67], off offset:256
	global_load_dwordx2 v[86:87], v[64:65], off offset:256
	v_add_u32_e32 v66, 0xb0, v142
	v_add_u32_e32 v64, 0xb8, v142
	v_ashrrev_i32_e32 v67, 31, v66
	v_ashrrev_i32_e32 v65, 31, v64
	v_lshlrev_b64 v[68:69], 11, v[66:67]
	v_lshlrev_b64 v[70:71], 11, v[64:65]
	v_lshl_add_u64 v[74:75], v[140:141], 0, v[68:69]
	v_lshl_add_u64 v[70:71], v[140:141], 0, v[70:71]
	global_load_dwordx2 v[78:79], v[74:75], off
	global_load_dwordx2 v[76:77], v[70:71], off
	s_nop 0
	global_load_dwordx2 v[70:71], v[70:71], off offset:256
	s_nop 0
	global_load_dwordx2 v[74:75], v[74:75], off offset:256
	v_mov_b32_e32 v193, v192
	v_pk_mul_f32 v[62:63], v[62:63], v[192:193]
	v_pk_mul_f32 v[60:61], v[60:61], v[132:133]
	v_pk_mul_f32 v[58:59], v[58:59], v[192:193]
	v_pk_mul_f32 v[56:57], v[56:57], v[132:133]
	ds_write_b128 v197, v[60:63]
	ds_write_b128 v197, v[56:59] offset:64
	ds_read_b128 v[56:59], v198
	s_waitcnt vmcnt(23)
	v_lshlrev_b32_e32 v92, 16, v122
	v_and_b32_e32 v93, 0xffff0000, v122
	v_lshlrev_b32_e32 v94, 16, v123
	v_and_b32_e32 v95, 0xffff0000, v123
	s_waitcnt lgkmcnt(0)
	v_pk_add_f32 v[94:95], v[58:59], v[94:95]
	v_pk_add_f32 v[92:93], v[56:57], v[92:93]
	v_lshl_add_u64 v[114:115], s[74:75], 0, v[114:115]
	v_cvt_pk_bf16_f32 v56, v92, v93
	v_cvt_pk_bf16_f32 v57, v94, v95
	ds_read_b128 v[58:61], v198 offset:1152
	s_waitcnt vmcnt(22)
	v_lshlrev_b32_e32 v122, 16, v120
	v_and_b32_e32 v123, 0xffff0000, v120
	v_lshlrev_b32_e32 v120, 16, v121
	v_and_b32_e32 v121, 0xffff0000, v121
	v_lshl_add_u64 v[114:115], v[114:115], 0, v[138:139]
	global_store_dwordx2 v[114:115], v[56:57], off
	s_waitcnt lgkmcnt(0)
	v_pk_add_f32 v[56:57], v[60:61], v[120:121]
	v_or_b32_e32 v60, 8, v112
	v_ashrrev_i32_e32 v61, 31, v60
	v_lshlrev_b64 v[60:61], 11, v[60:61]
	v_lshl_add_u64 v[60:61], s[74:75], 0, v[60:61]
	v_lshl_add_u64 v[60:61], v[60:61], 0, v[138:139]
	v_pk_add_f32 v[58:59], v[58:59], v[122:123]
	v_pk_mul_f32 v[54:55], v[54:55], v[192:193]
	v_cvt_pk_bf16_f32 v120, v58, v59
	v_cvt_pk_bf16_f32 v121, v56, v57
	global_store_dwordx2 v[60:61], v[120:121], off
	v_pk_mul_f32 v[52:53], v[52:53], v[132:133]
	v_pk_mul_f32 v[50:51], v[50:51], v[192:193]
	v_pk_mul_f32 v[48:49], v[48:49], v[132:133]
	s_waitcnt lgkmcnt(0)
	ds_write_b128 v197, v[52:55]
	ds_write_b128 v197, v[48:51] offset:64
	ds_read_b128 v[48:51], v198
	s_waitcnt vmcnt(22)
	v_lshlrev_b32_e32 v124, 16, v118
	v_and_b32_e32 v125, 0xffff0000, v118
	v_lshlrev_b32_e32 v118, 16, v119
	v_and_b32_e32 v119, 0xffff0000, v119
	v_mul_f32_e32 v93, v93, v93
	v_mul_f32_e32 v52, v95, v95
	v_fmac_f32_e32 v93, v92, v92
	v_fmac_f32_e32 v52, v94, v94
	s_waitcnt lgkmcnt(0)
	v_pk_add_f32 v[54:55], v[50:51], v[118:119]
	v_pk_add_f32 v[48:49], v[48:49], v[124:125]
	v_add_f32_e32 v92, v93, v52
	v_cvt_pk_bf16_f32 v50, v48, v49
	v_cvt_pk_bf16_f32 v51, v54, v55
	global_store_dwordx2 v[114:115], v[50:51], off offset:256
	ds_read_b128 v[50:53], v198 offset:1152
	v_mul_f32_e32 v49, v49, v49
	v_fmac_f32_e32 v49, v48, v48
	v_mul_f32_e32 v48, v55, v55
	v_fmac_f32_e32 v48, v54, v54
	v_lshlrev_b32_e32 v62, 16, v116
	v_and_b32_e32 v63, 0xffff0000, v116
	v_lshlrev_b32_e32 v116, 16, v117
	v_and_b32_e32 v117, 0xffff0000, v117
	v_add_f32_e32 v48, v49, v48
	v_add_f32_e32 v54, v92, v48
	s_waitcnt lgkmcnt(0)
	v_pk_add_f32 v[48:49], v[52:53], v[116:117]
	v_pk_add_f32 v[50:51], v[50:51], v[62:63]
	s_nop 0
	v_cvt_pk_bf16_f32 v52, v50, v51
	v_cvt_pk_bf16_f32 v53, v48, v49
	global_store_dwordx2 v[60:61], v[52:53], off offset:256
	s_waitcnt lgkmcnt(0)
	s_nop 0
	v_add_f32_dpp v52, v54, v54 quad_perm:[1,0,3,2] row_mask:0xf bank_mask:0xf bound_ctrl:1
	s_nop 1
	v_add_f32_dpp v52, v52, v52 quad_perm:[2,3,0,1] row_mask:0xf bank_mask:0xf bound_ctrl:1
	s_nop 1
	v_mov_b32_dpp v53, v52 row_shl:4 row_mask:0xf bank_mask:0xf bound_ctrl:1
	s_and_saveexec_b64 s[30:31], s[38:39]
	s_cbranch_execz .LBB0_333
	v_add_f32_e32 v54, v52, v53
	v_lshlrev_b64 v[52:53], 6, v[112:113]
	v_lshl_add_u64 v[52:53], s[28:29], 0, v[52:53]
	global_store_dword v[52:53], v54, off

; __device__ __forceinline__ unsigned pkh(float lo, float hi) { if (!RES_FP16) return cvt_pk_bf16(lo, hi); f16x2 v = {(_Float16)lo, (_Float16)hi}; return __builtin_bit_cast(unsigned, v); }
;     __device__ __forceinline__ void operator()(const f32x4 (&acc)[2][2][4][2], const Unit& u, int wr, int wc, int fr, int fq) const {
;     ...
;             for (int gg = 0; gg < 2; ++gg) {
;                 const int g = 2 * b + gg, ai = g >> 2, m = g & 3;
;                 const int row0 = u.pm * BM + ai * HALF + wr * 64 + m * 16 + rl;
;                 float sq[2] = {0.f, 0.f};
; #pragma unroll
;                 for (int bj = 0; bj < 2; ++bj) {
;                     *(f32x4*)(wl + fr * 36 + fq * 4) = acc[ai][bj][m][0] * alpha; *(f32x4*)(wl + fr * 36 + 16 + fq * 4) = acc[ai][bj][m][1] * alpha;
;                     asm volatile("s_waitcnt lgkmcnt(0)" ::: "memory");
; #pragma unroll
;                     for (int i = 0; i < 2; ++i) {
;                         const f32x4 x = rb[b & 1][gg][bj][i] + *(const f32x4*)(wl + (rl + 8 * i) * 36 + ch * 4);
;                         const size_t off = (size_t)(row0 + 8 * i) * 1024 + cbase + bj * HALF;
;                         u32x2 w; w.x = pkh(x[0], x[1]); w.y = pkh(x[2], x[3]); *(u32x2*)(X16 + off) = w;
;                         sq[i] += (x[0] * x[0] + x[1] * x[1]) + (x[2] * x[2] + x[3] * x[3]);
;                     }
;                     asm volatile("s_waitcnt lgkmcnt(0)" ::: "memory");
;                 }
; #pragma unroll
;                 for (int i = 0; i < 2; ++i) { float t = sq[i]; t += dpp_f(t, 0); t += dpp_f(t, 1); t += dpp_f(t, 2);
;                     if (ch == 0) ss[(size_t)(row0 + 8 * i) * 16 + u.pn * 4 + wc] = t; }
.LBB0_335:
	s_or_b64 exec, exec, s[30:31]
	v_mov_b32_e32 v193, v192
	v_pk_mul_f32 v[46:47], v[46:47], v[192:193]
	v_pk_mul_f32 v[44:45], v[44:45], v[132:133]
	v_pk_mul_f32 v[42:43], v[42:43], v[192:193]
	v_pk_mul_f32 v[40:41], v[40:41], v[132:133]
	ds_write_b128 v197, v[44:47]
	ds_write_b128 v197, v[40:43] offset:64
	ds_read_b128 v[40:43], v198
	s_waitcnt vmcnt(23)
	v_lshlrev_b32_e32 v48, 16, v110
	v_and_b32_e32 v49, 0xffff0000, v110
	v_lshlrev_b32_e32 v50, 16, v111
	v_and_b32_e32 v51, 0xffff0000, v111
	s_waitcnt lgkmcnt(0)
	v_pk_add_f32 v[50:51], v[42:43], v[50:51]
	v_pk_add_f32 v[48:49], v[40:41], v[48:49]
	v_lshl_add_u64 v[62:63], s[74:75], 0, v[100:101]
	v_cvt_pk_bf16_f32 v40, v48, v49
	v_cvt_pk_bf16_f32 v41, v50, v51
	ds_read_b128 v[42:45], v198 offset:1152
	s_waitcnt vmcnt(22)
	v_lshlrev_b32_e32 v54, 16, v109
	v_and_b32_e32 v55, 0xffff0000, v109
	v_lshl_add_u64 v[62:63], v[62:63], 0, v[138:139]
	global_store_dwordx2 v[62:63], v[40:41], off
	s_waitcnt lgkmcnt(0)
	v_pk_add_f32 v[40:41], v[44:45], v[54:55]
	v_or_b32_e32 v44, 8, v98
	v_ashrrev_i32_e32 v45, 31, v44
	v_lshlrev_b64 v[44:45], 11, v[44:45]
	v_lshl_add_u64 v[44:45], s[74:75], 0, v[44:45]
	v_lshlrev_b32_e32 v52, 16, v108
	v_and_b32_e32 v53, 0xffff0000, v108
	v_lshl_add_u64 v[44:45], v[44:45], 0, v[138:139]
	v_pk_add_f32 v[42:43], v[42:43], v[52:53]
	v_pk_mul_f32 v[38:39], v[38:39], v[192:193]
	v_cvt_pk_bf16_f32 v52, v42, v43
	v_cvt_pk_bf16_f32 v53, v40, v41
	global_store_dwordx2 v[44:45], v[52:53], off
	v_pk_mul_f32 v[36:37], v[36:37], v[132:133]
	v_pk_mul_f32 v[34:35], v[34:35], v[192:193]
	v_pk_mul_f32 v[32:33], v[32:33], v[132:133]
	s_waitcnt lgkmcnt(0)
	ds_write_b128 v197, v[36:39]
	ds_write_b128 v197, v[32:35] offset:64
	ds_read_b128 v[32:35], v198
	s_waitcnt vmcnt(22)
	v_lshlrev_b32_e32 v56, 16, v106
	v_and_b32_e32 v57, 0xffff0000, v106
	v_lshlrev_b32_e32 v58, 16, v107
	v_and_b32_e32 v59, 0xffff0000, v107
	v_mul_f32_e32 v49, v49, v49
	v_mul_f32_e32 v36, v51, v51
	v_fmac_f32_e32 v49, v48, v48
	v_fmac_f32_e32 v36, v50, v50
	s_waitcnt lgkmcnt(0)
	v_pk_add_f32 v[38:39], v[34:35], v[58:59]
	v_pk_add_f32 v[32:33], v[32:33], v[56:57]
	v_add_f32_e32 v48, v49, v36
	v_cvt_pk_bf16_f32 v34, v32, v33
	v_cvt_pk_bf16_f32 v35, v38, v39
	global_store_dwordx2 v[62:63], v[34:35], off offset:256
	ds_read_b128 v[34:37], v198 offset:1152
	v_mul_f32_e32 v33, v33, v33
	v_fmac_f32_e32 v33, v32, v32
	v_mul_f32_e32 v32, v39, v39
	v_fmac_f32_e32 v32, v38, v38
	v_lshlrev_b32_e32 v46, 16, v102
	v_and_b32_e32 v47, 0xffff0000, v102
	v_lshlrev_b32_e32 v60, 16, v103
	v_and_b32_e32 v61, 0xffff0000, v103
	v_add_f32_e32 v32, v33, v32
	v_add_f32_e32 v38, v48, v32
	s_waitcnt lgkmcnt(0)
	v_pk_add_f32 v[32:33], v[36:37], v[60:61]
	v_pk_add_f32 v[34:35], v[34:35], v[46:47]
	s_nop 0
	v_cvt_pk_bf16_f32 v36, v34, v35
	v_cvt_pk_bf16_f32 v37, v32, v33
	global_store_dwordx2 v[44:45], v[36:37], off offset:256
	s_waitcnt lgkmcnt(0)
	s_nop 0
	v_add_f32_dpp v36, v38, v38 quad_perm:[1,0,3,2] row_mask:0xf bank_mask:0xf bound_ctrl:1
	s_nop 1
	v_add_f32_dpp v36, v36, v36 quad_perm:[2,3,0,1] row_mask:0xf bank_mask:0xf bound_ctrl:1
	s_nop 1
	v_mov_b32_dpp v37, v36 row_shl:4 row_mask:0xf bank_mask:0xf bound_ctrl:1
	s_and_saveexec_b64 s[30:31], s[38:39]
	s_cbranch_execz .LBB0_337
	v_add_f32_e32 v38, v36, v37
	v_lshlrev_b64 v[36:37], 6, v[98:99]
	v_lshl_add_u64 v[36:37], s[28:29], 0, v[36:37]
	global_store_dword v[36:37], v38, off

; __device__ __forceinline__ unsigned pkh(float lo, float hi) { if (!RES_FP16) return cvt_pk_bf16(lo, hi); f16x2 v = {(_Float16)lo, (_Float16)hi}; return __builtin_bit_cast(unsigned, v); }
;     __device__ __forceinline__ void operator()(const f32x4 (&acc)[2][2][4][2], const Unit& u, int wr, int wc, int fr, int fq) const {
;     ...
;             for (int gg = 0; gg < 2; ++gg) {
;                 const int g = 2 * b + gg, ai = g >> 2, m = g & 3;
;                 const int row0 = u.pm * BM + ai * HALF + wr * 64 + m * 16 + rl;
;                 float sq[2] = {0.f, 0.f};
; #pragma unroll
;                 for (int bj = 0; bj < 2; ++bj) {
;                     *(f32x4*)(wl + fr * 36 + fq * 4) = acc[ai][bj][m][0] * alpha; *(f32x4*)(wl + fr * 36 + 16 + fq * 4) = acc[ai][bj][m][1] * alpha;
;                     asm volatile("s_waitcnt lgkmcnt(0)" ::: "memory");
; #pragma unroll
;                     for (int i = 0; i < 2; ++i) {
;                         const f32x4 x = rb[b & 1][gg][bj][i] + *(const f32x4*)(wl + (rl + 8 * i) * 36 + ch * 4);
;                         const size_t off = (size_t)(row0 + 8 * i) * 1024 + cbase + bj * HALF;
;                         u32x2 w; w.x = pkh(x[0], x[1]); w.y = pkh(x[2], x[3]); *(u32x2*)(X16 + off) = w;
;                         sq[i] += (x[0] * x[0] + x[1] * x[1]) + (x[2] * x[2] + x[3] * x[3]);
;                     }
;                     asm volatile("s_waitcnt lgkmcnt(0)" ::: "memory");
;                 }
; #pragma unroll
;                 for (int i = 0; i < 2; ++i) { float t = sq[i]; t += dpp_f(t, 0); t += dpp_f(t, 1); t += dpp_f(t, 2);
;                     if (ch == 0) ss[(size_t)(row0 + 8 * i) * 16 + u.pn * 4 + wc] = t; }
.LBB0_339:
	s_or_b64 exec, exec, s[30:31]
	v_mov_b32_e32 v193, v192
	v_pk_mul_f32 v[30:31], v[30:31], v[192:193]
	v_pk_mul_f32 v[28:29], v[28:29], v[132:133]
	v_pk_mul_f32 v[26:27], v[26:27], v[192:193]
	v_pk_mul_f32 v[24:25], v[24:25], v[132:133]
	ds_write_b128 v197, v[28:31]
	ds_write_b128 v197, v[24:27] offset:64
	ds_read_b128 v[24:27], v198
	s_waitcnt vmcnt(15)
	v_lshlrev_b32_e32 v32, 16, v90
	v_and_b32_e32 v33, 0xffff0000, v90
	v_lshlrev_b32_e32 v34, 16, v91
	v_and_b32_e32 v35, 0xffff0000, v91
	s_waitcnt lgkmcnt(0)
	v_pk_add_f32 v[34:35], v[26:27], v[34:35]
	v_pk_add_f32 v[32:33], v[24:25], v[32:33]
	v_lshl_add_u64 v[46:47], s[74:75], 0, v[82:83]
	v_cvt_pk_bf16_f32 v24, v32, v33
	v_cvt_pk_bf16_f32 v25, v34, v35
	ds_read_b128 v[26:29], v198 offset:1152
	s_waitcnt vmcnt(14)
	v_lshlrev_b32_e32 v38, 16, v89
	v_and_b32_e32 v39, 0xffff0000, v89
	v_lshl_add_u64 v[46:47], v[46:47], 0, v[138:139]
	global_store_dwordx2 v[46:47], v[24:25], off
	s_waitcnt lgkmcnt(0)
	v_pk_add_f32 v[24:25], v[28:29], v[38:39]
	v_or_b32_e32 v28, 8, v80
	v_ashrrev_i32_e32 v29, 31, v28
	v_lshlrev_b64 v[28:29], 11, v[28:29]
	v_lshl_add_u64 v[28:29], s[74:75], 0, v[28:29]
	v_lshlrev_b32_e32 v36, 16, v88
	v_and_b32_e32 v37, 0xffff0000, v88
	v_lshl_add_u64 v[28:29], v[28:29], 0, v[138:139]
	v_pk_add_f32 v[26:27], v[26:27], v[36:37]
	v_pk_mul_f32 v[22:23], v[22:23], v[192:193]
	v_cvt_pk_bf16_f32 v36, v26, v27
	v_cvt_pk_bf16_f32 v37, v24, v25
	global_store_dwordx2 v[28:29], v[36:37], off
	v_pk_mul_f32 v[20:21], v[20:21], v[132:133]
	v_pk_mul_f32 v[18:19], v[18:19], v[192:193]
	v_pk_mul_f32 v[16:17], v[16:17], v[132:133]
	s_waitcnt lgkmcnt(0)
	ds_write_b128 v197, v[20:23]
	ds_write_b128 v197, v[16:19] offset:64
	ds_read_b128 v[16:19], v198
	s_waitcnt vmcnt(14)
	v_lshlrev_b32_e32 v40, 16, v86
	v_and_b32_e32 v41, 0xffff0000, v86
	v_lshlrev_b32_e32 v42, 16, v87
	v_and_b32_e32 v43, 0xffff0000, v87
	v_mul_f32_e32 v33, v33, v33
	v_mul_f32_e32 v20, v35, v35
	v_fmac_f32_e32 v33, v32, v32
	v_fmac_f32_e32 v20, v34, v34
	s_waitcnt lgkmcnt(0)
	v_pk_add_f32 v[22:23], v[18:19], v[42:43]
	v_pk_add_f32 v[16:17], v[16:17], v[40:41]
	v_add_f32_e32 v32, v33, v20
	v_cvt_pk_bf16_f32 v18, v16, v17
	v_cvt_pk_bf16_f32 v19, v22, v23
	global_store_dwordx2 v[46:47], v[18:19], off offset:256
	ds_read_b128 v[18:21], v198 offset:1152
	v_mul_f32_e32 v17, v17, v17
	v_fmac_f32_e32 v17, v16, v16
	v_mul_f32_e32 v16, v23, v23
	v_fmac_f32_e32 v16, v22, v22
	v_lshlrev_b32_e32 v30, 16, v84
	v_and_b32_e32 v31, 0xffff0000, v84
	v_lshlrev_b32_e32 v44, 16, v85
	v_and_b32_e32 v45, 0xffff0000, v85
	v_add_f32_e32 v16, v17, v16
	v_add_f32_e32 v22, v32, v16
	s_waitcnt lgkmcnt(0)
	v_pk_add_f32 v[16:17], v[20:21], v[44:45]
	v_pk_add_f32 v[18:19], v[18:19], v[30:31]
	s_nop 0
	v_cvt_pk_bf16_f32 v20, v18, v19
	v_cvt_pk_bf16_f32 v21, v16, v17
	global_store_dwordx2 v[28:29], v[20:21], off offset:256
	s_waitcnt lgkmcnt(0)
	s_nop 0
	v_add_f32_dpp v20, v22, v22 quad_perm:[1,0,3,2] row_mask:0xf bank_mask:0xf bound_ctrl:1
	s_nop 1
	v_add_f32_dpp v20, v20, v20 quad_perm:[2,3,0,1] row_mask:0xf bank_mask:0xf bound_ctrl:1
	s_nop 1
	v_mov_b32_dpp v21, v20 row_shl:4 row_mask:0xf bank_mask:0xf bound_ctrl:1
	s_and_saveexec_b64 s[30:31], s[38:39]
	s_cbranch_execz .LBB0_341
	v_add_f32_e32 v22, v20, v21
	v_lshlrev_b64 v[20:21], 6, v[80:81]
	v_lshl_add_u64 v[20:21], s[28:29], 0, v[20:21]
	global_store_dword v[20:21], v22, off

; __device__ __forceinline__ unsigned pkh(float lo, float hi) { if (!RES_FP16) return cvt_pk_bf16(lo, hi); f16x2 v = {(_Float16)lo, (_Float16)hi}; return __builtin_bit_cast(unsigned, v); }
;     __device__ __forceinline__ void operator()(const f32x4 (&acc)[2][2][4][2], const Unit& u, int wr, int wc, int fr, int fq) const {
;     ...
;             for (int gg = 0; gg < 2; ++gg) {
;                 const int g = 2 * b + gg, ai = g >> 2, m = g & 3;
;                 const int row0 = u.pm * BM + ai * HALF + wr * 64 + m * 16 + rl;
;                 float sq[2] = {0.f, 0.f};
; #pragma unroll
;                 for (int bj = 0; bj < 2; ++bj) {
;                     *(f32x4*)(wl + fr * 36 + fq * 4) = acc[ai][bj][m][0] * alpha; *(f32x4*)(wl + fr * 36 + 16 + fq * 4) = acc[ai][bj][m][1] * alpha;
;                     asm volatile("s_waitcnt lgkmcnt(0)" ::: "memory");
; #pragma unroll
;                     for (int i = 0; i < 2; ++i) {
;                         const f32x4 x = rb[b & 1][gg][bj][i] + *(const f32x4*)(wl + (rl + 8 * i) * 36 + ch * 4);
;                         const size_t off = (size_t)(row0 + 8 * i) * 1024 + cbase + bj * HALF;
;                         u32x2 w; w.x = pkh(x[0], x[1]); w.y = pkh(x[2], x[3]); *(u32x2*)(X16 + off) = w;
;                         sq[i] += (x[0] * x[0] + x[1] * x[1]) + (x[2] * x[2] + x[3] * x[3]);
;                     }
;                     asm volatile("s_waitcnt lgkmcnt(0)" ::: "memory");
;                 }
; #pragma unroll
;                 for (int i = 0; i < 2; ++i) { float t = sq[i]; t += dpp_f(t, 0); t += dpp_f(t, 1); t += dpp_f(t, 2);
;                     if (ch == 0) ss[(size_t)(row0 + 8 * i) * 16 + u.pn * 4 + wc] = t; }
.LBB0_343:
	s_or_b64 exec, exec, s[30:31]
	v_mov_b32_e32 v193, v192
	v_pk_mul_f32 v[14:15], v[14:15], v[192:193]
	v_pk_mul_f32 v[12:13], v[12:13], v[132:133]
	v_pk_mul_f32 v[10:11], v[10:11], v[192:193]
	v_pk_mul_f32 v[8:9], v[8:9], v[132:133]
	ds_write_b128 v197, v[12:15]
	ds_write_b128 v197, v[8:11] offset:64
	ds_read_b128 v[8:11], v198
	s_waitcnt vmcnt(15)
	v_lshlrev_b32_e32 v16, 16, v78
	v_and_b32_e32 v17, 0xffff0000, v78
	v_lshlrev_b32_e32 v18, 16, v79
	v_and_b32_e32 v19, 0xffff0000, v79
	s_waitcnt lgkmcnt(0)
	v_pk_add_f32 v[18:19], v[10:11], v[18:19]
	v_pk_add_f32 v[16:17], v[8:9], v[16:17]
	v_lshl_add_u64 v[30:31], s[74:75], 0, v[68:69]
	v_cvt_pk_bf16_f32 v8, v16, v17
	v_cvt_pk_bf16_f32 v9, v18, v19
	ds_read_b128 v[10:13], v198 offset:1152
	s_waitcnt vmcnt(14)
	v_lshlrev_b32_e32 v22, 16, v77
	v_and_b32_e32 v23, 0xffff0000, v77
	v_lshl_add_u64 v[30:31], v[30:31], 0, v[138:139]
	global_store_dwordx2 v[30:31], v[8:9], off
	s_waitcnt lgkmcnt(0)
	v_pk_add_f32 v[8:9], v[12:13], v[22:23]
	v_or_b32_e32 v12, 8, v66
	v_ashrrev_i32_e32 v13, 31, v12
	v_lshlrev_b64 v[12:13], 11, v[12:13]
	v_lshl_add_u64 v[12:13], s[74:75], 0, v[12:13]
	v_lshlrev_b32_e32 v20, 16, v76
	v_and_b32_e32 v21, 0xffff0000, v76
	v_lshl_add_u64 v[12:13], v[12:13], 0, v[138:139]
	v_pk_add_f32 v[10:11], v[10:11], v[20:21]
	v_pk_mul_f32 v[6:7], v[6:7], v[192:193]
	v_cvt_pk_bf16_f32 v20, v10, v11
	v_cvt_pk_bf16_f32 v21, v8, v9
	global_store_dwordx2 v[12:13], v[20:21], off
	v_pk_mul_f32 v[4:5], v[4:5], v[132:133]
	v_pk_mul_f32 v[2:3], v[2:3], v[192:193]
	v_pk_mul_f32 v[0:1], v[0:1], v[132:133]
	s_waitcnt lgkmcnt(0)
	ds_write_b128 v197, v[4:7]
	ds_write_b128 v197, v[0:3] offset:64
	ds_read_b128 v[0:3], v198
	s_waitcnt vmcnt(14)
	v_lshlrev_b32_e32 v24, 16, v74
	v_and_b32_e32 v25, 0xffff0000, v74
	v_lshlrev_b32_e32 v26, 16, v75
	v_and_b32_e32 v27, 0xffff0000, v75
	v_mul_f32_e32 v17, v17, v17
	v_mul_f32_e32 v4, v19, v19
	v_fmac_f32_e32 v17, v16, v16
	v_fmac_f32_e32 v4, v18, v18
	s_waitcnt lgkmcnt(0)
	v_pk_add_f32 v[6:7], v[2:3], v[26:27]
	v_pk_add_f32 v[0:1], v[0:1], v[24:25]
	v_add_f32_e32 v16, v17, v4
	v_cvt_pk_bf16_f32 v2, v0, v1
	v_cvt_pk_bf16_f32 v3, v6, v7
	global_store_dwordx2 v[30:31], v[2:3], off offset:256
	ds_read_b128 v[2:5], v198 offset:1152
	v_mul_f32_e32 v1, v1, v1
	v_fmac_f32_e32 v1, v0, v0
	v_mul_f32_e32 v0, v7, v7
	v_fmac_f32_e32 v0, v6, v6
	v_lshlrev_b32_e32 v14, 16, v70
	v_and_b32_e32 v15, 0xffff0000, v70
	v_lshlrev_b32_e32 v28, 16, v71
	v_and_b32_e32 v29, 0xffff0000, v71
	v_add_f32_e32 v0, v1, v0
	v_add_f32_e32 v6, v16, v0
	s_waitcnt lgkmcnt(0)
	v_pk_add_f32 v[0:1], v[4:5], v[28:29]
	v_pk_add_f32 v[2:3], v[2:3], v[14:15]
	s_nop 0
	v_cvt_pk_bf16_f32 v4, v2, v3
	v_cvt_pk_bf16_f32 v5, v0, v1
	global_store_dwordx2 v[12:13], v[4:5], off offset:256
	s_waitcnt lgkmcnt(0)
	s_nop 0
	v_add_f32_dpp v4, v6, v6 quad_perm:[1,0,3,2] row_mask:0xf bank_mask:0xf bound_ctrl:1
	s_nop 1
	v_add_f32_dpp v4, v4, v4 quad_perm:[2,3,0,1] row_mask:0xf bank_mask:0xf bound_ctrl:1
	s_nop 1
	v_mov_b32_dpp v5, v4 row_shl:4 row_mask:0xf bank_mask:0xf bound_ctrl:1
	s_and_saveexec_b64 s[30:31], s[38:39]
	s_cbranch_execz .LBB0_345
	v_add_f32_e32 v6, v4, v5
	v_lshlrev_b64 v[4:5], 6, v[66:67]
	v_lshl_add_u64 v[4:5], s[28:29], 0, v[4:5]
	global_store_dword v[4:5], v6, off

; __device__ __forceinline__ unsigned pkh(float lo, float hi) { if (!RES_FP16) return cvt_pk_bf16(lo, hi); f16x2 v = {(_Float16)lo, (_Float16)hi}; return __builtin_bit_cast(unsigned, v); }
;     __device__ __forceinline__ void operator()(const f32x4 (&acc)[2][2][4][2], const Unit& u, int wr, int wc, int fr, int fq) const {
;         float* wl = wlds + (wr * 4 + wc) * 576;
;         const int lane = fq * 16 + fr, rl = lane >> 3, ch = lane & 7;
;         f32x4 rb[2][2][2][2];
;         const size_t cbase = (size_t)u.pn * BM + wc * 32 + ch * 4;
;     ...
;         RES_LOAD(0, 0);
; #pragma unroll
;         for (int b = 0; b < 4; ++b) {
;             if (b + 1 < 4) RES_LOAD((b + 1) & 1, b + 1);
; #pragma unroll
;             for (int gg = 0; gg < 2; ++gg) {
;                 const int g = 2 * b + gg, ai = g >> 2, m = g & 3;
;                 const int row0 = u.pm * BM + ai * HALF + wr * 64 + m * 16 + rl;
;                 float sq[2] = {0.f, 0.f};
; #pragma unroll
;                 for (int bj = 0; bj < 2; ++bj) {
;                     *(f32x4*)(wl + fr * 36 + fq * 4) = acc[ai][bj][m][0] * alpha; *(f32x4*)(wl + fr * 36 + 16 + fq * 4) = acc[ai][bj][m][1] * alpha;
;                     asm volatile("s_waitcnt lgkmcnt(0)" ::: "memory");
; #pragma unroll
;                     for (int i = 0; i < 2; ++i) {
;                         const f32x4 x = rb[b & 1][gg][bj][i] + *(const f32x4*)(wl + (rl + 8 * i) * 36 + ch * 4);
;                         const size_t off = (size_t)(row0 + 8 * i) * 1024 + cbase + bj * HALF;
;                         u32x2 w; w.x = pkh(x[0], x[1]); w.y = pkh(x[2], x[3]); *(u32x2*)(X16 + off) = w;
;                         sq[i] += (x[0] * x[0] + x[1] * x[1]) + (x[2] * x[2] + x[3] * x[3]);
;                     }
;                     asm volatile("s_waitcnt lgkmcnt(0)" ::: "memory");
;                 }
; #pragma unroll
;                 for (int i = 0; i < 2; ++i) { float t = sq[i]; t += dpp_f(t, 0); t += dpp_f(t, 1); t += dpp_f(t, 2);
;                     if (ch == 0) ss[(size_t)(row0 + 8 * i) * 16 + u.pn * 4 + wc] = t; }
.LBB0_372:
	s_ashr_i32 s29, s28, 31
	s_lshl_b64 s[30:31], s[28:29], 8
	v_lshl_add_u32 v204, s84, 8, v211
	v_readlane_b32 s52, v252, 6
	v_mov_b32_e32 v227, s31
	v_or_b32_e32 v226, s30, v196
	v_readlane_b32 s53, v252, 7
	v_ashrrev_i32_e32 v205, 31, v204
	v_lshlrev_b64 v[128:129], 12, v[204:205]
	v_lshl_add_u64 v[206:207], v[226:227], 2, s[52:53]
	v_lshl_add_u64 v[128:129], v[206:207], 0, v[128:129]
	global_load_dwordx4 v[188:191], v[128:129], off
	v_or_b32_e32 v224, 8, v204
	v_ashrrev_i32_e32 v225, 31, v224
	v_lshlrev_b64 v[130:131], 12, v[224:225]
	v_lshl_add_u64 v[130:131], v[206:207], 0, v[130:131]
	global_load_dwordx4 v[184:187], v[130:131], off
	global_load_dwordx4 v[180:183], v[128:129], off offset:512
	global_load_dwordx4 v[176:179], v[130:131], off offset:512
	v_or_b32_e32 v222, 16, v204
	v_or_b32_e32 v220, 24, v204
	v_ashrrev_i32_e32 v223, 31, v222
	v_ashrrev_i32_e32 v221, 31, v220
	v_lshlrev_b64 v[128:129], 12, v[222:223]
	v_lshlrev_b64 v[130:131], 12, v[220:221]
	v_or_b32_e32 v218, 32, v204
	v_or_b32_e32 v216, 40, v204
	v_lshl_add_u64 v[128:129], v[206:207], 0, v[128:129]
	v_lshl_add_u64 v[130:131], v[206:207], 0, v[130:131]
	v_ashrrev_i32_e32 v219, 31, v218
	v_ashrrev_i32_e32 v217, 31, v216
	global_load_dwordx4 v[172:175], v[128:129], off
	global_load_dwordx4 v[168:171], v[130:131], off
	global_load_dwordx4 v[164:167], v[128:129], off offset:512
	global_load_dwordx4 v[160:163], v[130:131], off offset:512
	v_lshlrev_b64 v[128:129], 12, v[218:219]
	v_lshlrev_b64 v[130:131], 12, v[216:217]
	v_or_b32_e32 v214, 48, v204
	v_or_b32_e32 v212, 56, v204
	v_lshl_add_u64 v[128:129], v[206:207], 0, v[128:129]
	v_lshl_add_u64 v[130:131], v[206:207], 0, v[130:131]
	v_ashrrev_i32_e32 v215, 31, v214
	v_ashrrev_i32_e32 v213, 31, v212
	global_load_dwordx4 v[156:159], v[128:129], off
	global_load_dwordx4 v[152:155], v[130:131], off
	global_load_dwordx4 v[148:151], v[128:129], off offset:512
	global_load_dwordx4 v[136:139], v[130:131], off offset:512
	v_lshlrev_b64 v[128:129], 12, v[214:215]
	v_lshlrev_b64 v[134:135], 12, v[212:213]
	v_lshl_add_u64 v[132:133], v[206:207], 0, v[128:129]
	v_lshl_add_u64 v[134:135], v[206:207], 0, v[134:135]
	global_load_dwordx4 v[128:131], v[132:133], off
	global_load_dwordx4 v[144:147], v[134:135], off
	global_load_dwordx4 v[140:143], v[132:133], off offset:512
	s_nop 0
	global_load_dwordx4 v[132:135], v[134:135], off offset:512
	v_mov_b32_e32 v193, v192
	v_pk_mul_f32 v[126:127], v[126:127], v[192:193]
	v_pk_mul_f32 v[124:125], v[124:125], v[198:199]
	v_pk_mul_f32 v[122:123], v[122:123], v[192:193]
	v_pk_mul_f32 v[120:121], v[120:121], v[198:199]
	ds_write_b128 v228, v[124:127]
	ds_write_b128 v228, v[120:123] offset:64
	ds_read_b128 v[120:123], v229
	v_lshlrev_b64 v[126:127], 11, v[204:205]
	v_lshl_add_u64 v[126:127], s[74:75], 0, v[126:127]
	v_pk_mul_f32 v[118:119], v[118:119], v[192:193]
	v_pk_mul_f32 v[116:117], v[116:117], v[198:199]
	v_pk_mul_f32 v[114:115], v[114:115], v[192:193]
	v_pk_mul_f32 v[112:113], v[112:113], v[198:199]
	s_lshl_b32 s28, s28, 2
	s_ashr_i32 s29, s28, 31
	s_lshl_b64 s[28:29], s[28:29], 2
	s_add_u32 s28, s95, s28
	s_addc_u32 s29, s68, s29
	v_readlane_b32 s54, v252, 8
	v_readlane_b32 s55, v252, 9
	v_readlane_b32 s56, v252, 10
	v_readlane_b32 s57, v252, 11
	v_readlane_b32 s58, v252, 12
	v_readlane_b32 s59, v252, 13
	v_readlane_b32 s60, v252, 14
	v_readlane_b32 s61, v252, 15
	v_readlane_b32 s62, v252, 16
	v_readlane_b32 s63, v252, 17
	v_readlane_b32 s64, v252, 18
	v_readlane_b32 s65, v252, 19
	v_readlane_b32 s66, v252, 20
	v_readlane_b32 s67, v252, 21
	s_waitcnt vmcnt(0) lgkmcnt(0)
	v_pk_add_f32 v[120:121], v[188:189], v[120:121]
	v_pk_add_f32 v[122:123], v[190:191], v[122:123]
	v_cvt_pk_bf16_f32 v124, v120, v121
	v_lshlrev_b64 v[188:189], 1, v[226:227]
	v_mul_f32_e32 v121, v121, v121
	v_cvt_pk_bf16_f32 v125, v122, v123
	v_lshl_add_u64 v[126:127], v[126:127], 0, v[188:189]
	v_fmac_f32_e32 v121, v120, v120
	v_mul_f32_e32 v120, v123, v123
	global_store_dwordx2 v[126:127], v[124:125], off
	v_fmac_f32_e32 v120, v122, v122
	ds_read_b128 v[122:125], v229 offset:1152
	v_add_f32_e32 v190, v121, v120
	s_waitcnt lgkmcnt(0)
	v_pk_add_f32 v[120:121], v[186:187], v[124:125]
	v_lshlrev_b64 v[124:125], 11, v[224:225]
	v_lshl_add_u64 v[124:125], s[74:75], 0, v[124:125]
	v_lshl_add_u64 v[124:125], v[124:125], 0, v[188:189]
	v_pk_add_f32 v[122:123], v[184:185], v[122:123]
	s_nop 0
	v_cvt_pk_bf16_f32 v184, v122, v123
	v_cvt_pk_bf16_f32 v185, v120, v121
	global_store_dwordx2 v[124:125], v[184:185], off
	s_waitcnt lgkmcnt(0)
	ds_write_b128 v228, v[116:119]
	ds_write_b128 v228, v[112:115] offset:64
	ds_read_b128 v[112:115], v229
	s_waitcnt lgkmcnt(0)
	v_pk_add_f32 v[112:113], v[180:181], v[112:113]
	v_pk_add_f32 v[114:115], v[182:183], v[114:115]
	v_cvt_pk_bf16_f32 v116, v112, v113
	v_mul_f32_e32 v113, v113, v113
	v_cvt_pk_bf16_f32 v117, v114, v115
	v_fmac_f32_e32 v113, v112, v112
	v_mul_f32_e32 v112, v115, v115
	global_store_dwordx2 v[126:127], v[116:117], off offset:256
	v_fmac_f32_e32 v112, v114, v114
	ds_read_b128 v[114:117], v229 offset:1152
	v_add_f32_e32 v112, v113, v112
	v_add_f32_e32 v118, v190, v112
	s_waitcnt lgkmcnt(0)
	v_pk_add_f32 v[112:113], v[178:179], v[116:117]
	v_pk_add_f32 v[114:115], v[176:177], v[114:115]
	s_nop 0
	v_cvt_pk_bf16_f32 v116, v114, v115
	v_cvt_pk_bf16_f32 v117, v112, v113
	global_store_dwordx2 v[124:125], v[116:117], off offset:256
	s_waitcnt lgkmcnt(0)
	s_nop 0
	v_add_f32_dpp v116, v118, v118 quad_perm:[1,0,3,2] row_mask:0xf bank_mask:0xf bound_ctrl:1
	s_nop 1
	v_add_f32_dpp v116, v116, v116 quad_perm:[2,3,0,1] row_mask:0xf bank_mask:0xf bound_ctrl:1
	s_nop 1
	v_mov_b32_dpp v117, v116 row_shl:4 row_mask:0xf bank_mask:0xf bound_ctrl:1
	s_and_saveexec_b64 s[30:31], s[38:39]
	s_cbranch_execz .LBB0_374
	v_add_f32_e32 v118, v116, v117
	v_lshlrev_b64 v[116:117], 6, v[204:205]
	v_lshl_add_u64 v[116:117], s[28:29], 0, v[116:117]
	global_store_dword v[116:117], v118, off

; __device__ __forceinline__ unsigned pkh(float lo, float hi) { if (!RES_FP16) return cvt_pk_bf16(lo, hi); f16x2 v = {(_Float16)lo, (_Float16)hi}; return __builtin_bit_cast(unsigned, v); }
;     __device__ __forceinline__ void operator()(const f32x4 (&acc)[2][2][4][2], const Unit& u, int wr, int wc, int fr, int fq) const {
;     ...
;             for (int gg = 0; gg < 2; ++gg) {
;                 const int g = 2 * b + gg, ai = g >> 2, m = g & 3;
;                 const int row0 = u.pm * BM + ai * HALF + wr * 64 + m * 16 + rl;
;                 float sq[2] = {0.f, 0.f};
; #pragma unroll
;                 for (int bj = 0; bj < 2; ++bj) {
;                     *(f32x4*)(wl + fr * 36 + fq * 4) = acc[ai][bj][m][0] * alpha; *(f32x4*)(wl + fr * 36 + 16 + fq * 4) = acc[ai][bj][m][1] * alpha;
;                     asm volatile("s_waitcnt lgkmcnt(0)" ::: "memory");
; #pragma unroll
;                     for (int i = 0; i < 2; ++i) {
;                         const f32x4 x = rb[b & 1][gg][bj][i] + *(const f32x4*)(wl + (rl + 8 * i) * 36 + ch * 4);
;                         const size_t off = (size_t)(row0 + 8 * i) * 1024 + cbase + bj * HALF;
;                         u32x2 w; w.x = pkh(x[0], x[1]); w.y = pkh(x[2], x[3]); *(u32x2*)(X16 + off) = w;
;                         sq[i] += (x[0] * x[0] + x[1] * x[1]) + (x[2] * x[2] + x[3] * x[3]);
;                     }
;                     asm volatile("s_waitcnt lgkmcnt(0)" ::: "memory");
;                 }
; #pragma unroll
;                 for (int i = 0; i < 2; ++i) { float t = sq[i]; t += dpp_f(t, 0); t += dpp_f(t, 1); t += dpp_f(t, 2);
;                     if (ch == 0) ss[(size_t)(row0 + 8 * i) * 16 + u.pn * 4 + wc] = t; }
.LBB0_376:
	s_or_b64 exec, exec, s[30:31]
	v_mov_b32_e32 v193, v192
	v_pk_mul_f32 v[110:111], v[110:111], v[192:193]
	v_pk_mul_f32 v[108:109], v[108:109], v[198:199]
	v_pk_mul_f32 v[106:107], v[106:107], v[192:193]
	v_pk_mul_f32 v[104:105], v[104:105], v[198:199]
	ds_write_b128 v228, v[108:111]
	ds_write_b128 v228, v[104:107] offset:64
	ds_read_b128 v[104:107], v229
	v_lshlrev_b64 v[114:115], 11, v[222:223]
	v_lshlrev_b64 v[116:117], 11, v[220:221]
	v_lshl_add_u64 v[114:115], s[74:75], 0, v[114:115]
	v_lshl_add_u64 v[116:117], s[74:75], 0, v[116:117]
	s_waitcnt lgkmcnt(0)
	v_pk_add_f32 v[110:111], v[174:175], v[106:107]
	v_pk_add_f32 v[112:113], v[172:173], v[104:105]
	v_lshl_add_u64 v[114:115], v[114:115], 0, v[188:189]
	v_cvt_pk_bf16_f32 v104, v112, v113
	v_cvt_pk_bf16_f32 v105, v110, v111
	ds_read_b128 v[106:109], v229 offset:1152
	v_lshl_add_u64 v[116:117], v[116:117], 0, v[188:189]
	global_store_dwordx2 v[114:115], v[104:105], off
	v_pk_mul_f32 v[102:103], v[102:103], v[192:193]
	v_pk_mul_f32 v[100:101], v[100:101], v[198:199]
	s_waitcnt lgkmcnt(0)
	v_pk_add_f32 v[104:105], v[170:171], v[108:109]
	v_pk_add_f32 v[106:107], v[168:169], v[106:107]
	v_pk_mul_f32 v[98:99], v[98:99], v[192:193]
	v_cvt_pk_bf16_f32 v108, v106, v107
	v_cvt_pk_bf16_f32 v109, v104, v105
	global_store_dwordx2 v[116:117], v[108:109], off
	v_pk_mul_f32 v[96:97], v[96:97], v[198:199]
	s_waitcnt lgkmcnt(0)
	ds_write_b128 v228, v[100:103]
	ds_write_b128 v228, v[96:99] offset:64
	ds_read_b128 v[96:99], v229
	v_mul_f32_e32 v113, v113, v113
	v_mul_f32_e32 v100, v111, v111
	v_fmac_f32_e32 v113, v112, v112
	v_fmac_f32_e32 v100, v110, v110
	s_waitcnt lgkmcnt(0)
	v_pk_add_f32 v[102:103], v[166:167], v[98:99]
	v_pk_add_f32 v[96:97], v[164:165], v[96:97]
	v_add_f32_e32 v108, v113, v100
	v_cvt_pk_bf16_f32 v98, v96, v97
	v_cvt_pk_bf16_f32 v99, v102, v103
	global_store_dwordx2 v[114:115], v[98:99], off offset:256
	ds_read_b128 v[98:101], v229 offset:1152
	v_mul_f32_e32 v97, v97, v97
	v_fmac_f32_e32 v97, v96, v96
	v_mul_f32_e32 v96, v103, v103
	v_fmac_f32_e32 v96, v102, v102
	v_add_f32_e32 v96, v97, v96
	v_add_f32_e32 v102, v108, v96
	s_waitcnt lgkmcnt(0)
	v_pk_add_f32 v[96:97], v[162:163], v[100:101]
	v_pk_add_f32 v[98:99], v[160:161], v[98:99]
	s_nop 0
	v_cvt_pk_bf16_f32 v100, v98, v99
	v_cvt_pk_bf16_f32 v101, v96, v97
	global_store_dwordx2 v[116:117], v[100:101], off offset:256
	s_waitcnt lgkmcnt(0)
	s_nop 0
	v_add_f32_dpp v100, v102, v102 quad_perm:[1,0,3,2] row_mask:0xf bank_mask:0xf bound_ctrl:1
	s_nop 1
	v_add_f32_dpp v100, v100, v100 quad_perm:[2,3,0,1] row_mask:0xf bank_mask:0xf bound_ctrl:1
	s_nop 1
	v_mov_b32_dpp v101, v100 row_shl:4 row_mask:0xf bank_mask:0xf bound_ctrl:1
	s_and_saveexec_b64 s[30:31], s[38:39]
	s_cbranch_execz .LBB0_378
	v_add_f32_e32 v102, v100, v101
	v_lshlrev_b64 v[100:101], 6, v[222:223]
	v_lshl_add_u64 v[100:101], s[28:29], 0, v[100:101]
	global_store_dword v[100:101], v102, off

; __device__ __forceinline__ unsigned pkh(float lo, float hi) { if (!RES_FP16) return cvt_pk_bf16(lo, hi); f16x2 v = {(_Float16)lo, (_Float16)hi}; return __builtin_bit_cast(unsigned, v); }
;     __device__ __forceinline__ void operator()(const f32x4 (&acc)[2][2][4][2], const Unit& u, int wr, int wc, int fr, int fq) const {
;     ...
;         RES_LOAD(0, 0);
; #pragma unroll
;         for (int b = 0; b < 4; ++b) {
;             if (b + 1 < 4) RES_LOAD((b + 1) & 1, b + 1);
; #pragma unroll
;             for (int gg = 0; gg < 2; ++gg) {
;                 const int g = 2 * b + gg, ai = g >> 2, m = g & 3;
;                 const int row0 = u.pm * BM + ai * HALF + wr * 64 + m * 16 + rl;
;                 float sq[2] = {0.f, 0.f};
; #pragma unroll
;                 for (int bj = 0; bj < 2; ++bj) {
;                     *(f32x4*)(wl + fr * 36 + fq * 4) = acc[ai][bj][m][0] * alpha; *(f32x4*)(wl + fr * 36 + 16 + fq * 4) = acc[ai][bj][m][1] * alpha;
;                     asm volatile("s_waitcnt lgkmcnt(0)" ::: "memory");
; #pragma unroll
;                     for (int i = 0; i < 2; ++i) {
;                         const f32x4 x = rb[b & 1][gg][bj][i] + *(const f32x4*)(wl + (rl + 8 * i) * 36 + ch * 4);
;                         const size_t off = (size_t)(row0 + 8 * i) * 1024 + cbase + bj * HALF;
;                         u32x2 w; w.x = pkh(x[0], x[1]); w.y = pkh(x[2], x[3]); *(u32x2*)(X16 + off) = w;
;                         sq[i] += (x[0] * x[0] + x[1] * x[1]) + (x[2] * x[2] + x[3] * x[3]);
;                     }
;                     asm volatile("s_waitcnt lgkmcnt(0)" ::: "memory");
;                 }
; #pragma unroll
;                 for (int i = 0; i < 2; ++i) { float t = sq[i]; t += dpp_f(t, 0); t += dpp_f(t, 1); t += dpp_f(t, 2);
;                     if (ch == 0) ss[(size_t)(row0 + 8 * i) * 16 + u.pn * 4 + wc] = t; }
.LBB0_380:
	s_or_b64 exec, exec, s[30:31]
	v_add_u32_e32 v166, 0x80, v204
	v_add_u32_e32 v164, 0x88, v204
	v_ashrrev_i32_e32 v167, 31, v166
	v_ashrrev_i32_e32 v165, 31, v164
	v_lshlrev_b64 v[96:97], 12, v[166:167]
	v_lshlrev_b64 v[98:99], 12, v[164:165]
	v_add_u32_e32 v162, 0x90, v204
	v_add_u32_e32 v160, 0x98, v204
	v_lshl_add_u64 v[96:97], v[206:207], 0, v[96:97]
	v_lshl_add_u64 v[98:99], v[206:207], 0, v[98:99]
	v_ashrrev_i32_e32 v163, 31, v162
	v_ashrrev_i32_e32 v161, 31, v160
	global_load_dwordx4 v[124:127], v[96:97], off
	global_load_dwordx4 v[116:119], v[96:97], off offset:512
	global_load_dwordx4 v[120:123], v[98:99], off
	global_load_dwordx4 v[112:115], v[98:99], off offset:512
	v_lshlrev_b64 v[96:97], 12, v[162:163]
	v_lshlrev_b64 v[98:99], 12, v[160:161]
	v_lshl_add_u64 v[96:97], v[206:207], 0, v[96:97]
	v_lshl_add_u64 v[98:99], v[206:207], 0, v[98:99]
	global_load_dwordx4 v[108:111], v[96:97], off
	global_load_dwordx4 v[100:103], v[96:97], off offset:512
	global_load_dwordx4 v[104:107], v[98:99], off
	s_nop 0
	global_load_dwordx4 v[96:99], v[98:99], off offset:512
	v_mov_b32_e32 v193, v192
	v_pk_mul_f32 v[94:95], v[94:95], v[192:193]
	v_pk_mul_f32 v[92:93], v[92:93], v[198:199]
	v_pk_mul_f32 v[90:91], v[90:91], v[192:193]
	v_pk_mul_f32 v[88:89], v[88:89], v[198:199]
	ds_write_b128 v228, v[92:95]
	ds_write_b128 v228, v[88:91] offset:64
	ds_read_b128 v[88:91], v229
	v_pk_mul_f32 v[86:87], v[86:87], v[192:193]
	v_pk_mul_f32 v[84:85], v[84:85], v[198:199]
	v_pk_mul_f32 v[82:83], v[82:83], v[192:193]
	v_pk_mul_f32 v[80:81], v[80:81], v[198:199]
	s_waitcnt lgkmcnt(0)
	v_pk_add_f32 v[94:95], v[158:159], v[90:91]
	v_pk_add_f32 v[156:157], v[156:157], v[88:89]
	v_lshlrev_b64 v[158:159], 11, v[218:219]
	v_cvt_pk_bf16_f32 v88, v156, v157
	v_cvt_pk_bf16_f32 v89, v94, v95
	ds_read_b128 v[90:93], v229 offset:1152
	v_lshl_add_u64 v[158:159], s[74:75], 0, v[158:159]
	v_lshl_add_u64 v[158:159], v[158:159], 0, v[188:189]
	global_store_dwordx2 v[158:159], v[88:89], off
	v_mul_f32_e32 v157, v157, v157
	s_waitcnt lgkmcnt(0)
	v_pk_add_f32 v[90:91], v[152:153], v[90:91]
	v_lshlrev_b64 v[152:153], 11, v[216:217]
	v_lshl_add_u64 v[152:153], s[74:75], 0, v[152:153]
	v_lshl_add_u64 v[152:153], v[152:153], 0, v[188:189]
	v_pk_add_f32 v[88:89], v[154:155], v[92:93]
	v_cvt_pk_bf16_f32 v92, v90, v91
	v_fmac_f32_e32 v157, v156, v156
	v_cvt_pk_bf16_f32 v93, v88, v89
	global_store_dwordx2 v[152:153], v[92:93], off
	s_waitcnt lgkmcnt(0)
	ds_write_b128 v228, v[84:87]
	ds_write_b128 v228, v[80:83] offset:64
	ds_read_b128 v[80:83], v229
	v_mul_f32_e32 v84, v95, v95
	v_fmac_f32_e32 v84, v94, v94
	v_add_f32_e32 v92, v157, v84
	s_waitcnt lgkmcnt(0)
	v_pk_add_f32 v[86:87], v[150:151], v[82:83]
	v_pk_add_f32 v[80:81], v[148:149], v[80:81]
	s_nop 0
	v_cvt_pk_bf16_f32 v82, v80, v81
	v_cvt_pk_bf16_f32 v83, v86, v87
	global_store_dwordx2 v[158:159], v[82:83], off offset:256
	ds_read_b128 v[82:85], v229 offset:1152
	v_mul_f32_e32 v81, v81, v81
	v_fmac_f32_e32 v81, v80, v80
	v_mul_f32_e32 v80, v87, v87
	v_fmac_f32_e32 v80, v86, v86
	v_add_f32_e32 v80, v81, v80
	v_add_f32_e32 v86, v92, v80
	s_waitcnt lgkmcnt(0)
	v_pk_add_f32 v[80:81], v[138:139], v[84:85]
	v_pk_add_f32 v[82:83], v[136:137], v[82:83]
	s_nop 0
	v_cvt_pk_bf16_f32 v84, v82, v83
	v_cvt_pk_bf16_f32 v85, v80, v81
	global_store_dwordx2 v[152:153], v[84:85], off offset:256
	s_waitcnt lgkmcnt(0)
	s_nop 0
	v_add_f32_dpp v84, v86, v86 quad_perm:[1,0,3,2] row_mask:0xf bank_mask:0xf bound_ctrl:1
	s_nop 1
	v_add_f32_dpp v84, v84, v84 quad_perm:[2,3,0,1] row_mask:0xf bank_mask:0xf bound_ctrl:1
	s_nop 1
	v_mov_b32_dpp v85, v84 row_shl:4 row_mask:0xf bank_mask:0xf bound_ctrl:1
	s_and_saveexec_b64 s[30:31], s[38:39]
	s_cbranch_execz .LBB0_382
	v_add_f32_e32 v86, v84, v85
	v_lshlrev_b64 v[84:85], 6, v[218:219]
	v_lshl_add_u64 v[84:85], s[28:29], 0, v[84:85]
	global_store_dword v[84:85], v86, off

; __device__ __forceinline__ unsigned pkh(float lo, float hi) { if (!RES_FP16) return cvt_pk_bf16(lo, hi); f16x2 v = {(_Float16)lo, (_Float16)hi}; return __builtin_bit_cast(unsigned, v); }
;     __device__ __forceinline__ void operator()(const f32x4 (&acc)[2][2][4][2], const Unit& u, int wr, int wc, int fr, int fq) const {
;     ...
;             for (int gg = 0; gg < 2; ++gg) {
;                 const int g = 2 * b + gg, ai = g >> 2, m = g & 3;
;                 const int row0 = u.pm * BM + ai * HALF + wr * 64 + m * 16 + rl;
;                 float sq[2] = {0.f, 0.f};
; #pragma unroll
;                 for (int bj = 0; bj < 2; ++bj) {
;                     *(f32x4*)(wl + fr * 36 + fq * 4) = acc[ai][bj][m][0] * alpha; *(f32x4*)(wl + fr * 36 + 16 + fq * 4) = acc[ai][bj][m][1] * alpha;
;                     asm volatile("s_waitcnt lgkmcnt(0)" ::: "memory");
; #pragma unroll
;                     for (int i = 0; i < 2; ++i) {
;                         const f32x4 x = rb[b & 1][gg][bj][i] + *(const f32x4*)(wl + (rl + 8 * i) * 36 + ch * 4);
;                         const size_t off = (size_t)(row0 + 8 * i) * 1024 + cbase + bj * HALF;
;                         u32x2 w; w.x = pkh(x[0], x[1]); w.y = pkh(x[2], x[3]); *(u32x2*)(X16 + off) = w;
;                         sq[i] += (x[0] * x[0] + x[1] * x[1]) + (x[2] * x[2] + x[3] * x[3]);
;                     }
;                     asm volatile("s_waitcnt lgkmcnt(0)" ::: "memory");
;                 }
; #pragma unroll
;                 for (int i = 0; i < 2; ++i) { float t = sq[i]; t += dpp_f(t, 0); t += dpp_f(t, 1); t += dpp_f(t, 2);
;                     if (ch == 0) ss[(size_t)(row0 + 8 * i) * 16 + u.pn * 4 + wc] = t; }
.LBB0_384:
	s_or_b64 exec, exec, s[30:31]
	v_mov_b32_e32 v193, v192
	v_pk_mul_f32 v[78:79], v[78:79], v[192:193]
	v_pk_mul_f32 v[76:77], v[76:77], v[198:199]
	v_pk_mul_f32 v[74:75], v[74:75], v[192:193]
	v_pk_mul_f32 v[72:73], v[72:73], v[198:199]
	ds_write_b128 v228, v[76:79]
	ds_write_b128 v228, v[72:75] offset:64
	ds_read_b128 v[72:75], v229
	v_lshlrev_b64 v[82:83], 11, v[214:215]
	v_lshlrev_b64 v[84:85], 11, v[212:213]
	v_lshl_add_u64 v[82:83], s[74:75], 0, v[82:83]
	v_lshl_add_u64 v[84:85], s[74:75], 0, v[84:85]
	s_waitcnt lgkmcnt(0)
	v_pk_add_f32 v[78:79], v[130:131], v[74:75]
	v_pk_add_f32 v[80:81], v[128:129], v[72:73]
	v_lshl_add_u64 v[82:83], v[82:83], 0, v[188:189]
	v_cvt_pk_bf16_f32 v72, v80, v81
	v_cvt_pk_bf16_f32 v73, v78, v79
	ds_read_b128 v[74:77], v229 offset:1152
	v_lshl_add_u64 v[84:85], v[84:85], 0, v[188:189]
	global_store_dwordx2 v[82:83], v[72:73], off
	v_pk_mul_f32 v[70:71], v[70:71], v[192:193]
	v_pk_mul_f32 v[68:69], v[68:69], v[198:199]
	s_waitcnt lgkmcnt(0)
	v_pk_add_f32 v[72:73], v[146:147], v[76:77]
	v_pk_add_f32 v[74:75], v[144:145], v[74:75]
	v_pk_mul_f32 v[66:67], v[66:67], v[192:193]
	v_cvt_pk_bf16_f32 v76, v74, v75
	v_cvt_pk_bf16_f32 v77, v72, v73
	global_store_dwordx2 v[84:85], v[76:77], off
	v_pk_mul_f32 v[64:65], v[64:65], v[198:199]
	s_waitcnt lgkmcnt(0)
	ds_write_b128 v228, v[68:71]
	ds_write_b128 v228, v[64:67] offset:64
	ds_read_b128 v[64:67], v229
	v_mul_f32_e32 v81, v81, v81
	v_mul_f32_e32 v68, v79, v79
	v_fmac_f32_e32 v81, v80, v80
	v_fmac_f32_e32 v68, v78, v78
	s_waitcnt lgkmcnt(0)
	v_pk_add_f32 v[70:71], v[142:143], v[66:67]
	v_pk_add_f32 v[64:65], v[140:141], v[64:65]
	v_add_f32_e32 v76, v81, v68
	v_cvt_pk_bf16_f32 v66, v64, v65
	v_cvt_pk_bf16_f32 v67, v70, v71
	global_store_dwordx2 v[82:83], v[66:67], off offset:256
	ds_read_b128 v[66:69], v229 offset:1152
	v_mul_f32_e32 v65, v65, v65
	v_fmac_f32_e32 v65, v64, v64
	v_mul_f32_e32 v64, v71, v71
	v_fmac_f32_e32 v64, v70, v70
	v_add_f32_e32 v64, v65, v64
	v_add_f32_e32 v70, v76, v64
	s_waitcnt lgkmcnt(0)
	v_pk_add_f32 v[64:65], v[134:135], v[68:69]
	v_pk_add_f32 v[66:67], v[132:133], v[66:67]
	s_nop 0
	v_cvt_pk_bf16_f32 v68, v66, v67
	v_cvt_pk_bf16_f32 v69, v64, v65
	global_store_dwordx2 v[84:85], v[68:69], off offset:256
	s_waitcnt lgkmcnt(0)
	s_nop 0
	v_add_f32_dpp v68, v70, v70 quad_perm:[1,0,3,2] row_mask:0xf bank_mask:0xf bound_ctrl:1
	s_nop 1
	v_add_f32_dpp v68, v68, v68 quad_perm:[2,3,0,1] row_mask:0xf bank_mask:0xf bound_ctrl:1
	s_nop 1
	v_mov_b32_dpp v69, v68 row_shl:4 row_mask:0xf bank_mask:0xf bound_ctrl:1
	s_and_saveexec_b64 s[30:31], s[38:39]
	s_cbranch_execz .LBB0_386
	v_add_f32_e32 v70, v68, v69
	v_lshlrev_b64 v[68:69], 6, v[214:215]
	v_lshl_add_u64 v[68:69], s[28:29], 0, v[68:69]
	global_store_dword v[68:69], v70, off

; __device__ __forceinline__ unsigned pkh(float lo, float hi) { if (!RES_FP16) return cvt_pk_bf16(lo, hi); f16x2 v = {(_Float16)lo, (_Float16)hi}; return __builtin_bit_cast(unsigned, v); }
;     __device__ __forceinline__ void operator()(const f32x4 (&acc)[2][2][4][2], const Unit& u, int wr, int wc, int fr, int fq) const {
;     ...
;         RES_LOAD(0, 0);
; #pragma unroll
;         for (int b = 0; b < 4; ++b) {
;             if (b + 1 < 4) RES_LOAD((b + 1) & 1, b + 1);
; #pragma unroll
;             for (int gg = 0; gg < 2; ++gg) {
;                 const int g = 2 * b + gg, ai = g >> 2, m = g & 3;
;                 const int row0 = u.pm * BM + ai * HALF + wr * 64 + m * 16 + rl;
;                 float sq[2] = {0.f, 0.f};
; #pragma unroll
;                 for (int bj = 0; bj < 2; ++bj) {
;                     *(f32x4*)(wl + fr * 36 + fq * 4) = acc[ai][bj][m][0] * alpha; *(f32x4*)(wl + fr * 36 + 16 + fq * 4) = acc[ai][bj][m][1] * alpha;
;                     asm volatile("s_waitcnt lgkmcnt(0)" ::: "memory");
; #pragma unroll
;                     for (int i = 0; i < 2; ++i) {
;                         const f32x4 x = rb[b & 1][gg][bj][i] + *(const f32x4*)(wl + (rl + 8 * i) * 36 + ch * 4);
;                         const size_t off = (size_t)(row0 + 8 * i) * 1024 + cbase + bj * HALF;
;                         u32x2 w; w.x = pkh(x[0], x[1]); w.y = pkh(x[2], x[3]); *(u32x2*)(X16 + off) = w;
;                         sq[i] += (x[0] * x[0] + x[1] * x[1]) + (x[2] * x[2] + x[3] * x[3]);
;                     }
;                     asm volatile("s_waitcnt lgkmcnt(0)" ::: "memory");
;                 }
; #pragma unroll
;                 for (int i = 0; i < 2; ++i) { float t = sq[i]; t += dpp_f(t, 0); t += dpp_f(t, 1); t += dpp_f(t, 2);
;                     if (ch == 0) ss[(size_t)(row0 + 8 * i) * 16 + u.pn * 4 + wc] = t; }
.LBB0_388:
	s_or_b64 exec, exec, s[30:31]
	v_add_u32_e32 v134, 0xa0, v204
	v_add_u32_e32 v132, 0xa8, v204
	v_ashrrev_i32_e32 v135, 31, v134
	v_ashrrev_i32_e32 v133, 31, v132
	v_lshlrev_b64 v[64:65], 12, v[134:135]
	v_lshlrev_b64 v[66:67], 12, v[132:133]
	v_add_u32_e32 v130, 0xb0, v204
	v_add_u32_e32 v128, 0xb8, v204
	v_lshl_add_u64 v[64:65], v[206:207], 0, v[64:65]
	v_lshl_add_u64 v[66:67], v[206:207], 0, v[66:67]
	v_ashrrev_i32_e32 v131, 31, v130
	v_ashrrev_i32_e32 v129, 31, v128
	global_load_dwordx4 v[92:95], v[64:65], off
	global_load_dwordx4 v[84:87], v[64:65], off offset:512
	global_load_dwordx4 v[88:91], v[66:67], off
	global_load_dwordx4 v[80:83], v[66:67], off offset:512
	v_lshlrev_b64 v[64:65], 12, v[130:131]
	v_lshlrev_b64 v[66:67], 12, v[128:129]
	v_lshl_add_u64 v[64:65], v[206:207], 0, v[64:65]
	v_lshl_add_u64 v[66:67], v[206:207], 0, v[66:67]
	global_load_dwordx4 v[76:79], v[64:65], off
	global_load_dwordx4 v[68:71], v[64:65], off offset:512
	global_load_dwordx4 v[72:75], v[66:67], off
	s_nop 0
	global_load_dwordx4 v[64:67], v[66:67], off offset:512
	v_mov_b32_e32 v193, v192
	v_pk_mul_f32 v[62:63], v[62:63], v[192:193]
	v_pk_mul_f32 v[60:61], v[60:61], v[198:199]
	v_pk_mul_f32 v[58:59], v[58:59], v[192:193]
	v_pk_mul_f32 v[56:57], v[56:57], v[198:199]
	ds_write_b128 v228, v[60:63]
	ds_write_b128 v228, v[56:59] offset:64
	ds_read_b128 v[56:59], v229
	v_pk_mul_f32 v[54:55], v[54:55], v[192:193]
	v_pk_mul_f32 v[52:53], v[52:53], v[198:199]
	v_pk_mul_f32 v[50:51], v[50:51], v[192:193]
	v_pk_mul_f32 v[48:49], v[48:49], v[198:199]
	s_waitcnt vmcnt(23) lgkmcnt(0)
	v_pk_add_f32 v[62:63], v[126:127], v[58:59]
	v_pk_add_f32 v[124:125], v[124:125], v[56:57]
	v_lshlrev_b64 v[126:127], 11, v[166:167]
	v_cvt_pk_bf16_f32 v56, v124, v125
	v_cvt_pk_bf16_f32 v57, v62, v63
	ds_read_b128 v[58:61], v229 offset:1152
	v_lshl_add_u64 v[126:127], s[74:75], 0, v[126:127]
	v_lshl_add_u64 v[126:127], v[126:127], 0, v[188:189]
	global_store_dwordx2 v[126:127], v[56:57], off
	v_mul_f32_e32 v125, v125, v125
	s_waitcnt vmcnt(22) lgkmcnt(0)
	v_pk_add_f32 v[56:57], v[122:123], v[60:61]
	v_or_b32_e32 v60, 8, v166
	v_ashrrev_i32_e32 v61, 31, v60
	v_lshlrev_b64 v[60:61], 11, v[60:61]
	v_lshl_add_u64 v[60:61], s[74:75], 0, v[60:61]
	v_lshl_add_u64 v[60:61], v[60:61], 0, v[188:189]
	v_pk_add_f32 v[58:59], v[120:121], v[58:59]
	v_fmac_f32_e32 v125, v124, v124
	v_cvt_pk_bf16_f32 v120, v58, v59
	v_cvt_pk_bf16_f32 v121, v56, v57
	global_store_dwordx2 v[60:61], v[120:121], off
	s_waitcnt lgkmcnt(0)
	ds_write_b128 v228, v[52:55]
	ds_write_b128 v228, v[48:51] offset:64
	ds_read_b128 v[48:51], v229
	v_mul_f32_e32 v52, v63, v63
	v_fmac_f32_e32 v52, v62, v62
	v_add_f32_e32 v62, v125, v52
	s_waitcnt lgkmcnt(0)
	v_pk_add_f32 v[54:55], v[118:119], v[50:51]
	v_pk_add_f32 v[48:49], v[116:117], v[48:49]
	s_nop 0
	v_cvt_pk_bf16_f32 v50, v48, v49
	v_cvt_pk_bf16_f32 v51, v54, v55
	global_store_dwordx2 v[126:127], v[50:51], off offset:256
	ds_read_b128 v[50:53], v229 offset:1152
	v_mul_f32_e32 v49, v49, v49
	v_fmac_f32_e32 v49, v48, v48
	v_mul_f32_e32 v48, v55, v55
	v_fmac_f32_e32 v48, v54, v54
	v_add_f32_e32 v48, v49, v48
	v_add_f32_e32 v54, v62, v48
	s_waitcnt vmcnt(23) lgkmcnt(0)
	v_pk_add_f32 v[48:49], v[114:115], v[52:53]
	v_pk_add_f32 v[50:51], v[112:113], v[50:51]
	s_nop 0
	v_cvt_pk_bf16_f32 v52, v50, v51
	v_cvt_pk_bf16_f32 v53, v48, v49
	global_store_dwordx2 v[60:61], v[52:53], off offset:256
	s_waitcnt lgkmcnt(0)
	s_nop 0
	v_add_f32_dpp v52, v54, v54 quad_perm:[1,0,3,2] row_mask:0xf bank_mask:0xf bound_ctrl:1
	s_nop 1
	v_add_f32_dpp v52, v52, v52 quad_perm:[2,3,0,1] row_mask:0xf bank_mask:0xf bound_ctrl:1
	s_nop 1
	v_mov_b32_dpp v53, v52 row_shl:4 row_mask:0xf bank_mask:0xf bound_ctrl:1
	s_and_saveexec_b64 s[30:31], s[38:39]
	s_cbranch_execz .LBB0_390
	v_add_f32_e32 v54, v52, v53
	v_lshlrev_b64 v[52:53], 6, v[166:167]
	v_lshl_add_u64 v[52:53], s[28:29], 0, v[52:53]
	global_store_dword v[52:53], v54, off

; __device__ __forceinline__ unsigned pkh(float lo, float hi) { if (!RES_FP16) return cvt_pk_bf16(lo, hi); f16x2 v = {(_Float16)lo, (_Float16)hi}; return __builtin_bit_cast(unsigned, v); }
;     __device__ __forceinline__ void operator()(const f32x4 (&acc)[2][2][4][2], const Unit& u, int wr, int wc, int fr, int fq) const {
;     ...
;             for (int gg = 0; gg < 2; ++gg) {
;                 const int g = 2 * b + gg, ai = g >> 2, m = g & 3;
;                 const int row0 = u.pm * BM + ai * HALF + wr * 64 + m * 16 + rl;
;                 float sq[2] = {0.f, 0.f};
; #pragma unroll
;                 for (int bj = 0; bj < 2; ++bj) {
;                     *(f32x4*)(wl + fr * 36 + fq * 4) = acc[ai][bj][m][0] * alpha; *(f32x4*)(wl + fr * 36 + 16 + fq * 4) = acc[ai][bj][m][1] * alpha;
;                     asm volatile("s_waitcnt lgkmcnt(0)" ::: "memory");
; #pragma unroll
;                     for (int i = 0; i < 2; ++i) {
;                         const f32x4 x = rb[b & 1][gg][bj][i] + *(const f32x4*)(wl + (rl + 8 * i) * 36 + ch * 4);
;                         const size_t off = (size_t)(row0 + 8 * i) * 1024 + cbase + bj * HALF;
;                         u32x2 w; w.x = pkh(x[0], x[1]); w.y = pkh(x[2], x[3]); *(u32x2*)(X16 + off) = w;
;                         sq[i] += (x[0] * x[0] + x[1] * x[1]) + (x[2] * x[2] + x[3] * x[3]);
;                     }
;                     asm volatile("s_waitcnt lgkmcnt(0)" ::: "memory");
;                 }
; #pragma unroll
;                 for (int i = 0; i < 2; ++i) { float t = sq[i]; t += dpp_f(t, 0); t += dpp_f(t, 1); t += dpp_f(t, 2);
;                     if (ch == 0) ss[(size_t)(row0 + 8 * i) * 16 + u.pn * 4 + wc] = t; }
.LBB0_392:
	s_or_b64 exec, exec, s[30:31]
	v_mov_b32_e32 v193, v192
	v_pk_mul_f32 v[46:47], v[46:47], v[192:193]
	v_pk_mul_f32 v[44:45], v[44:45], v[198:199]
	v_pk_mul_f32 v[42:43], v[42:43], v[192:193]
	v_pk_mul_f32 v[40:41], v[40:41], v[198:199]
	ds_write_b128 v228, v[44:47]
	ds_write_b128 v228, v[40:43] offset:64
	ds_read_b128 v[40:43], v229
	v_lshlrev_b64 v[50:51], 11, v[162:163]
	v_lshl_add_u64 v[50:51], s[74:75], 0, v[50:51]
	v_lshl_add_u64 v[50:51], v[50:51], 0, v[188:189]
	v_pk_mul_f32 v[38:39], v[38:39], v[192:193]
	s_waitcnt vmcnt(23) lgkmcnt(0)
	v_pk_add_f32 v[46:47], v[110:111], v[42:43]
	v_pk_add_f32 v[48:49], v[108:109], v[40:41]
	v_pk_mul_f32 v[36:37], v[36:37], v[198:199]
	v_cvt_pk_bf16_f32 v40, v48, v49
	v_cvt_pk_bf16_f32 v41, v46, v47
	ds_read_b128 v[42:45], v229 offset:1152
	global_store_dwordx2 v[50:51], v[40:41], off
	v_pk_mul_f32 v[34:35], v[34:35], v[192:193]
	v_pk_mul_f32 v[32:33], v[32:33], v[198:199]
	v_mul_f32_e32 v49, v49, v49
	s_waitcnt vmcnt(22) lgkmcnt(0)
	v_pk_add_f32 v[40:41], v[106:107], v[44:45]
	v_or_b32_e32 v44, 8, v162
	v_ashrrev_i32_e32 v45, 31, v44
	v_lshlrev_b64 v[44:45], 11, v[44:45]
	v_lshl_add_u64 v[44:45], s[74:75], 0, v[44:45]
	v_lshl_add_u64 v[44:45], v[44:45], 0, v[188:189]
	v_pk_add_f32 v[42:43], v[104:105], v[42:43]
	v_fmac_f32_e32 v49, v48, v48
	v_cvt_pk_bf16_f32 v52, v42, v43
	v_cvt_pk_bf16_f32 v53, v40, v41
	global_store_dwordx2 v[44:45], v[52:53], off
	s_waitcnt lgkmcnt(0)
	ds_write_b128 v228, v[36:39]
	ds_write_b128 v228, v[32:35] offset:64
	ds_read_b128 v[32:35], v229
	v_mul_f32_e32 v36, v47, v47
	v_fmac_f32_e32 v36, v46, v46
	v_add_f32_e32 v46, v49, v36
	s_waitcnt lgkmcnt(0)
	v_pk_add_f32 v[38:39], v[102:103], v[34:35]
	v_pk_add_f32 v[32:33], v[100:101], v[32:33]
	s_nop 0
	v_cvt_pk_bf16_f32 v34, v32, v33
	v_cvt_pk_bf16_f32 v35, v38, v39
	global_store_dwordx2 v[50:51], v[34:35], off offset:256
	ds_read_b128 v[34:37], v229 offset:1152
	v_mul_f32_e32 v33, v33, v33
	v_fmac_f32_e32 v33, v32, v32
	v_mul_f32_e32 v32, v39, v39
	v_fmac_f32_e32 v32, v38, v38
	v_add_f32_e32 v32, v33, v32
	v_add_f32_e32 v38, v46, v32
	s_waitcnt vmcnt(23) lgkmcnt(0)
	v_pk_add_f32 v[32:33], v[98:99], v[36:37]
	v_pk_add_f32 v[34:35], v[96:97], v[34:35]
	s_nop 0
	v_cvt_pk_bf16_f32 v36, v34, v35
	v_cvt_pk_bf16_f32 v37, v32, v33
	global_store_dwordx2 v[44:45], v[36:37], off offset:256
	s_waitcnt lgkmcnt(0)
	s_nop 0
	v_add_f32_dpp v36, v38, v38 quad_perm:[1,0,3,2] row_mask:0xf bank_mask:0xf bound_ctrl:1
	s_nop 1
	v_add_f32_dpp v36, v36, v36 quad_perm:[2,3,0,1] row_mask:0xf bank_mask:0xf bound_ctrl:1
	s_nop 1
	v_mov_b32_dpp v37, v36 row_shl:4 row_mask:0xf bank_mask:0xf bound_ctrl:1
	s_and_saveexec_b64 s[30:31], s[38:39]
	s_cbranch_execz .LBB0_394
	v_add_f32_e32 v38, v36, v37
	v_lshlrev_b64 v[36:37], 6, v[162:163]
	v_lshl_add_u64 v[36:37], s[28:29], 0, v[36:37]
	global_store_dword v[36:37], v38, off

; __device__ __forceinline__ unsigned pkh(float lo, float hi) { if (!RES_FP16) return cvt_pk_bf16(lo, hi); f16x2 v = {(_Float16)lo, (_Float16)hi}; return __builtin_bit_cast(unsigned, v); }
;     __device__ __forceinline__ void operator()(const f32x4 (&acc)[2][2][4][2], const Unit& u, int wr, int wc, int fr, int fq) const {
;     ...
;             for (int gg = 0; gg < 2; ++gg) {
;                 const int g = 2 * b + gg, ai = g >> 2, m = g & 3;
;                 const int row0 = u.pm * BM + ai * HALF + wr * 64 + m * 16 + rl;
;                 float sq[2] = {0.f, 0.f};
; #pragma unroll
;                 for (int bj = 0; bj < 2; ++bj) {
;                     *(f32x4*)(wl + fr * 36 + fq * 4) = acc[ai][bj][m][0] * alpha; *(f32x4*)(wl + fr * 36 + 16 + fq * 4) = acc[ai][bj][m][1] * alpha;
;                     asm volatile("s_waitcnt lgkmcnt(0)" ::: "memory");
; #pragma unroll
;                     for (int i = 0; i < 2; ++i) {
;                         const f32x4 x = rb[b & 1][gg][bj][i] + *(const f32x4*)(wl + (rl + 8 * i) * 36 + ch * 4);
;                         const size_t off = (size_t)(row0 + 8 * i) * 1024 + cbase + bj * HALF;
;                         u32x2 w; w.x = pkh(x[0], x[1]); w.y = pkh(x[2], x[3]); *(u32x2*)(X16 + off) = w;
;                         sq[i] += (x[0] * x[0] + x[1] * x[1]) + (x[2] * x[2] + x[3] * x[3]);
;                     }
;                     asm volatile("s_waitcnt lgkmcnt(0)" ::: "memory");
;                 }
; #pragma unroll
;                 for (int i = 0; i < 2; ++i) { float t = sq[i]; t += dpp_f(t, 0); t += dpp_f(t, 1); t += dpp_f(t, 2);
;                     if (ch == 0) ss[(size_t)(row0 + 8 * i) * 16 + u.pn * 4 + wc] = t; }
.LBB0_396:
	s_or_b64 exec, exec, s[30:31]
	v_mov_b32_e32 v193, v192
	v_pk_mul_f32 v[30:31], v[30:31], v[192:193]
	v_pk_mul_f32 v[28:29], v[28:29], v[198:199]
	v_pk_mul_f32 v[26:27], v[26:27], v[192:193]
	v_pk_mul_f32 v[24:25], v[24:25], v[198:199]
	ds_write_b128 v228, v[28:31]
	ds_write_b128 v228, v[24:27] offset:64
	ds_read_b128 v[24:27], v229
	v_lshlrev_b64 v[34:35], 11, v[134:135]
	v_lshl_add_u64 v[34:35], s[74:75], 0, v[34:35]
	v_lshl_add_u64 v[34:35], v[34:35], 0, v[188:189]
	v_pk_mul_f32 v[22:23], v[22:23], v[192:193]
	s_waitcnt vmcnt(15) lgkmcnt(0)
	v_pk_add_f32 v[30:31], v[94:95], v[26:27]
	v_pk_add_f32 v[32:33], v[92:93], v[24:25]
	v_pk_mul_f32 v[20:21], v[20:21], v[198:199]
	v_cvt_pk_bf16_f32 v24, v32, v33
	v_cvt_pk_bf16_f32 v25, v30, v31
	ds_read_b128 v[26:29], v229 offset:1152
	global_store_dwordx2 v[34:35], v[24:25], off
	v_pk_mul_f32 v[18:19], v[18:19], v[192:193]
	v_pk_mul_f32 v[16:17], v[16:17], v[198:199]
	v_mul_f32_e32 v33, v33, v33
	s_waitcnt vmcnt(14) lgkmcnt(0)
	v_pk_add_f32 v[24:25], v[90:91], v[28:29]
	v_or_b32_e32 v28, 8, v134
	v_ashrrev_i32_e32 v29, 31, v28
	v_lshlrev_b64 v[28:29], 11, v[28:29]
	v_lshl_add_u64 v[28:29], s[74:75], 0, v[28:29]
	v_lshl_add_u64 v[28:29], v[28:29], 0, v[188:189]
	v_pk_add_f32 v[26:27], v[88:89], v[26:27]
	v_fmac_f32_e32 v33, v32, v32
	v_cvt_pk_bf16_f32 v36, v26, v27
	v_cvt_pk_bf16_f32 v37, v24, v25
	global_store_dwordx2 v[28:29], v[36:37], off
	s_waitcnt lgkmcnt(0)
	ds_write_b128 v228, v[20:23]
	ds_write_b128 v228, v[16:19] offset:64
	ds_read_b128 v[16:19], v229
	v_mul_f32_e32 v20, v31, v31
	v_fmac_f32_e32 v20, v30, v30
	v_add_f32_e32 v30, v33, v20
	s_waitcnt lgkmcnt(0)
	v_pk_add_f32 v[22:23], v[86:87], v[18:19]
	v_pk_add_f32 v[16:17], v[84:85], v[16:17]
	s_nop 0
	v_cvt_pk_bf16_f32 v18, v16, v17
	v_cvt_pk_bf16_f32 v19, v22, v23
	global_store_dwordx2 v[34:35], v[18:19], off offset:256
	ds_read_b128 v[18:21], v229 offset:1152
	v_mul_f32_e32 v17, v17, v17
	v_fmac_f32_e32 v17, v16, v16
	v_mul_f32_e32 v16, v23, v23
	v_fmac_f32_e32 v16, v22, v22
	v_add_f32_e32 v16, v17, v16
	v_add_f32_e32 v22, v30, v16
	s_waitcnt vmcnt(15) lgkmcnt(0)
	v_pk_add_f32 v[16:17], v[82:83], v[20:21]
	v_pk_add_f32 v[18:19], v[80:81], v[18:19]
	s_nop 0
	v_cvt_pk_bf16_f32 v20, v18, v19
	v_cvt_pk_bf16_f32 v21, v16, v17
	global_store_dwordx2 v[28:29], v[20:21], off offset:256
	s_waitcnt lgkmcnt(0)
	s_nop 0
	v_add_f32_dpp v20, v22, v22 quad_perm:[1,0,3,2] row_mask:0xf bank_mask:0xf bound_ctrl:1
	s_nop 1
	v_add_f32_dpp v20, v20, v20 quad_perm:[2,3,0,1] row_mask:0xf bank_mask:0xf bound_ctrl:1
	s_nop 1
	v_mov_b32_dpp v21, v20 row_shl:4 row_mask:0xf bank_mask:0xf bound_ctrl:1
	s_and_saveexec_b64 s[30:31], s[38:39]
	s_cbranch_execz .LBB0_398
	v_add_f32_e32 v22, v20, v21
	v_lshlrev_b64 v[20:21], 6, v[134:135]
	v_lshl_add_u64 v[20:21], s[28:29], 0, v[20:21]
	global_store_dword v[20:21], v22, off

; __device__ __forceinline__ unsigned pkh(float lo, float hi) { if (!RES_FP16) return cvt_pk_bf16(lo, hi); f16x2 v = {(_Float16)lo, (_Float16)hi}; return __builtin_bit_cast(unsigned, v); }
;     __device__ __forceinline__ void operator()(const f32x4 (&acc)[2][2][4][2], const Unit& u, int wr, int wc, int fr, int fq) const {
;     ...
;             for (int gg = 0; gg < 2; ++gg) {
;                 const int g = 2 * b + gg, ai = g >> 2, m = g & 3;
;                 const int row0 = u.pm * BM + ai * HALF + wr * 64 + m * 16 + rl;
;                 float sq[2] = {0.f, 0.f};
; #pragma unroll
;                 for (int bj = 0; bj < 2; ++bj) {
;                     *(f32x4*)(wl + fr * 36 + fq * 4) = acc[ai][bj][m][0] * alpha; *(f32x4*)(wl + fr * 36 + 16 + fq * 4) = acc[ai][bj][m][1] * alpha;
;                     asm volatile("s_waitcnt lgkmcnt(0)" ::: "memory");
; #pragma unroll
;                     for (int i = 0; i < 2; ++i) {
;                         const f32x4 x = rb[b & 1][gg][bj][i] + *(const f32x4*)(wl + (rl + 8 * i) * 36 + ch * 4);
;                         const size_t off = (size_t)(row0 + 8 * i) * 1024 + cbase + bj * HALF;
;                         u32x2 w; w.x = pkh(x[0], x[1]); w.y = pkh(x[2], x[3]); *(u32x2*)(X16 + off) = w;
;                         sq[i] += (x[0] * x[0] + x[1] * x[1]) + (x[2] * x[2] + x[3] * x[3]);
;                     }
;                     asm volatile("s_waitcnt lgkmcnt(0)" ::: "memory");
;                 }
; #pragma unroll
;                 for (int i = 0; i < 2; ++i) { float t = sq[i]; t += dpp_f(t, 0); t += dpp_f(t, 1); t += dpp_f(t, 2);
;                     if (ch == 0) ss[(size_t)(row0 + 8 * i) * 16 + u.pn * 4 + wc] = t; }
.LBB0_400:
	s_or_b64 exec, exec, s[30:31]
	v_mov_b32_e32 v193, v192
	v_pk_mul_f32 v[14:15], v[14:15], v[192:193]
	v_pk_mul_f32 v[12:13], v[12:13], v[198:199]
	v_pk_mul_f32 v[10:11], v[10:11], v[192:193]
	v_pk_mul_f32 v[8:9], v[8:9], v[198:199]
	ds_write_b128 v228, v[12:15]
	ds_write_b128 v228, v[8:11] offset:64
	ds_read_b128 v[8:11], v229
	v_lshlrev_b64 v[18:19], 11, v[130:131]
	v_lshl_add_u64 v[18:19], s[74:75], 0, v[18:19]
	v_lshl_add_u64 v[18:19], v[18:19], 0, v[188:189]
	v_pk_mul_f32 v[6:7], v[6:7], v[192:193]
	s_waitcnt vmcnt(15) lgkmcnt(0)
	v_pk_add_f32 v[14:15], v[78:79], v[10:11]
	v_pk_add_f32 v[16:17], v[76:77], v[8:9]
	v_pk_mul_f32 v[4:5], v[4:5], v[198:199]
	v_cvt_pk_bf16_f32 v8, v16, v17
	v_cvt_pk_bf16_f32 v9, v14, v15
	ds_read_b128 v[10:13], v229 offset:1152
	global_store_dwordx2 v[18:19], v[8:9], off
	v_pk_mul_f32 v[2:3], v[2:3], v[192:193]
	v_pk_mul_f32 v[0:1], v[0:1], v[198:199]
	v_mul_f32_e32 v17, v17, v17
	s_waitcnt vmcnt(14) lgkmcnt(0)
	v_pk_add_f32 v[8:9], v[74:75], v[12:13]
	v_or_b32_e32 v12, 8, v130
	v_ashrrev_i32_e32 v13, 31, v12
	v_lshlrev_b64 v[12:13], 11, v[12:13]
	v_lshl_add_u64 v[12:13], s[74:75], 0, v[12:13]
	v_lshl_add_u64 v[12:13], v[12:13], 0, v[188:189]
	v_pk_add_f32 v[10:11], v[72:73], v[10:11]
	v_fmac_f32_e32 v17, v16, v16
	v_cvt_pk_bf16_f32 v20, v10, v11
	v_cvt_pk_bf16_f32 v21, v8, v9
	global_store_dwordx2 v[12:13], v[20:21], off
	s_waitcnt lgkmcnt(0)
	ds_write_b128 v228, v[4:7]
	ds_write_b128 v228, v[0:3] offset:64
	ds_read_b128 v[0:3], v229
	v_mul_f32_e32 v4, v15, v15
	v_fmac_f32_e32 v4, v14, v14
	v_add_f32_e32 v14, v17, v4
	s_waitcnt lgkmcnt(0)
	v_pk_add_f32 v[6:7], v[70:71], v[2:3]
	v_pk_add_f32 v[0:1], v[68:69], v[0:1]
	s_nop 0
	v_cvt_pk_bf16_f32 v2, v0, v1
	v_cvt_pk_bf16_f32 v3, v6, v7
	global_store_dwordx2 v[18:19], v[2:3], off offset:256
	ds_read_b128 v[2:5], v229 offset:1152
	v_mul_f32_e32 v1, v1, v1
	v_fmac_f32_e32 v1, v0, v0
	v_mul_f32_e32 v0, v7, v7
	v_fmac_f32_e32 v0, v6, v6
	v_add_f32_e32 v0, v1, v0
	v_add_f32_e32 v6, v14, v0
	s_waitcnt vmcnt(15) lgkmcnt(0)
	v_pk_add_f32 v[0:1], v[66:67], v[4:5]
	v_pk_add_f32 v[2:3], v[64:65], v[2:3]
	s_nop 0
	v_cvt_pk_bf16_f32 v4, v2, v3
	v_cvt_pk_bf16_f32 v5, v0, v1
	global_store_dwordx2 v[12:13], v[4:5], off offset:256
	s_waitcnt lgkmcnt(0)
	s_nop 0
	v_add_f32_dpp v4, v6, v6 quad_perm:[1,0,3,2] row_mask:0xf bank_mask:0xf bound_ctrl:1
	s_nop 1
	v_add_f32_dpp v4, v4, v4 quad_perm:[2,3,0,1] row_mask:0xf bank_mask:0xf bound_ctrl:1
	s_nop 1
	v_mov_b32_dpp v5, v4 row_shl:4 row_mask:0xf bank_mask:0xf bound_ctrl:1
	s_and_saveexec_b64 s[30:31], s[38:39]
	s_cbranch_execz .LBB0_402
	v_add_f32_e32 v6, v4, v5
	v_lshlrev_b64 v[4:5], 6, v[130:131]
	v_lshl_add_u64 v[4:5], s[28:29], 0, v[4:5]
	global_store_dword v[4:5], v6, off

; __device__ __forceinline__ unsigned pkh(float lo, float hi) { if (!RES_FP16) return cvt_pk_bf16(lo, hi); f16x2 v = {(_Float16)lo, (_Float16)hi}; return __builtin_bit_cast(unsigned, v); }
;     __device__ __forceinline__ void operator()(const f32x4 (&acc)[2][2][4][2], const Unit& u, int wr, int wc, int fr, int fq) const {
;         float* wl = wlds + (wr * 4 + wc) * 576;
;         const int lane = fq * 16 + fr, rl = lane >> 3, ch = lane & 7;
;         f32x4 rb[2][2][2][2];
;         const size_t cbase = (size_t)u.pn * BM + wc * 32 + ch * 4;
;     ...
;         RES_LOAD(0, 0);
; #pragma unroll
;         for (int b = 0; b < 4; ++b) {
;             if (b + 1 < 4) RES_LOAD((b + 1) & 1, b + 1);
; #pragma unroll
;             for (int gg = 0; gg < 2; ++gg) {
;                 const int g = 2 * b + gg, ai = g >> 2, m = g & 3;
;                 const int row0 = u.pm * BM + ai * HALF + wr * 64 + m * 16 + rl;
;                 float sq[2] = {0.f, 0.f};
; #pragma unroll
;                 for (int bj = 0; bj < 2; ++bj) {
;                     *(f32x4*)(wl + fr * 36 + fq * 4) = acc[ai][bj][m][0] * alpha; *(f32x4*)(wl + fr * 36 + 16 + fq * 4) = acc[ai][bj][m][1] * alpha;
;                     asm volatile("s_waitcnt lgkmcnt(0)" ::: "memory");
; #pragma unroll
;                     for (int i = 0; i < 2; ++i) {
;                         const f32x4 x = rb[b & 1][gg][bj][i] + *(const f32x4*)(wl + (rl + 8 * i) * 36 + ch * 4);
;                         const size_t off = (size_t)(row0 + 8 * i) * 1024 + cbase + bj * HALF;
;                         u32x2 w; w.x = pkh(x[0], x[1]); w.y = pkh(x[2], x[3]); *(u32x2*)(X16 + off) = w;
;                         sq[i] += (x[0] * x[0] + x[1] * x[1]) + (x[2] * x[2] + x[3] * x[3]);
;                     }
;                     asm volatile("s_waitcnt lgkmcnt(0)" ::: "memory");
;                 }
; #pragma unroll
;                 for (int i = 0; i < 2; ++i) { float t = sq[i]; t += dpp_f(t, 0); t += dpp_f(t, 1); t += dpp_f(t, 2);
;                     if (ch == 0) ss[(size_t)(row0 + 8 * i) * 16 + u.pn * 4 + wc] = t; }
.LBB0_760:
	s_ashr_i32 s29, s28, 31
	s_lshl_b64 s[30:31], s[28:29], 8
	v_mov_b32_e32 v141, s31
	v_or_b32_e32 v140, s30, v132
	v_lshl_add_u32 v144, s72, 8, v196
	v_lshlrev_b64 v[140:141], 1, v[140:141]
	v_ashrrev_i32_e32 v145, 31, v144
	v_lshl_add_u64 v[142:143], s[74:75], 0, v[140:141]
	v_lshlrev_b64 v[200:201], 11, v[144:145]
	v_lshl_add_u64 v[146:147], v[142:143], 0, v[200:201]
	global_load_dwordx2 v[202:203], v[146:147], off
	v_or_b32_e32 v186, 8, v144
	v_ashrrev_i32_e32 v187, 31, v186
	v_lshlrev_b64 v[204:205], 11, v[186:187]
	v_lshl_add_u64 v[148:149], v[142:143], 0, v[204:205]
	global_load_dwordx2 v[206:207], v[148:149], off
	global_load_dwordx2 v[212:213], v[148:149], off offset:256
	global_load_dwordx2 v[214:215], v[146:147], off offset:256
	v_or_b32_e32 v180, 16, v144
	v_or_b32_e32 v178, 24, v144
	v_or_b32_e32 v158, 32, v144
	v_or_b32_e32 v156, 40, v144
	v_or_b32_e32 v148, 48, v144
	v_or_b32_e32 v146, 56, v144
	v_ashrrev_i32_e32 v181, 31, v180
	v_ashrrev_i32_e32 v179, 31, v178
	v_ashrrev_i32_e32 v159, 31, v158
	v_ashrrev_i32_e32 v157, 31, v156
	v_ashrrev_i32_e32 v149, 31, v148
	v_ashrrev_i32_e32 v147, 31, v146
	v_lshlrev_b64 v[184:185], 11, v[180:181]
	v_lshlrev_b64 v[182:183], 11, v[178:179]
	v_lshlrev_b64 v[168:169], 11, v[158:159]
	v_lshlrev_b64 v[166:167], 11, v[156:157]
	v_lshlrev_b64 v[152:153], 11, v[148:149]
	v_lshlrev_b64 v[150:151], 11, v[146:147]
	v_lshl_add_u64 v[154:155], v[142:143], 0, v[184:185]
	v_lshl_add_u64 v[160:161], v[142:143], 0, v[182:183]
	v_lshl_add_u64 v[162:163], v[142:143], 0, v[168:169]
	v_lshl_add_u64 v[164:165], v[142:143], 0, v[166:167]
	v_lshl_add_u64 v[216:217], v[142:143], 0, v[152:153]
	v_lshl_add_u64 v[218:219], v[142:143], 0, v[150:151]
	global_load_dwordx2 v[194:195], v[154:155], off
	global_load_dwordx2 v[192:193], v[160:161], off
	global_load_dwordx2 v[188:189], v[160:161], off offset:256
	global_load_dwordx2 v[190:191], v[154:155], off offset:256
	global_load_dwordx2 v[176:177], v[162:163], off
	global_load_dwordx2 v[174:175], v[164:165], off
	global_load_dwordx2 v[170:171], v[164:165], off offset:256
	global_load_dwordx2 v[172:173], v[162:163], off offset:256
	s_nop 0
	global_load_dwordx2 v[164:165], v[216:217], off
	global_load_dwordx2 v[162:163], v[218:219], off
	global_load_dwordx2 v[154:155], v[218:219], off offset:256
	global_load_dwordx2 v[160:161], v[216:217], off offset:256
	v_mov_b32_e32 v131, v130
	v_pk_mul_f32 v[120:121], v[120:121], v[134:135]
	v_pk_mul_f32 v[122:123], v[122:123], v[130:131]
	v_pk_mul_f32 v[124:125], v[124:125], v[134:135]
	v_pk_mul_f32 v[126:127], v[126:127], v[130:131]
	ds_write_b128 v197, v[120:123]
	ds_write_b128 v197, v[124:127] offset:64
	v_lshl_add_u64 v[120:121], s[74:75], 0, v[200:201]
	v_lshl_add_u64 v[126:127], v[120:121], 0, v[140:141]
	ds_read_b128 v[120:123], v198
	v_lshl_add_u64 v[200:201], s[74:75], 0, v[204:205]
	v_lshl_add_u64 v[200:201], v[200:201], 0, v[140:141]
	v_pk_mul_f32 v[118:119], v[118:119], v[130:131]
	v_pk_mul_f32 v[116:117], v[116:117], v[134:135]
	v_pk_mul_f32 v[114:115], v[114:115], v[130:131]
	v_pk_mul_f32 v[112:113], v[112:113], v[134:135]
	s_lshl_b32 s28, s28, 2
	s_ashr_i32 s29, s28, 31
	s_lshl_b64 s[28:29], s[28:29], 2
	s_add_u32 s28, s63, s28
	s_addc_u32 s29, s64, s29
	s_waitcnt vmcnt(0)
	v_lshlrev_b32_e32 v124, 16, v202
	v_and_b32_e32 v125, 0xffff0000, v202
	v_lshlrev_b32_e32 v202, 16, v203
	v_and_b32_e32 v203, 0xffff0000, v203
	s_waitcnt lgkmcnt(0)
	v_pk_add_f32 v[202:203], v[122:123], v[202:203]
	v_pk_add_f32 v[220:221], v[120:121], v[124:125]
	v_lshlrev_b32_e32 v204, 16, v206
	v_cvt_pk_bf16_f32 v120, v220, v221
	v_cvt_pk_bf16_f32 v121, v202, v203
	ds_read_b128 v[122:125], v198 offset:1152
	v_and_b32_e32 v205, 0xffff0000, v206
	v_lshlrev_b32_e32 v206, 16, v207
	v_and_b32_e32 v207, 0xffff0000, v207
	global_store_dwordx2 v[126:127], v[120:121], off
	s_waitcnt lgkmcnt(0)
	v_pk_add_f32 v[120:121], v[124:125], v[206:207]
	v_pk_add_f32 v[122:123], v[122:123], v[204:205]
	v_lshlrev_b32_e32 v216, 16, v214
	v_cvt_pk_bf16_f32 v124, v122, v123
	v_cvt_pk_bf16_f32 v125, v120, v121
	global_store_dwordx2 v[200:201], v[124:125], off
	s_waitcnt lgkmcnt(0)
	ds_write_b128 v197, v[116:119]
	ds_write_b128 v197, v[112:115] offset:64
	ds_read_b128 v[112:115], v198
	v_and_b32_e32 v217, 0xffff0000, v214
	v_lshlrev_b32_e32 v214, 16, v215
	v_and_b32_e32 v215, 0xffff0000, v215
	v_mul_f32_e32 v211, v221, v221
	v_mul_f32_e32 v116, v203, v203
	v_fmac_f32_e32 v211, v220, v220
	v_fmac_f32_e32 v116, v202, v202
	s_waitcnt lgkmcnt(0)
	v_pk_add_f32 v[118:119], v[114:115], v[214:215]
	v_pk_add_f32 v[112:113], v[112:113], v[216:217]
	v_add_f32_e32 v124, v211, v116
	v_cvt_pk_bf16_f32 v114, v112, v113
	v_cvt_pk_bf16_f32 v115, v118, v119
	global_store_dwordx2 v[126:127], v[114:115], off offset:256
	ds_read_b128 v[114:117], v198 offset:1152
	v_mul_f32_e32 v113, v113, v113
	v_fmac_f32_e32 v113, v112, v112
	v_mul_f32_e32 v112, v119, v119
	v_fmac_f32_e32 v112, v118, v118
	v_lshlrev_b32_e32 v218, 16, v212
	v_and_b32_e32 v219, 0xffff0000, v212
	v_lshlrev_b32_e32 v212, 16, v213
	v_and_b32_e32 v213, 0xffff0000, v213
	v_add_f32_e32 v112, v113, v112
	v_add_f32_e32 v118, v124, v112
	s_waitcnt lgkmcnt(0)
	v_pk_add_f32 v[112:113], v[116:117], v[212:213]
	v_pk_add_f32 v[114:115], v[114:115], v[218:219]
	s_nop 0
	v_cvt_pk_bf16_f32 v116, v114, v115
	v_cvt_pk_bf16_f32 v117, v112, v113
	global_store_dwordx2 v[200:201], v[116:117], off offset:256
	s_waitcnt lgkmcnt(0)
	s_nop 0
	v_add_f32_dpp v116, v118, v118 quad_perm:[1,0,3,2] row_mask:0xf bank_mask:0xf bound_ctrl:1
	s_nop 1
	v_add_f32_dpp v116, v116, v116 quad_perm:[2,3,0,1] row_mask:0xf bank_mask:0xf bound_ctrl:1
	s_nop 1
	v_mov_b32_dpp v117, v116 row_shl:4 row_mask:0xf bank_mask:0xf bound_ctrl:1
	s_and_saveexec_b64 s[30:31], s[40:41]
	s_cbranch_execz .LBB0_762
	v_add_f32_e32 v118, v116, v117
	v_lshlrev_b64 v[116:117], 6, v[144:145]
	v_lshl_add_u64 v[116:117], s[28:29], 0, v[116:117]
	global_store_dword v[116:117], v118, off

; __device__ __forceinline__ unsigned pkh(float lo, float hi) { if (!RES_FP16) return cvt_pk_bf16(lo, hi); f16x2 v = {(_Float16)lo, (_Float16)hi}; return __builtin_bit_cast(unsigned, v); }
;     __device__ __forceinline__ void operator()(const f32x4 (&acc)[2][2][4][2], const Unit& u, int wr, int wc, int fr, int fq) const {
;     ...
;             for (int gg = 0; gg < 2; ++gg) {
;                 const int g = 2 * b + gg, ai = g >> 2, m = g & 3;
;                 const int row0 = u.pm * BM + ai * HALF + wr * 64 + m * 16 + rl;
;                 float sq[2] = {0.f, 0.f};
; #pragma unroll
;                 for (int bj = 0; bj < 2; ++bj) {
;                     *(f32x4*)(wl + fr * 36 + fq * 4) = acc[ai][bj][m][0] * alpha; *(f32x4*)(wl + fr * 36 + 16 + fq * 4) = acc[ai][bj][m][1] * alpha;
;                     asm volatile("s_waitcnt lgkmcnt(0)" ::: "memory");
; #pragma unroll
;                     for (int i = 0; i < 2; ++i) {
;                         const f32x4 x = rb[b & 1][gg][bj][i] + *(const f32x4*)(wl + (rl + 8 * i) * 36 + ch * 4);
;                         const size_t off = (size_t)(row0 + 8 * i) * 1024 + cbase + bj * HALF;
;                         u32x2 w; w.x = pkh(x[0], x[1]); w.y = pkh(x[2], x[3]); *(u32x2*)(X16 + off) = w;
;                         sq[i] += (x[0] * x[0] + x[1] * x[1]) + (x[2] * x[2] + x[3] * x[3]);
;                     }
;                     asm volatile("s_waitcnt lgkmcnt(0)" ::: "memory");
;                 }
; #pragma unroll
;                 for (int i = 0; i < 2; ++i) { float t = sq[i]; t += dpp_f(t, 0); t += dpp_f(t, 1); t += dpp_f(t, 2);
;                     if (ch == 0) ss[(size_t)(row0 + 8 * i) * 16 + u.pn * 4 + wc] = t; }
.LBB0_764:
	s_or_b64 exec, exec, s[30:31]
	v_mov_b32_e32 v131, v130
	v_pk_mul_f32 v[110:111], v[110:111], v[130:131]
	v_pk_mul_f32 v[108:109], v[108:109], v[134:135]
	v_pk_mul_f32 v[106:107], v[106:107], v[130:131]
	v_pk_mul_f32 v[104:105], v[104:105], v[134:135]
	ds_write_b128 v197, v[108:111]
	ds_write_b128 v197, v[104:107] offset:64
	ds_read_b128 v[104:107], v198
	v_lshlrev_b32_e32 v112, 16, v194
	v_and_b32_e32 v113, 0xffff0000, v194
	v_lshlrev_b32_e32 v114, 16, v195
	v_and_b32_e32 v115, 0xffff0000, v195
	s_waitcnt lgkmcnt(0)
	v_pk_add_f32 v[114:115], v[106:107], v[114:115]
	v_pk_add_f32 v[112:113], v[104:105], v[112:113]
	v_lshlrev_b32_e32 v116, 16, v192
	v_cvt_pk_bf16_f32 v104, v112, v113
	v_cvt_pk_bf16_f32 v105, v114, v115
	ds_read_b128 v[106:109], v198 offset:1152
	v_and_b32_e32 v117, 0xffff0000, v192
	v_lshl_add_u64 v[126:127], s[74:75], 0, v[184:185]
	v_lshlrev_b32_e32 v118, 16, v193
	v_and_b32_e32 v119, 0xffff0000, v193
	s_waitcnt lgkmcnt(0)
	v_pk_add_f32 v[106:107], v[106:107], v[116:117]
	v_lshl_add_u64 v[116:117], s[74:75], 0, v[182:183]
	v_lshl_add_u64 v[126:127], v[126:127], 0, v[140:141]
	v_lshl_add_u64 v[116:117], v[116:117], 0, v[140:141]
	global_store_dwordx2 v[126:127], v[104:105], off
	v_pk_add_f32 v[104:105], v[108:109], v[118:119]
	v_cvt_pk_bf16_f32 v108, v106, v107
	v_pk_mul_f32 v[102:103], v[102:103], v[130:131]
	v_cvt_pk_bf16_f32 v109, v104, v105
	global_store_dwordx2 v[116:117], v[108:109], off
	v_pk_mul_f32 v[100:101], v[100:101], v[134:135]
	v_pk_mul_f32 v[98:99], v[98:99], v[130:131]
	v_pk_mul_f32 v[96:97], v[96:97], v[134:135]
	s_waitcnt lgkmcnt(0)
	ds_write_b128 v197, v[100:103]
	ds_write_b128 v197, v[96:99] offset:64
	ds_read_b128 v[96:99], v198
	v_lshlrev_b32_e32 v120, 16, v190
	v_and_b32_e32 v121, 0xffff0000, v190
	v_lshlrev_b32_e32 v122, 16, v191
	v_and_b32_e32 v123, 0xffff0000, v191
	v_mul_f32_e32 v113, v113, v113
	v_mul_f32_e32 v100, v115, v115
	v_fmac_f32_e32 v113, v112, v112
	v_fmac_f32_e32 v100, v114, v114
	s_waitcnt lgkmcnt(0)
	v_pk_add_f32 v[102:103], v[98:99], v[122:123]
	v_pk_add_f32 v[96:97], v[96:97], v[120:121]
	v_add_f32_e32 v108, v113, v100
	v_cvt_pk_bf16_f32 v98, v96, v97
	v_cvt_pk_bf16_f32 v99, v102, v103
	global_store_dwordx2 v[126:127], v[98:99], off offset:256
	ds_read_b128 v[98:101], v198 offset:1152
	v_mul_f32_e32 v97, v97, v97
	v_fmac_f32_e32 v97, v96, v96
	v_mul_f32_e32 v96, v103, v103
	v_fmac_f32_e32 v96, v102, v102
	v_lshlrev_b32_e32 v110, 16, v188
	v_and_b32_e32 v111, 0xffff0000, v188
	v_lshlrev_b32_e32 v124, 16, v189
	v_and_b32_e32 v125, 0xffff0000, v189
	v_add_f32_e32 v96, v97, v96
	v_add_f32_e32 v102, v108, v96
	s_waitcnt lgkmcnt(0)
	v_pk_add_f32 v[96:97], v[100:101], v[124:125]
	v_pk_add_f32 v[98:99], v[98:99], v[110:111]
	s_nop 0
	v_cvt_pk_bf16_f32 v100, v98, v99
	v_cvt_pk_bf16_f32 v101, v96, v97
	global_store_dwordx2 v[116:117], v[100:101], off offset:256
	s_waitcnt lgkmcnt(0)
	s_nop 0
	v_add_f32_dpp v100, v102, v102 quad_perm:[1,0,3,2] row_mask:0xf bank_mask:0xf bound_ctrl:1
	s_nop 1
	v_add_f32_dpp v100, v100, v100 quad_perm:[2,3,0,1] row_mask:0xf bank_mask:0xf bound_ctrl:1
	s_nop 1
	v_mov_b32_dpp v101, v100 row_shl:4 row_mask:0xf bank_mask:0xf bound_ctrl:1
	s_and_saveexec_b64 s[30:31], s[40:41]
	s_cbranch_execz .LBB0_766
	v_add_f32_e32 v102, v100, v101
	v_lshlrev_b64 v[100:101], 6, v[180:181]
	v_lshl_add_u64 v[100:101], s[28:29], 0, v[100:101]
	global_store_dword v[100:101], v102, off

; __device__ __forceinline__ unsigned pkh(float lo, float hi) { if (!RES_FP16) return cvt_pk_bf16(lo, hi); f16x2 v = {(_Float16)lo, (_Float16)hi}; return __builtin_bit_cast(unsigned, v); }
;     __device__ __forceinline__ void operator()(const f32x4 (&acc)[2][2][4][2], const Unit& u, int wr, int wc, int fr, int fq) const {
;     ...
;         RES_LOAD(0, 0);
; #pragma unroll
;         for (int b = 0; b < 4; ++b) {
;             if (b + 1 < 4) RES_LOAD((b + 1) & 1, b + 1);
; #pragma unroll
;             for (int gg = 0; gg < 2; ++gg) {
;                 const int g = 2 * b + gg, ai = g >> 2, m = g & 3;
;                 const int row0 = u.pm * BM + ai * HALF + wr * 64 + m * 16 + rl;
;                 float sq[2] = {0.f, 0.f};
; #pragma unroll
;                 for (int bj = 0; bj < 2; ++bj) {
;                     *(f32x4*)(wl + fr * 36 + fq * 4) = acc[ai][bj][m][0] * alpha; *(f32x4*)(wl + fr * 36 + 16 + fq * 4) = acc[ai][bj][m][1] * alpha;
;                     asm volatile("s_waitcnt lgkmcnt(0)" ::: "memory");
; #pragma unroll
;                     for (int i = 0; i < 2; ++i) {
;                         const f32x4 x = rb[b & 1][gg][bj][i] + *(const f32x4*)(wl + (rl + 8 * i) * 36 + ch * 4);
;                         const size_t off = (size_t)(row0 + 8 * i) * 1024 + cbase + bj * HALF;
;                         u32x2 w; w.x = pkh(x[0], x[1]); w.y = pkh(x[2], x[3]); *(u32x2*)(X16 + off) = w;
;                         sq[i] += (x[0] * x[0] + x[1] * x[1]) + (x[2] * x[2] + x[3] * x[3]);
;                     }
;                     asm volatile("s_waitcnt lgkmcnt(0)" ::: "memory");
;                 }
; #pragma unroll
;                 for (int i = 0; i < 2; ++i) { float t = sq[i]; t += dpp_f(t, 0); t += dpp_f(t, 1); t += dpp_f(t, 2);
;                     if (ch == 0) ss[(size_t)(row0 + 8 * i) * 16 + u.pn * 4 + wc] = t; }
.LBB0_768:
	s_or_b64 exec, exec, s[30:31]
	v_add_u32_e32 v112, 0x80, v144
	v_add_u32_e32 v104, 0x88, v144
	v_ashrrev_i32_e32 v113, 31, v112
	v_ashrrev_i32_e32 v105, 31, v104
	v_lshlrev_b64 v[114:115], 11, v[112:113]
	v_lshlrev_b64 v[98:99], 11, v[104:105]
	v_lshl_add_u64 v[96:97], v[142:143], 0, v[114:115]
	v_lshl_add_u64 v[98:99], v[142:143], 0, v[98:99]
	global_load_dwordx2 v[122:123], v[96:97], off
	global_load_dwordx2 v[120:121], v[98:99], off
	global_load_dwordx2 v[116:117], v[98:99], off offset:256
	global_load_dwordx2 v[118:119], v[96:97], off offset:256
	v_add_u32_e32 v98, 0x90, v144
	v_add_u32_e32 v96, 0x98, v144
	v_ashrrev_i32_e32 v99, 31, v98
	v_ashrrev_i32_e32 v97, 31, v96
	v_lshlrev_b64 v[100:101], 11, v[98:99]
	v_lshlrev_b64 v[102:103], 11, v[96:97]
	v_lshl_add_u64 v[106:107], v[142:143], 0, v[100:101]
	v_lshl_add_u64 v[102:103], v[142:143], 0, v[102:103]
	global_load_dwordx2 v[110:111], v[106:107], off
	global_load_dwordx2 v[108:109], v[102:103], off
	s_nop 0
	global_load_dwordx2 v[102:103], v[102:103], off offset:256
	s_nop 0
	global_load_dwordx2 v[106:107], v[106:107], off offset:256
	v_mov_b32_e32 v131, v130
	v_pk_mul_f32 v[94:95], v[94:95], v[130:131]
	v_pk_mul_f32 v[92:93], v[92:93], v[134:135]
	v_pk_mul_f32 v[90:91], v[90:91], v[130:131]
	v_pk_mul_f32 v[88:89], v[88:89], v[134:135]
	ds_write_b128 v197, v[92:95]
	ds_write_b128 v197, v[88:91] offset:64
	ds_read_b128 v[88:91], v198
	v_lshlrev_b32_e32 v124, 16, v176
	v_and_b32_e32 v125, 0xffff0000, v176
	v_lshlrev_b32_e32 v126, 16, v177
	v_and_b32_e32 v127, 0xffff0000, v177
	s_waitcnt lgkmcnt(0)
	v_pk_add_f32 v[126:127], v[90:91], v[126:127]
	v_pk_add_f32 v[124:125], v[88:89], v[124:125]
	v_lshl_add_u64 v[168:169], s[74:75], 0, v[168:169]
	v_cvt_pk_bf16_f32 v88, v124, v125
	v_cvt_pk_bf16_f32 v89, v126, v127
	ds_read_b128 v[90:93], v198 offset:1152
	v_lshl_add_u64 v[166:167], s[74:75], 0, v[166:167]
	v_lshlrev_b32_e32 v176, 16, v174
	v_and_b32_e32 v177, 0xffff0000, v174
	v_lshlrev_b32_e32 v174, 16, v175
	v_and_b32_e32 v175, 0xffff0000, v175
	v_lshl_add_u64 v[168:169], v[168:169], 0, v[140:141]
	v_lshl_add_u64 v[166:167], v[166:167], 0, v[140:141]
	global_store_dwordx2 v[168:169], v[88:89], off
	s_waitcnt lgkmcnt(0)
	v_pk_add_f32 v[88:89], v[92:93], v[174:175]
	v_pk_add_f32 v[90:91], v[90:91], v[176:177]
	v_pk_mul_f32 v[86:87], v[86:87], v[130:131]
	v_cvt_pk_bf16_f32 v92, v90, v91
	v_cvt_pk_bf16_f32 v93, v88, v89
	global_store_dwordx2 v[166:167], v[92:93], off
	v_pk_mul_f32 v[84:85], v[84:85], v[134:135]
	v_pk_mul_f32 v[82:83], v[82:83], v[130:131]
	v_pk_mul_f32 v[80:81], v[80:81], v[134:135]
	s_waitcnt lgkmcnt(0)
	ds_write_b128 v197, v[84:87]
	ds_write_b128 v197, v[80:83] offset:64
	ds_read_b128 v[80:83], v198
	v_lshlrev_b32_e32 v178, 16, v172
	v_and_b32_e32 v179, 0xffff0000, v172
	v_lshlrev_b32_e32 v172, 16, v173
	v_and_b32_e32 v173, 0xffff0000, v173
	v_mul_f32_e32 v125, v125, v125
	v_mul_f32_e32 v84, v127, v127
	v_fmac_f32_e32 v125, v124, v124
	v_fmac_f32_e32 v84, v126, v126
	s_waitcnt lgkmcnt(0)
	v_pk_add_f32 v[86:87], v[82:83], v[172:173]
	v_pk_add_f32 v[80:81], v[80:81], v[178:179]
	v_add_f32_e32 v92, v125, v84
	v_cvt_pk_bf16_f32 v82, v80, v81
	v_cvt_pk_bf16_f32 v83, v86, v87
	global_store_dwordx2 v[168:169], v[82:83], off offset:256
	ds_read_b128 v[82:85], v198 offset:1152
	v_mul_f32_e32 v81, v81, v81
	v_fmac_f32_e32 v81, v80, v80
	v_mul_f32_e32 v80, v87, v87
	v_fmac_f32_e32 v80, v86, v86
	v_lshlrev_b32_e32 v94, 16, v170
	v_and_b32_e32 v95, 0xffff0000, v170
	v_lshlrev_b32_e32 v170, 16, v171
	v_and_b32_e32 v171, 0xffff0000, v171
	v_add_f32_e32 v80, v81, v80
	v_add_f32_e32 v86, v92, v80
	s_waitcnt lgkmcnt(0)
	v_pk_add_f32 v[80:81], v[84:85], v[170:171]
	v_pk_add_f32 v[82:83], v[82:83], v[94:95]
	s_nop 0
	v_cvt_pk_bf16_f32 v84, v82, v83
	v_cvt_pk_bf16_f32 v85, v80, v81
	global_store_dwordx2 v[166:167], v[84:85], off offset:256
	s_waitcnt lgkmcnt(0)
	s_nop 0
	v_add_f32_dpp v84, v86, v86 quad_perm:[1,0,3,2] row_mask:0xf bank_mask:0xf bound_ctrl:1
	s_nop 1
	v_add_f32_dpp v84, v84, v84 quad_perm:[2,3,0,1] row_mask:0xf bank_mask:0xf bound_ctrl:1
	s_nop 1
	v_mov_b32_dpp v85, v84 row_shl:4 row_mask:0xf bank_mask:0xf bound_ctrl:1
	s_and_saveexec_b64 s[30:31], s[40:41]
	s_cbranch_execz .LBB0_770
	v_add_f32_e32 v86, v84, v85
	v_lshlrev_b64 v[84:85], 6, v[158:159]
	v_lshl_add_u64 v[84:85], s[28:29], 0, v[84:85]
	global_store_dword v[84:85], v86, off

; __device__ __forceinline__ unsigned pkh(float lo, float hi) { if (!RES_FP16) return cvt_pk_bf16(lo, hi); f16x2 v = {(_Float16)lo, (_Float16)hi}; return __builtin_bit_cast(unsigned, v); }
;     __device__ __forceinline__ void operator()(const f32x4 (&acc)[2][2][4][2], const Unit& u, int wr, int wc, int fr, int fq) const {
;     ...
;             for (int gg = 0; gg < 2; ++gg) {
;                 const int g = 2 * b + gg, ai = g >> 2, m = g & 3;
;                 const int row0 = u.pm * BM + ai * HALF + wr * 64 + m * 16 + rl;
;                 float sq[2] = {0.f, 0.f};
; #pragma unroll
;                 for (int bj = 0; bj < 2; ++bj) {
;                     *(f32x4*)(wl + fr * 36 + fq * 4) = acc[ai][bj][m][0] * alpha; *(f32x4*)(wl + fr * 36 + 16 + fq * 4) = acc[ai][bj][m][1] * alpha;
;                     asm volatile("s_waitcnt lgkmcnt(0)" ::: "memory");
; #pragma unroll
;                     for (int i = 0; i < 2; ++i) {
;                         const f32x4 x = rb[b & 1][gg][bj][i] + *(const f32x4*)(wl + (rl + 8 * i) * 36 + ch * 4);
;                         const size_t off = (size_t)(row0 + 8 * i) * 1024 + cbase + bj * HALF;
;                         u32x2 w; w.x = pkh(x[0], x[1]); w.y = pkh(x[2], x[3]); *(u32x2*)(X16 + off) = w;
;                         sq[i] += (x[0] * x[0] + x[1] * x[1]) + (x[2] * x[2] + x[3] * x[3]);
;                     }
;                     asm volatile("s_waitcnt lgkmcnt(0)" ::: "memory");
;                 }
; #pragma unroll
;                 for (int i = 0; i < 2; ++i) { float t = sq[i]; t += dpp_f(t, 0); t += dpp_f(t, 1); t += dpp_f(t, 2);
;                     if (ch == 0) ss[(size_t)(row0 + 8 * i) * 16 + u.pn * 4 + wc] = t; }
.LBB0_772:
	s_or_b64 exec, exec, s[30:31]
	v_mov_b32_e32 v131, v130
	v_pk_mul_f32 v[78:79], v[78:79], v[130:131]
	v_pk_mul_f32 v[76:77], v[76:77], v[134:135]
	v_pk_mul_f32 v[74:75], v[74:75], v[130:131]
	v_pk_mul_f32 v[72:73], v[72:73], v[134:135]
	ds_write_b128 v197, v[76:79]
	ds_write_b128 v197, v[72:75] offset:64
	ds_read_b128 v[72:75], v198
	v_lshlrev_b32_e32 v80, 16, v164
	v_and_b32_e32 v81, 0xffff0000, v164
	v_lshlrev_b32_e32 v82, 16, v165
	v_and_b32_e32 v83, 0xffff0000, v165
	s_waitcnt lgkmcnt(0)
	v_pk_add_f32 v[82:83], v[74:75], v[82:83]
	v_pk_add_f32 v[80:81], v[72:73], v[80:81]
	v_lshlrev_b32_e32 v84, 16, v162
	v_cvt_pk_bf16_f32 v72, v80, v81
	v_cvt_pk_bf16_f32 v73, v82, v83
	ds_read_b128 v[74:77], v198 offset:1152
	v_and_b32_e32 v85, 0xffff0000, v162
	v_lshl_add_u64 v[94:95], s[74:75], 0, v[152:153]
	v_lshlrev_b32_e32 v86, 16, v163
	v_and_b32_e32 v87, 0xffff0000, v163
	s_waitcnt lgkmcnt(0)
	v_pk_add_f32 v[74:75], v[74:75], v[84:85]
	v_lshl_add_u64 v[84:85], s[74:75], 0, v[150:151]
	v_lshl_add_u64 v[94:95], v[94:95], 0, v[140:141]
	v_lshl_add_u64 v[84:85], v[84:85], 0, v[140:141]
	global_store_dwordx2 v[94:95], v[72:73], off
	v_pk_add_f32 v[72:73], v[76:77], v[86:87]
	v_cvt_pk_bf16_f32 v76, v74, v75
	v_pk_mul_f32 v[70:71], v[70:71], v[130:131]
	v_cvt_pk_bf16_f32 v77, v72, v73
	global_store_dwordx2 v[84:85], v[76:77], off
	v_pk_mul_f32 v[68:69], v[68:69], v[134:135]
	v_pk_mul_f32 v[66:67], v[66:67], v[130:131]
	v_pk_mul_f32 v[64:65], v[64:65], v[134:135]
	s_waitcnt lgkmcnt(0)
	ds_write_b128 v197, v[68:71]
	ds_write_b128 v197, v[64:67] offset:64
	ds_read_b128 v[64:67], v198
	v_lshlrev_b32_e32 v88, 16, v160
	v_and_b32_e32 v89, 0xffff0000, v160
	v_lshlrev_b32_e32 v90, 16, v161
	v_and_b32_e32 v91, 0xffff0000, v161
	v_mul_f32_e32 v81, v81, v81
	v_mul_f32_e32 v68, v83, v83
	v_fmac_f32_e32 v81, v80, v80
	v_fmac_f32_e32 v68, v82, v82
	s_waitcnt lgkmcnt(0)
	v_pk_add_f32 v[70:71], v[66:67], v[90:91]
	v_pk_add_f32 v[64:65], v[64:65], v[88:89]
	v_add_f32_e32 v76, v81, v68
	v_cvt_pk_bf16_f32 v66, v64, v65
	v_cvt_pk_bf16_f32 v67, v70, v71
	global_store_dwordx2 v[94:95], v[66:67], off offset:256
	ds_read_b128 v[66:69], v198 offset:1152
	v_mul_f32_e32 v65, v65, v65
	v_fmac_f32_e32 v65, v64, v64
	v_mul_f32_e32 v64, v71, v71
	v_fmac_f32_e32 v64, v70, v70
	v_lshlrev_b32_e32 v78, 16, v154
	v_and_b32_e32 v79, 0xffff0000, v154
	v_lshlrev_b32_e32 v92, 16, v155
	v_and_b32_e32 v93, 0xffff0000, v155
	v_add_f32_e32 v64, v65, v64
	v_add_f32_e32 v70, v76, v64
	s_waitcnt lgkmcnt(0)
	v_pk_add_f32 v[64:65], v[68:69], v[92:93]
	v_pk_add_f32 v[66:67], v[66:67], v[78:79]
	s_nop 0
	v_cvt_pk_bf16_f32 v68, v66, v67
	v_cvt_pk_bf16_f32 v69, v64, v65
	global_store_dwordx2 v[84:85], v[68:69], off offset:256
	s_waitcnt lgkmcnt(0)
	s_nop 0
	v_add_f32_dpp v68, v70, v70 quad_perm:[1,0,3,2] row_mask:0xf bank_mask:0xf bound_ctrl:1
	s_nop 1
	v_add_f32_dpp v68, v68, v68 quad_perm:[2,3,0,1] row_mask:0xf bank_mask:0xf bound_ctrl:1
	s_nop 1
	v_mov_b32_dpp v69, v68 row_shl:4 row_mask:0xf bank_mask:0xf bound_ctrl:1
	s_and_saveexec_b64 s[30:31], s[40:41]
	s_cbranch_execz .LBB0_774
	v_add_f32_e32 v70, v68, v69
	v_lshlrev_b64 v[68:69], 6, v[148:149]
	v_lshl_add_u64 v[68:69], s[28:29], 0, v[68:69]
	global_store_dword v[68:69], v70, off

; __device__ __forceinline__ unsigned pkh(float lo, float hi) { if (!RES_FP16) return cvt_pk_bf16(lo, hi); f16x2 v = {(_Float16)lo, (_Float16)hi}; return __builtin_bit_cast(unsigned, v); }
;     __device__ __forceinline__ void operator()(const f32x4 (&acc)[2][2][4][2], const Unit& u, int wr, int wc, int fr, int fq) const {
;     ...
;         RES_LOAD(0, 0);
; #pragma unroll
;         for (int b = 0; b < 4; ++b) {
;             if (b + 1 < 4) RES_LOAD((b + 1) & 1, b + 1);
; #pragma unroll
;             for (int gg = 0; gg < 2; ++gg) {
;                 const int g = 2 * b + gg, ai = g >> 2, m = g & 3;
;                 const int row0 = u.pm * BM + ai * HALF + wr * 64 + m * 16 + rl;
;                 float sq[2] = {0.f, 0.f};
; #pragma unroll
;                 for (int bj = 0; bj < 2; ++bj) {
;                     *(f32x4*)(wl + fr * 36 + fq * 4) = acc[ai][bj][m][0] * alpha; *(f32x4*)(wl + fr * 36 + 16 + fq * 4) = acc[ai][bj][m][1] * alpha;
;                     asm volatile("s_waitcnt lgkmcnt(0)" ::: "memory");
; #pragma unroll
;                     for (int i = 0; i < 2; ++i) {
;                         const f32x4 x = rb[b & 1][gg][bj][i] + *(const f32x4*)(wl + (rl + 8 * i) * 36 + ch * 4);
;                         const size_t off = (size_t)(row0 + 8 * i) * 1024 + cbase + bj * HALF;
;                         u32x2 w; w.x = pkh(x[0], x[1]); w.y = pkh(x[2], x[3]); *(u32x2*)(X16 + off) = w;
;                         sq[i] += (x[0] * x[0] + x[1] * x[1]) + (x[2] * x[2] + x[3] * x[3]);
;                     }
;                     asm volatile("s_waitcnt lgkmcnt(0)" ::: "memory");
;                 }
; #pragma unroll
;                 for (int i = 0; i < 2; ++i) { float t = sq[i]; t += dpp_f(t, 0); t += dpp_f(t, 1); t += dpp_f(t, 2);
;                     if (ch == 0) ss[(size_t)(row0 + 8 * i) * 16 + u.pn * 4 + wc] = t; }
.LBB0_776:
	s_or_b64 exec, exec, s[30:31]
	v_add_u32_e32 v80, 0xa0, v144
	v_add_u32_e32 v72, 0xa8, v144
	v_ashrrev_i32_e32 v81, 31, v80
	v_ashrrev_i32_e32 v73, 31, v72
	v_lshlrev_b64 v[82:83], 11, v[80:81]
	v_lshlrev_b64 v[66:67], 11, v[72:73]
	v_lshl_add_u64 v[64:65], v[142:143], 0, v[82:83]
	v_lshl_add_u64 v[66:67], v[142:143], 0, v[66:67]
	global_load_dwordx2 v[90:91], v[64:65], off
	global_load_dwordx2 v[88:89], v[66:67], off
	global_load_dwordx2 v[84:85], v[66:67], off offset:256
	global_load_dwordx2 v[86:87], v[64:65], off offset:256
	v_add_u32_e32 v66, 0xb0, v144
	v_add_u32_e32 v64, 0xb8, v144
	v_ashrrev_i32_e32 v67, 31, v66
	v_ashrrev_i32_e32 v65, 31, v64
	v_lshlrev_b64 v[68:69], 11, v[66:67]
	v_lshlrev_b64 v[70:71], 11, v[64:65]
	v_lshl_add_u64 v[74:75], v[142:143], 0, v[68:69]
	v_lshl_add_u64 v[70:71], v[142:143], 0, v[70:71]
	global_load_dwordx2 v[78:79], v[74:75], off
	global_load_dwordx2 v[76:77], v[70:71], off
	s_nop 0
	global_load_dwordx2 v[70:71], v[70:71], off offset:256
	s_nop 0
	global_load_dwordx2 v[74:75], v[74:75], off offset:256
	v_mov_b32_e32 v131, v130
	v_pk_mul_f32 v[62:63], v[62:63], v[130:131]
	v_pk_mul_f32 v[60:61], v[60:61], v[134:135]
	v_pk_mul_f32 v[58:59], v[58:59], v[130:131]
	v_pk_mul_f32 v[56:57], v[56:57], v[134:135]
	ds_write_b128 v197, v[60:63]
	ds_write_b128 v197, v[56:59] offset:64
	ds_read_b128 v[56:59], v198
	s_waitcnt vmcnt(23)
	v_lshlrev_b32_e32 v92, 16, v122
	v_and_b32_e32 v93, 0xffff0000, v122
	v_lshlrev_b32_e32 v94, 16, v123
	v_and_b32_e32 v95, 0xffff0000, v123
	s_waitcnt lgkmcnt(0)
	v_pk_add_f32 v[94:95], v[58:59], v[94:95]
	v_pk_add_f32 v[92:93], v[56:57], v[92:93]
	v_lshl_add_u64 v[114:115], s[74:75], 0, v[114:115]
	v_cvt_pk_bf16_f32 v56, v92, v93
	v_cvt_pk_bf16_f32 v57, v94, v95
	ds_read_b128 v[58:61], v198 offset:1152
	s_waitcnt vmcnt(22)
	v_lshlrev_b32_e32 v122, 16, v120
	v_and_b32_e32 v123, 0xffff0000, v120
	v_lshlrev_b32_e32 v120, 16, v121
	v_and_b32_e32 v121, 0xffff0000, v121
	v_lshl_add_u64 v[114:115], v[114:115], 0, v[140:141]
	global_store_dwordx2 v[114:115], v[56:57], off
	s_waitcnt lgkmcnt(0)
	v_pk_add_f32 v[56:57], v[60:61], v[120:121]
	v_or_b32_e32 v60, 8, v112
	v_ashrrev_i32_e32 v61, 31, v60
	v_lshlrev_b64 v[60:61], 11, v[60:61]
	v_lshl_add_u64 v[60:61], s[74:75], 0, v[60:61]
	v_lshl_add_u64 v[60:61], v[60:61], 0, v[140:141]
	v_pk_add_f32 v[58:59], v[58:59], v[122:123]
	v_pk_mul_f32 v[54:55], v[54:55], v[130:131]
	v_cvt_pk_bf16_f32 v120, v58, v59
	v_cvt_pk_bf16_f32 v121, v56, v57
	global_store_dwordx2 v[60:61], v[120:121], off
	v_pk_mul_f32 v[52:53], v[52:53], v[134:135]
	v_pk_mul_f32 v[50:51], v[50:51], v[130:131]
	v_pk_mul_f32 v[48:49], v[48:49], v[134:135]
	s_waitcnt lgkmcnt(0)
	ds_write_b128 v197, v[52:55]
	ds_write_b128 v197, v[48:51] offset:64
	ds_read_b128 v[48:51], v198
	s_waitcnt vmcnt(22)
	v_lshlrev_b32_e32 v124, 16, v118
	v_and_b32_e32 v125, 0xffff0000, v118
	v_lshlrev_b32_e32 v118, 16, v119
	v_and_b32_e32 v119, 0xffff0000, v119
	v_mul_f32_e32 v93, v93, v93
	v_mul_f32_e32 v52, v95, v95
	v_fmac_f32_e32 v93, v92, v92
	v_fmac_f32_e32 v52, v94, v94
	s_waitcnt lgkmcnt(0)
	v_pk_add_f32 v[54:55], v[50:51], v[118:119]
	v_pk_add_f32 v[48:49], v[48:49], v[124:125]
	v_add_f32_e32 v92, v93, v52
	v_cvt_pk_bf16_f32 v50, v48, v49
	v_cvt_pk_bf16_f32 v51, v54, v55
	global_store_dwordx2 v[114:115], v[50:51], off offset:256
	ds_read_b128 v[50:53], v198 offset:1152
	v_mul_f32_e32 v49, v49, v49
	v_fmac_f32_e32 v49, v48, v48
	v_mul_f32_e32 v48, v55, v55
	v_fmac_f32_e32 v48, v54, v54
	v_lshlrev_b32_e32 v62, 16, v116
	v_and_b32_e32 v63, 0xffff0000, v116
	v_lshlrev_b32_e32 v116, 16, v117
	v_and_b32_e32 v117, 0xffff0000, v117
	v_add_f32_e32 v48, v49, v48
	v_add_f32_e32 v54, v92, v48
	s_waitcnt lgkmcnt(0)
	v_pk_add_f32 v[48:49], v[52:53], v[116:117]
	v_pk_add_f32 v[50:51], v[50:51], v[62:63]
	s_nop 0
	v_cvt_pk_bf16_f32 v52, v50, v51
	v_cvt_pk_bf16_f32 v53, v48, v49
	global_store_dwordx2 v[60:61], v[52:53], off offset:256
	s_waitcnt lgkmcnt(0)
	s_nop 0
	v_add_f32_dpp v52, v54, v54 quad_perm:[1,0,3,2] row_mask:0xf bank_mask:0xf bound_ctrl:1
	s_nop 1
	v_add_f32_dpp v52, v52, v52 quad_perm:[2,3,0,1] row_mask:0xf bank_mask:0xf bound_ctrl:1
	s_nop 1
	v_mov_b32_dpp v53, v52 row_shl:4 row_mask:0xf bank_mask:0xf bound_ctrl:1
	s_and_saveexec_b64 s[30:31], s[40:41]
	s_cbranch_execz .LBB0_778
	v_add_f32_e32 v54, v52, v53
	v_lshlrev_b64 v[52:53], 6, v[112:113]
	v_lshl_add_u64 v[52:53], s[28:29], 0, v[52:53]
	global_store_dword v[52:53], v54, off

; __device__ __forceinline__ unsigned pkh(float lo, float hi) { if (!RES_FP16) return cvt_pk_bf16(lo, hi); f16x2 v = {(_Float16)lo, (_Float16)hi}; return __builtin_bit_cast(unsigned, v); }
;     __device__ __forceinline__ void operator()(const f32x4 (&acc)[2][2][4][2], const Unit& u, int wr, int wc, int fr, int fq) const {
;     ...
;             for (int gg = 0; gg < 2; ++gg) {
;                 const int g = 2 * b + gg, ai = g >> 2, m = g & 3;
;                 const int row0 = u.pm * BM + ai * HALF + wr * 64 + m * 16 + rl;
;                 float sq[2] = {0.f, 0.f};
; #pragma unroll
;                 for (int bj = 0; bj < 2; ++bj) {
;                     *(f32x4*)(wl + fr * 36 + fq * 4) = acc[ai][bj][m][0] * alpha; *(f32x4*)(wl + fr * 36 + 16 + fq * 4) = acc[ai][bj][m][1] * alpha;
;                     asm volatile("s_waitcnt lgkmcnt(0)" ::: "memory");
; #pragma unroll
;                     for (int i = 0; i < 2; ++i) {
;                         const f32x4 x = rb[b & 1][gg][bj][i] + *(const f32x4*)(wl + (rl + 8 * i) * 36 + ch * 4);
;                         const size_t off = (size_t)(row0 + 8 * i) * 1024 + cbase + bj * HALF;
;                         u32x2 w; w.x = pkh(x[0], x[1]); w.y = pkh(x[2], x[3]); *(u32x2*)(X16 + off) = w;
;                         sq[i] += (x[0] * x[0] + x[1] * x[1]) + (x[2] * x[2] + x[3] * x[3]);
;                     }
;                     asm volatile("s_waitcnt lgkmcnt(0)" ::: "memory");
;                 }
; #pragma unroll
;                 for (int i = 0; i < 2; ++i) { float t = sq[i]; t += dpp_f(t, 0); t += dpp_f(t, 1); t += dpp_f(t, 2);
;                     if (ch == 0) ss[(size_t)(row0 + 8 * i) * 16 + u.pn * 4 + wc] = t; }
.LBB0_780:
	s_or_b64 exec, exec, s[30:31]
	v_mov_b32_e32 v131, v130
	v_pk_mul_f32 v[46:47], v[46:47], v[130:131]
	v_pk_mul_f32 v[44:45], v[44:45], v[134:135]
	v_pk_mul_f32 v[42:43], v[42:43], v[130:131]
	v_pk_mul_f32 v[40:41], v[40:41], v[134:135]
	ds_write_b128 v197, v[44:47]
	ds_write_b128 v197, v[40:43] offset:64
	ds_read_b128 v[40:43], v198
	s_waitcnt vmcnt(23)
	v_lshlrev_b32_e32 v48, 16, v110
	v_and_b32_e32 v49, 0xffff0000, v110
	v_lshlrev_b32_e32 v50, 16, v111
	v_and_b32_e32 v51, 0xffff0000, v111
	s_waitcnt lgkmcnt(0)
	v_pk_add_f32 v[50:51], v[42:43], v[50:51]
	v_pk_add_f32 v[48:49], v[40:41], v[48:49]
	v_lshl_add_u64 v[62:63], s[74:75], 0, v[100:101]
	v_cvt_pk_bf16_f32 v40, v48, v49
	v_cvt_pk_bf16_f32 v41, v50, v51
	ds_read_b128 v[42:45], v198 offset:1152
	s_waitcnt vmcnt(22)
	v_lshlrev_b32_e32 v54, 16, v109
	v_and_b32_e32 v55, 0xffff0000, v109
	v_lshl_add_u64 v[62:63], v[62:63], 0, v[140:141]
	global_store_dwordx2 v[62:63], v[40:41], off
	s_waitcnt lgkmcnt(0)
	v_pk_add_f32 v[40:41], v[44:45], v[54:55]
	v_or_b32_e32 v44, 8, v98
	v_ashrrev_i32_e32 v45, 31, v44
	v_lshlrev_b64 v[44:45], 11, v[44:45]
	v_lshl_add_u64 v[44:45], s[74:75], 0, v[44:45]
	v_lshlrev_b32_e32 v52, 16, v108
	v_and_b32_e32 v53, 0xffff0000, v108
	v_lshl_add_u64 v[44:45], v[44:45], 0, v[140:141]
	v_pk_add_f32 v[42:43], v[42:43], v[52:53]
	v_pk_mul_f32 v[38:39], v[38:39], v[130:131]
	v_cvt_pk_bf16_f32 v52, v42, v43
	v_cvt_pk_bf16_f32 v53, v40, v41
	global_store_dwordx2 v[44:45], v[52:53], off
	v_pk_mul_f32 v[36:37], v[36:37], v[134:135]
	v_pk_mul_f32 v[34:35], v[34:35], v[130:131]
	v_pk_mul_f32 v[32:33], v[32:33], v[134:135]
	s_waitcnt lgkmcnt(0)
	ds_write_b128 v197, v[36:39]
	ds_write_b128 v197, v[32:35] offset:64
	ds_read_b128 v[32:35], v198
	s_waitcnt vmcnt(22)
	v_lshlrev_b32_e32 v56, 16, v106
	v_and_b32_e32 v57, 0xffff0000, v106
	v_lshlrev_b32_e32 v58, 16, v107
	v_and_b32_e32 v59, 0xffff0000, v107
	v_mul_f32_e32 v49, v49, v49
	v_mul_f32_e32 v36, v51, v51
	v_fmac_f32_e32 v49, v48, v48
	v_fmac_f32_e32 v36, v50, v50
	s_waitcnt lgkmcnt(0)
	v_pk_add_f32 v[38:39], v[34:35], v[58:59]
	v_pk_add_f32 v[32:33], v[32:33], v[56:57]
	v_add_f32_e32 v48, v49, v36
	v_cvt_pk_bf16_f32 v34, v32, v33
	v_cvt_pk_bf16_f32 v35, v38, v39
	global_store_dwordx2 v[62:63], v[34:35], off offset:256
	ds_read_b128 v[34:37], v198 offset:1152
	v_mul_f32_e32 v33, v33, v33
	v_fmac_f32_e32 v33, v32, v32
	v_mul_f32_e32 v32, v39, v39
	v_fmac_f32_e32 v32, v38, v38
	v_lshlrev_b32_e32 v46, 16, v102
	v_and_b32_e32 v47, 0xffff0000, v102
	v_lshlrev_b32_e32 v60, 16, v103
	v_and_b32_e32 v61, 0xffff0000, v103
	v_add_f32_e32 v32, v33, v32
	v_add_f32_e32 v38, v48, v32
	s_waitcnt lgkmcnt(0)
	v_pk_add_f32 v[32:33], v[36:37], v[60:61]
	v_pk_add_f32 v[34:35], v[34:35], v[46:47]
	s_nop 0
	v_cvt_pk_bf16_f32 v36, v34, v35
	v_cvt_pk_bf16_f32 v37, v32, v33
	global_store_dwordx2 v[44:45], v[36:37], off offset:256
	s_waitcnt lgkmcnt(0)
	s_nop 0
	v_add_f32_dpp v36, v38, v38 quad_perm:[1,0,3,2] row_mask:0xf bank_mask:0xf bound_ctrl:1
	s_nop 1
	v_add_f32_dpp v36, v36, v36 quad_perm:[2,3,0,1] row_mask:0xf bank_mask:0xf bound_ctrl:1
	s_nop 1
	v_mov_b32_dpp v37, v36 row_shl:4 row_mask:0xf bank_mask:0xf bound_ctrl:1
	s_and_saveexec_b64 s[30:31], s[40:41]
	s_cbranch_execz .LBB0_782
	v_add_f32_e32 v38, v36, v37
	v_lshlrev_b64 v[36:37], 6, v[98:99]
	v_lshl_add_u64 v[36:37], s[28:29], 0, v[36:37]
	global_store_dword v[36:37], v38, off

; __device__ __forceinline__ unsigned pkh(float lo, float hi) { if (!RES_FP16) return cvt_pk_bf16(lo, hi); f16x2 v = {(_Float16)lo, (_Float16)hi}; return __builtin_bit_cast(unsigned, v); }
;     __device__ __forceinline__ void operator()(const f32x4 (&acc)[2][2][4][2], const Unit& u, int wr, int wc, int fr, int fq) const {
;     ...
;             for (int gg = 0; gg < 2; ++gg) {
;                 const int g = 2 * b + gg, ai = g >> 2, m = g & 3;
;                 const int row0 = u.pm * BM + ai * HALF + wr * 64 + m * 16 + rl;
;                 float sq[2] = {0.f, 0.f};
; #pragma unroll
;                 for (int bj = 0; bj < 2; ++bj) {
;                     *(f32x4*)(wl + fr * 36 + fq * 4) = acc[ai][bj][m][0] * alpha; *(f32x4*)(wl + fr * 36 + 16 + fq * 4) = acc[ai][bj][m][1] * alpha;
;                     asm volatile("s_waitcnt lgkmcnt(0)" ::: "memory");
; #pragma unroll
;                     for (int i = 0; i < 2; ++i) {
;                         const f32x4 x = rb[b & 1][gg][bj][i] + *(const f32x4*)(wl + (rl + 8 * i) * 36 + ch * 4);
;                         const size_t off = (size_t)(row0 + 8 * i) * 1024 + cbase + bj * HALF;
;                         u32x2 w; w.x = pkh(x[0], x[1]); w.y = pkh(x[2], x[3]); *(u32x2*)(X16 + off) = w;
;                         sq[i] += (x[0] * x[0] + x[1] * x[1]) + (x[2] * x[2] + x[3] * x[3]);
;                     }
;                     asm volatile("s_waitcnt lgkmcnt(0)" ::: "memory");
;                 }
; #pragma unroll
;                 for (int i = 0; i < 2; ++i) { float t = sq[i]; t += dpp_f(t, 0); t += dpp_f(t, 1); t += dpp_f(t, 2);
;                     if (ch == 0) ss[(size_t)(row0 + 8 * i) * 16 + u.pn * 4 + wc] = t; }
.LBB0_784:
	s_or_b64 exec, exec, s[30:31]
	v_mov_b32_e32 v131, v130
	v_pk_mul_f32 v[30:31], v[30:31], v[130:131]
	v_pk_mul_f32 v[28:29], v[28:29], v[134:135]
	v_pk_mul_f32 v[26:27], v[26:27], v[130:131]
	v_pk_mul_f32 v[24:25], v[24:25], v[134:135]
	ds_write_b128 v197, v[28:31]
	ds_write_b128 v197, v[24:27] offset:64
	ds_read_b128 v[24:27], v198
	s_waitcnt vmcnt(15)
	v_lshlrev_b32_e32 v32, 16, v90
	v_and_b32_e32 v33, 0xffff0000, v90
	v_lshlrev_b32_e32 v34, 16, v91
	v_and_b32_e32 v35, 0xffff0000, v91
	s_waitcnt lgkmcnt(0)
	v_pk_add_f32 v[34:35], v[26:27], v[34:35]
	v_pk_add_f32 v[32:33], v[24:25], v[32:33]
	v_lshl_add_u64 v[46:47], s[74:75], 0, v[82:83]
	v_cvt_pk_bf16_f32 v24, v32, v33
	v_cvt_pk_bf16_f32 v25, v34, v35
	ds_read_b128 v[26:29], v198 offset:1152
	s_waitcnt vmcnt(14)
	v_lshlrev_b32_e32 v38, 16, v89
	v_and_b32_e32 v39, 0xffff0000, v89
	v_lshl_add_u64 v[46:47], v[46:47], 0, v[140:141]
	global_store_dwordx2 v[46:47], v[24:25], off
	s_waitcnt lgkmcnt(0)
	v_pk_add_f32 v[24:25], v[28:29], v[38:39]
	v_or_b32_e32 v28, 8, v80
	v_ashrrev_i32_e32 v29, 31, v28
	v_lshlrev_b64 v[28:29], 11, v[28:29]
	v_lshl_add_u64 v[28:29], s[74:75], 0, v[28:29]
	v_lshlrev_b32_e32 v36, 16, v88
	v_and_b32_e32 v37, 0xffff0000, v88
	v_lshl_add_u64 v[28:29], v[28:29], 0, v[140:141]
	v_pk_add_f32 v[26:27], v[26:27], v[36:37]
	v_pk_mul_f32 v[22:23], v[22:23], v[130:131]
	v_cvt_pk_bf16_f32 v36, v26, v27
	v_cvt_pk_bf16_f32 v37, v24, v25
	global_store_dwordx2 v[28:29], v[36:37], off
	v_pk_mul_f32 v[20:21], v[20:21], v[134:135]
	v_pk_mul_f32 v[18:19], v[18:19], v[130:131]
	v_pk_mul_f32 v[16:17], v[16:17], v[134:135]
	s_waitcnt lgkmcnt(0)
	ds_write_b128 v197, v[20:23]
	ds_write_b128 v197, v[16:19] offset:64
	ds_read_b128 v[16:19], v198
	s_waitcnt vmcnt(14)
	v_lshlrev_b32_e32 v40, 16, v86
	v_and_b32_e32 v41, 0xffff0000, v86
	v_lshlrev_b32_e32 v42, 16, v87
	v_and_b32_e32 v43, 0xffff0000, v87
	v_mul_f32_e32 v33, v33, v33
	v_mul_f32_e32 v20, v35, v35
	v_fmac_f32_e32 v33, v32, v32
	v_fmac_f32_e32 v20, v34, v34
	s_waitcnt lgkmcnt(0)
	v_pk_add_f32 v[22:23], v[18:19], v[42:43]
	v_pk_add_f32 v[16:17], v[16:17], v[40:41]
	v_add_f32_e32 v32, v33, v20
	v_cvt_pk_bf16_f32 v18, v16, v17
	v_cvt_pk_bf16_f32 v19, v22, v23
	global_store_dwordx2 v[46:47], v[18:19], off offset:256
	ds_read_b128 v[18:21], v198 offset:1152
	v_mul_f32_e32 v17, v17, v17
	v_fmac_f32_e32 v17, v16, v16
	v_mul_f32_e32 v16, v23, v23
	v_fmac_f32_e32 v16, v22, v22
	v_lshlrev_b32_e32 v30, 16, v84
	v_and_b32_e32 v31, 0xffff0000, v84
	v_lshlrev_b32_e32 v44, 16, v85
	v_and_b32_e32 v45, 0xffff0000, v85
	v_add_f32_e32 v16, v17, v16
	v_add_f32_e32 v22, v32, v16
	s_waitcnt lgkmcnt(0)
	v_pk_add_f32 v[16:17], v[20:21], v[44:45]
	v_pk_add_f32 v[18:19], v[18:19], v[30:31]
	s_nop 0
	v_cvt_pk_bf16_f32 v20, v18, v19
	v_cvt_pk_bf16_f32 v21, v16, v17
	global_store_dwordx2 v[28:29], v[20:21], off offset:256
	s_waitcnt lgkmcnt(0)
	s_nop 0
	v_add_f32_dpp v20, v22, v22 quad_perm:[1,0,3,2] row_mask:0xf bank_mask:0xf bound_ctrl:1
	s_nop 1
	v_add_f32_dpp v20, v20, v20 quad_perm:[2,3,0,1] row_mask:0xf bank_mask:0xf bound_ctrl:1
	s_nop 1
	v_mov_b32_dpp v21, v20 row_shl:4 row_mask:0xf bank_mask:0xf bound_ctrl:1
	s_and_saveexec_b64 s[30:31], s[40:41]
	s_cbranch_execz .LBB0_786
	v_add_f32_e32 v22, v20, v21
	v_lshlrev_b64 v[20:21], 6, v[80:81]
	v_lshl_add_u64 v[20:21], s[28:29], 0, v[20:21]
	global_store_dword v[20:21], v22, off

; __device__ __forceinline__ unsigned pkh(float lo, float hi) { if (!RES_FP16) return cvt_pk_bf16(lo, hi); f16x2 v = {(_Float16)lo, (_Float16)hi}; return __builtin_bit_cast(unsigned, v); }
;     __device__ __forceinline__ void operator()(const f32x4 (&acc)[2][2][4][2], const Unit& u, int wr, int wc, int fr, int fq) const {
;     ...
;             for (int gg = 0; gg < 2; ++gg) {
;                 const int g = 2 * b + gg, ai = g >> 2, m = g & 3;
;                 const int row0 = u.pm * BM + ai * HALF + wr * 64 + m * 16 + rl;
;                 float sq[2] = {0.f, 0.f};
; #pragma unroll
;                 for (int bj = 0; bj < 2; ++bj) {
;                     *(f32x4*)(wl + fr * 36 + fq * 4) = acc[ai][bj][m][0] * alpha; *(f32x4*)(wl + fr * 36 + 16 + fq * 4) = acc[ai][bj][m][1] * alpha;
;                     asm volatile("s_waitcnt lgkmcnt(0)" ::: "memory");
; #pragma unroll
;                     for (int i = 0; i < 2; ++i) {
;                         const f32x4 x = rb[b & 1][gg][bj][i] + *(const f32x4*)(wl + (rl + 8 * i) * 36 + ch * 4);
;                         const size_t off = (size_t)(row0 + 8 * i) * 1024 + cbase + bj * HALF;
;                         u32x2 w; w.x = pkh(x[0], x[1]); w.y = pkh(x[2], x[3]); *(u32x2*)(X16 + off) = w;
;                         sq[i] += (x[0] * x[0] + x[1] * x[1]) + (x[2] * x[2] + x[3] * x[3]);
;                     }
;                     asm volatile("s_waitcnt lgkmcnt(0)" ::: "memory");
;                 }
; #pragma unroll
;                 for (int i = 0; i < 2; ++i) { float t = sq[i]; t += dpp_f(t, 0); t += dpp_f(t, 1); t += dpp_f(t, 2);
;                     if (ch == 0) ss[(size_t)(row0 + 8 * i) * 16 + u.pn * 4 + wc] = t; }
.LBB0_788:
	s_or_b64 exec, exec, s[30:31]
	v_mov_b32_e32 v131, v130
	v_pk_mul_f32 v[14:15], v[14:15], v[130:131]
	v_pk_mul_f32 v[12:13], v[12:13], v[134:135]
	v_pk_mul_f32 v[10:11], v[10:11], v[130:131]
	v_pk_mul_f32 v[8:9], v[8:9], v[134:135]
	ds_write_b128 v197, v[12:15]
	ds_write_b128 v197, v[8:11] offset:64
	ds_read_b128 v[8:11], v198
	s_waitcnt vmcnt(15)
	v_lshlrev_b32_e32 v16, 16, v78
	v_and_b32_e32 v17, 0xffff0000, v78
	v_lshlrev_b32_e32 v18, 16, v79
	v_and_b32_e32 v19, 0xffff0000, v79
	s_waitcnt lgkmcnt(0)
	v_pk_add_f32 v[18:19], v[10:11], v[18:19]
	v_pk_add_f32 v[16:17], v[8:9], v[16:17]
	v_lshl_add_u64 v[30:31], s[74:75], 0, v[68:69]
	v_cvt_pk_bf16_f32 v8, v16, v17
	v_cvt_pk_bf16_f32 v9, v18, v19
	ds_read_b128 v[10:13], v198 offset:1152
	s_waitcnt vmcnt(14)
	v_lshlrev_b32_e32 v22, 16, v77
	v_and_b32_e32 v23, 0xffff0000, v77
	v_lshl_add_u64 v[30:31], v[30:31], 0, v[140:141]
	global_store_dwordx2 v[30:31], v[8:9], off
	s_waitcnt lgkmcnt(0)
	v_pk_add_f32 v[8:9], v[12:13], v[22:23]
	v_or_b32_e32 v12, 8, v66
	v_ashrrev_i32_e32 v13, 31, v12
	v_lshlrev_b64 v[12:13], 11, v[12:13]
	v_lshl_add_u64 v[12:13], s[74:75], 0, v[12:13]
	v_lshlrev_b32_e32 v20, 16, v76
	v_and_b32_e32 v21, 0xffff0000, v76
	v_lshl_add_u64 v[12:13], v[12:13], 0, v[140:141]
	v_pk_add_f32 v[10:11], v[10:11], v[20:21]
	v_pk_mul_f32 v[6:7], v[6:7], v[130:131]
	v_cvt_pk_bf16_f32 v20, v10, v11
	v_cvt_pk_bf16_f32 v21, v8, v9
	global_store_dwordx2 v[12:13], v[20:21], off
	v_pk_mul_f32 v[4:5], v[4:5], v[134:135]
	v_pk_mul_f32 v[2:3], v[2:3], v[130:131]
	v_pk_mul_f32 v[0:1], v[0:1], v[134:135]
	s_waitcnt lgkmcnt(0)
	ds_write_b128 v197, v[4:7]
	ds_write_b128 v197, v[0:3] offset:64
	ds_read_b128 v[0:3], v198
	s_waitcnt vmcnt(14)
	v_lshlrev_b32_e32 v24, 16, v74
	v_and_b32_e32 v25, 0xffff0000, v74
	v_lshlrev_b32_e32 v26, 16, v75
	v_and_b32_e32 v27, 0xffff0000, v75
	v_mul_f32_e32 v17, v17, v17
	v_mul_f32_e32 v4, v19, v19
	v_fmac_f32_e32 v17, v16, v16
	v_fmac_f32_e32 v4, v18, v18
	s_waitcnt lgkmcnt(0)
	v_pk_add_f32 v[6:7], v[2:3], v[26:27]
	v_pk_add_f32 v[0:1], v[0:1], v[24:25]
	v_add_f32_e32 v16, v17, v4
	v_cvt_pk_bf16_f32 v2, v0, v1
	v_cvt_pk_bf16_f32 v3, v6, v7
	global_store_dwordx2 v[30:31], v[2:3], off offset:256
	ds_read_b128 v[2:5], v198 offset:1152
	v_mul_f32_e32 v1, v1, v1
	v_fmac_f32_e32 v1, v0, v0
	v_mul_f32_e32 v0, v7, v7
	v_fmac_f32_e32 v0, v6, v6
	v_lshlrev_b32_e32 v14, 16, v70
	v_and_b32_e32 v15, 0xffff0000, v70
	v_lshlrev_b32_e32 v28, 16, v71
	v_and_b32_e32 v29, 0xffff0000, v71
	v_add_f32_e32 v0, v1, v0
	v_add_f32_e32 v6, v16, v0
	s_waitcnt lgkmcnt(0)
	v_pk_add_f32 v[0:1], v[4:5], v[28:29]
	v_pk_add_f32 v[2:3], v[2:3], v[14:15]
	s_nop 0
	v_cvt_pk_bf16_f32 v4, v2, v3
	v_cvt_pk_bf16_f32 v5, v0, v1
	global_store_dwordx2 v[12:13], v[4:5], off offset:256
	s_waitcnt lgkmcnt(0)
	s_nop 0
	v_add_f32_dpp v4, v6, v6 quad_perm:[1,0,3,2] row_mask:0xf bank_mask:0xf bound_ctrl:1
	s_nop 1
	v_add_f32_dpp v4, v4, v4 quad_perm:[2,3,0,1] row_mask:0xf bank_mask:0xf bound_ctrl:1
	s_nop 1
	v_mov_b32_dpp v5, v4 row_shl:4 row_mask:0xf bank_mask:0xf bound_ctrl:1
	s_and_saveexec_b64 s[30:31], s[40:41]
	s_cbranch_execz .LBB0_790
	v_add_f32_e32 v6, v4, v5
	v_lshlrev_b64 v[4:5], 6, v[66:67]
	v_lshl_add_u64 v[4:5], s[28:29], 0, v[4:5]
	global_store_dword v[4:5], v6, off

; __device__ __forceinline__ unsigned pkh(float lo, float hi) { if (!RES_FP16) return cvt_pk_bf16(lo, hi); f16x2 v = {(_Float16)lo, (_Float16)hi}; return __builtin_bit_cast(unsigned, v); }
;     __device__ __forceinline__ void operator()(const f32x4 (&acc)[2][2][4][2], const Unit& u, int wr, int wc, int fr, int fq) const {
;         float* wl = wlds + (wr * 4 + wc) * 576;
;         const int lane = fq * 16 + fr, rl = lane >> 3, ch = lane & 7;
;         f32x4 rb[2][2][2][2];
;         const size_t cbase = (size_t)u.pn * BM + wc * 32 + ch * 4;
;     ...
;         RES_LOAD(0, 0);
; #pragma unroll
;         for (int b = 0; b < 4; ++b) {
;             if (b + 1 < 4) RES_LOAD((b + 1) & 1, b + 1);
; #pragma unroll
;             for (int gg = 0; gg < 2; ++gg) {
;                 const int g = 2 * b + gg, ai = g >> 2, m = g & 3;
;                 const int row0 = u.pm * BM + ai * HALF + wr * 64 + m * 16 + rl;
;                 float sq[2] = {0.f, 0.f};
; #pragma unroll
;                 for (int bj = 0; bj < 2; ++bj) {
;                     *(f32x4*)(wl + fr * 36 + fq * 4) = acc[ai][bj][m][0] * alpha; *(f32x4*)(wl + fr * 36 + 16 + fq * 4) = acc[ai][bj][m][1] * alpha;
;                     asm volatile("s_waitcnt lgkmcnt(0)" ::: "memory");
; #pragma unroll
;                     for (int i = 0; i < 2; ++i) {
;                         const f32x4 x = rb[b & 1][gg][bj][i] + *(const f32x4*)(wl + (rl + 8 * i) * 36 + ch * 4);
;                         const size_t off = (size_t)(row0 + 8 * i) * 1024 + cbase + bj * HALF;
;                         u32x2 w; w.x = pkh(x[0], x[1]); w.y = pkh(x[2], x[3]); *(u32x2*)(X16 + off) = w;
;                         sq[i] += (x[0] * x[0] + x[1] * x[1]) + (x[2] * x[2] + x[3] * x[3]);
;                     }
;                     asm volatile("s_waitcnt lgkmcnt(0)" ::: "memory");
;                 }
; #pragma unroll
;                 for (int i = 0; i < 2; ++i) { float t = sq[i]; t += dpp_f(t, 0); t += dpp_f(t, 1); t += dpp_f(t, 2);
;                     if (ch == 0) ss[(size_t)(row0 + 8 * i) * 16 + u.pn * 4 + wc] = t; }
.LBB0_1483:
	s_ashr_i32 s29, s28, 31
	s_lshl_b64 s[30:31], s[28:29], 8
	v_mov_b32_e32 v141, s31
	v_or_b32_e32 v140, s30, v132
	v_lshl_add_u32 v144, s70, 8, v196
	v_lshlrev_b64 v[140:141], 1, v[140:141]
	v_ashrrev_i32_e32 v145, 31, v144
	v_lshl_add_u64 v[142:143], s[74:75], 0, v[140:141]
	v_lshlrev_b64 v[200:201], 11, v[144:145]
	v_lshl_add_u64 v[146:147], v[142:143], 0, v[200:201]
	global_load_dwordx2 v[202:203], v[146:147], off
	v_or_b32_e32 v186, 8, v144
	v_ashrrev_i32_e32 v187, 31, v186
	v_lshlrev_b64 v[204:205], 11, v[186:187]
	v_lshl_add_u64 v[148:149], v[142:143], 0, v[204:205]
	global_load_dwordx2 v[206:207], v[148:149], off
	global_load_dwordx2 v[212:213], v[148:149], off offset:256
	global_load_dwordx2 v[214:215], v[146:147], off offset:256
	v_or_b32_e32 v180, 16, v144
	v_or_b32_e32 v178, 24, v144
	v_or_b32_e32 v158, 32, v144
	v_or_b32_e32 v156, 40, v144
	v_or_b32_e32 v148, 48, v144
	v_or_b32_e32 v146, 56, v144
	v_ashrrev_i32_e32 v181, 31, v180
	v_ashrrev_i32_e32 v179, 31, v178
	v_ashrrev_i32_e32 v159, 31, v158
	v_ashrrev_i32_e32 v157, 31, v156
	v_ashrrev_i32_e32 v149, 31, v148
	v_ashrrev_i32_e32 v147, 31, v146
	v_lshlrev_b64 v[184:185], 11, v[180:181]
	v_lshlrev_b64 v[182:183], 11, v[178:179]
	v_lshlrev_b64 v[168:169], 11, v[158:159]
	v_lshlrev_b64 v[166:167], 11, v[156:157]
	v_lshlrev_b64 v[152:153], 11, v[148:149]
	v_lshlrev_b64 v[150:151], 11, v[146:147]
	v_lshl_add_u64 v[154:155], v[142:143], 0, v[184:185]
	v_lshl_add_u64 v[160:161], v[142:143], 0, v[182:183]
	v_lshl_add_u64 v[162:163], v[142:143], 0, v[168:169]
	v_lshl_add_u64 v[164:165], v[142:143], 0, v[166:167]
	v_lshl_add_u64 v[216:217], v[142:143], 0, v[152:153]
	v_lshl_add_u64 v[218:219], v[142:143], 0, v[150:151]
	global_load_dwordx2 v[194:195], v[154:155], off
	global_load_dwordx2 v[192:193], v[160:161], off
	global_load_dwordx2 v[188:189], v[160:161], off offset:256
	global_load_dwordx2 v[190:191], v[154:155], off offset:256
	global_load_dwordx2 v[176:177], v[162:163], off
	global_load_dwordx2 v[174:175], v[164:165], off
	global_load_dwordx2 v[170:171], v[164:165], off offset:256
	global_load_dwordx2 v[172:173], v[162:163], off offset:256
	s_nop 0
	global_load_dwordx2 v[164:165], v[216:217], off
	global_load_dwordx2 v[162:163], v[218:219], off
	global_load_dwordx2 v[154:155], v[218:219], off offset:256
	global_load_dwordx2 v[160:161], v[216:217], off offset:256
	v_mov_b32_e32 v131, v130
	v_pk_mul_f32 v[120:121], v[120:121], v[134:135]
	v_pk_mul_f32 v[122:123], v[122:123], v[130:131]
	v_pk_mul_f32 v[124:125], v[124:125], v[134:135]
	v_pk_mul_f32 v[126:127], v[126:127], v[130:131]
	ds_write_b128 v197, v[120:123]
	ds_write_b128 v197, v[124:127] offset:64
	v_lshl_add_u64 v[120:121], s[74:75], 0, v[200:201]
	v_lshl_add_u64 v[126:127], v[120:121], 0, v[140:141]
	ds_read_b128 v[120:123], v198
	v_lshl_add_u64 v[200:201], s[74:75], 0, v[204:205]
	v_lshl_add_u64 v[200:201], v[200:201], 0, v[140:141]
	v_pk_mul_f32 v[118:119], v[118:119], v[130:131]
	v_pk_mul_f32 v[116:117], v[116:117], v[134:135]
	v_pk_mul_f32 v[114:115], v[114:115], v[130:131]
	v_pk_mul_f32 v[112:113], v[112:113], v[134:135]
	s_lshl_b32 s28, s28, 2
	s_ashr_i32 s29, s28, 31
	s_lshl_b64 s[28:29], s[28:29], 2
	s_add_u32 s28, s61, s28
	s_addc_u32 s29, s62, s29
	s_waitcnt vmcnt(0)
	v_lshlrev_b32_e32 v124, 16, v202
	v_and_b32_e32 v125, 0xffff0000, v202
	v_lshlrev_b32_e32 v202, 16, v203
	v_and_b32_e32 v203, 0xffff0000, v203
	s_waitcnt lgkmcnt(0)
	v_pk_add_f32 v[202:203], v[122:123], v[202:203]
	v_pk_add_f32 v[220:221], v[120:121], v[124:125]
	v_lshlrev_b32_e32 v204, 16, v206
	v_cvt_pk_bf16_f32 v120, v220, v221
	v_cvt_pk_bf16_f32 v121, v202, v203
	ds_read_b128 v[122:125], v198 offset:1152
	v_and_b32_e32 v205, 0xffff0000, v206
	v_lshlrev_b32_e32 v206, 16, v207
	v_and_b32_e32 v207, 0xffff0000, v207
	global_store_dwordx2 v[126:127], v[120:121], off
	s_waitcnt lgkmcnt(0)
	v_pk_add_f32 v[120:121], v[124:125], v[206:207]
	v_pk_add_f32 v[122:123], v[122:123], v[204:205]
	v_lshlrev_b32_e32 v216, 16, v214
	v_cvt_pk_bf16_f32 v124, v122, v123
	v_cvt_pk_bf16_f32 v125, v120, v121
	global_store_dwordx2 v[200:201], v[124:125], off
	s_waitcnt lgkmcnt(0)
	ds_write_b128 v197, v[116:119]
	ds_write_b128 v197, v[112:115] offset:64
	ds_read_b128 v[112:115], v198
	v_and_b32_e32 v217, 0xffff0000, v214
	v_lshlrev_b32_e32 v214, 16, v215
	v_and_b32_e32 v215, 0xffff0000, v215
	v_mul_f32_e32 v211, v221, v221
	v_mul_f32_e32 v116, v203, v203
	v_fmac_f32_e32 v211, v220, v220
	v_fmac_f32_e32 v116, v202, v202
	s_waitcnt lgkmcnt(0)
	v_pk_add_f32 v[118:119], v[114:115], v[214:215]
	v_pk_add_f32 v[112:113], v[112:113], v[216:217]
	v_add_f32_e32 v124, v211, v116
	v_cvt_pk_bf16_f32 v114, v112, v113
	v_cvt_pk_bf16_f32 v115, v118, v119
	global_store_dwordx2 v[126:127], v[114:115], off offset:256
	ds_read_b128 v[114:117], v198 offset:1152
	v_mul_f32_e32 v113, v113, v113
	v_fmac_f32_e32 v113, v112, v112
	v_mul_f32_e32 v112, v119, v119
	v_fmac_f32_e32 v112, v118, v118
	v_lshlrev_b32_e32 v218, 16, v212
	v_and_b32_e32 v219, 0xffff0000, v212
	v_lshlrev_b32_e32 v212, 16, v213
	v_and_b32_e32 v213, 0xffff0000, v213
	v_add_f32_e32 v112, v113, v112
	v_add_f32_e32 v118, v124, v112
	s_waitcnt lgkmcnt(0)
	v_pk_add_f32 v[112:113], v[116:117], v[212:213]
	v_pk_add_f32 v[114:115], v[114:115], v[218:219]
	s_nop 0
	v_cvt_pk_bf16_f32 v116, v114, v115
	v_cvt_pk_bf16_f32 v117, v112, v113
	global_store_dwordx2 v[200:201], v[116:117], off offset:256
	s_waitcnt lgkmcnt(0)
	s_nop 0
	v_add_f32_dpp v116, v118, v118 quad_perm:[1,0,3,2] row_mask:0xf bank_mask:0xf bound_ctrl:1
	s_nop 1
	v_add_f32_dpp v116, v116, v116 quad_perm:[2,3,0,1] row_mask:0xf bank_mask:0xf bound_ctrl:1
	s_nop 1
	v_mov_b32_dpp v117, v116 row_shl:4 row_mask:0xf bank_mask:0xf bound_ctrl:1
	s_and_saveexec_b64 s[30:31], s[38:39]
	s_cbranch_execz .LBB0_1485
	v_add_f32_e32 v118, v116, v117
	v_lshlrev_b64 v[116:117], 6, v[144:145]
	v_lshl_add_u64 v[116:117], s[28:29], 0, v[116:117]
	global_store_dword v[116:117], v118, off

; __device__ __forceinline__ unsigned pkh(float lo, float hi) { if (!RES_FP16) return cvt_pk_bf16(lo, hi); f16x2 v = {(_Float16)lo, (_Float16)hi}; return __builtin_bit_cast(unsigned, v); }
;     __device__ __forceinline__ void operator()(const f32x4 (&acc)[2][2][4][2], const Unit& u, int wr, int wc, int fr, int fq) const {
;     ...
;             for (int gg = 0; gg < 2; ++gg) {
;                 const int g = 2 * b + gg, ai = g >> 2, m = g & 3;
;                 const int row0 = u.pm * BM + ai * HALF + wr * 64 + m * 16 + rl;
;                 float sq[2] = {0.f, 0.f};
; #pragma unroll
;                 for (int bj = 0; bj < 2; ++bj) {
;                     *(f32x4*)(wl + fr * 36 + fq * 4) = acc[ai][bj][m][0] * alpha; *(f32x4*)(wl + fr * 36 + 16 + fq * 4) = acc[ai][bj][m][1] * alpha;
;                     asm volatile("s_waitcnt lgkmcnt(0)" ::: "memory");
; #pragma unroll
;                     for (int i = 0; i < 2; ++i) {
;                         const f32x4 x = rb[b & 1][gg][bj][i] + *(const f32x4*)(wl + (rl + 8 * i) * 36 + ch * 4);
;                         const size_t off = (size_t)(row0 + 8 * i) * 1024 + cbase + bj * HALF;
;                         u32x2 w; w.x = pkh(x[0], x[1]); w.y = pkh(x[2], x[3]); *(u32x2*)(X16 + off) = w;
;                         sq[i] += (x[0] * x[0] + x[1] * x[1]) + (x[2] * x[2] + x[3] * x[3]);
;                     }
;                     asm volatile("s_waitcnt lgkmcnt(0)" ::: "memory");
;                 }
; #pragma unroll
;                 for (int i = 0; i < 2; ++i) { float t = sq[i]; t += dpp_f(t, 0); t += dpp_f(t, 1); t += dpp_f(t, 2);
;                     if (ch == 0) ss[(size_t)(row0 + 8 * i) * 16 + u.pn * 4 + wc] = t; }
.LBB0_1487:
	s_or_b64 exec, exec, s[30:31]
	v_mov_b32_e32 v131, v130
	v_pk_mul_f32 v[110:111], v[110:111], v[130:131]
	v_pk_mul_f32 v[108:109], v[108:109], v[134:135]
	v_pk_mul_f32 v[106:107], v[106:107], v[130:131]
	v_pk_mul_f32 v[104:105], v[104:105], v[134:135]
	ds_write_b128 v197, v[108:111]
	ds_write_b128 v197, v[104:107] offset:64
	ds_read_b128 v[104:107], v198
	v_lshlrev_b32_e32 v112, 16, v194
	v_and_b32_e32 v113, 0xffff0000, v194
	v_lshlrev_b32_e32 v114, 16, v195
	v_and_b32_e32 v115, 0xffff0000, v195
	s_waitcnt lgkmcnt(0)
	v_pk_add_f32 v[114:115], v[106:107], v[114:115]
	v_pk_add_f32 v[112:113], v[104:105], v[112:113]
	v_lshlrev_b32_e32 v116, 16, v192
	v_cvt_pk_bf16_f32 v104, v112, v113
	v_cvt_pk_bf16_f32 v105, v114, v115
	ds_read_b128 v[106:109], v198 offset:1152
	v_and_b32_e32 v117, 0xffff0000, v192
	v_lshl_add_u64 v[126:127], s[74:75], 0, v[184:185]
	v_lshlrev_b32_e32 v118, 16, v193
	v_and_b32_e32 v119, 0xffff0000, v193
	s_waitcnt lgkmcnt(0)
	v_pk_add_f32 v[106:107], v[106:107], v[116:117]
	v_lshl_add_u64 v[116:117], s[74:75], 0, v[182:183]
	v_lshl_add_u64 v[126:127], v[126:127], 0, v[140:141]
	v_lshl_add_u64 v[116:117], v[116:117], 0, v[140:141]
	global_store_dwordx2 v[126:127], v[104:105], off
	v_pk_add_f32 v[104:105], v[108:109], v[118:119]
	v_cvt_pk_bf16_f32 v108, v106, v107
	v_pk_mul_f32 v[102:103], v[102:103], v[130:131]
	v_cvt_pk_bf16_f32 v109, v104, v105
	global_store_dwordx2 v[116:117], v[108:109], off
	v_pk_mul_f32 v[100:101], v[100:101], v[134:135]
	v_pk_mul_f32 v[98:99], v[98:99], v[130:131]
	v_pk_mul_f32 v[96:97], v[96:97], v[134:135]
	s_waitcnt lgkmcnt(0)
	ds_write_b128 v197, v[100:103]
	ds_write_b128 v197, v[96:99] offset:64
	ds_read_b128 v[96:99], v198
	v_lshlrev_b32_e32 v120, 16, v190
	v_and_b32_e32 v121, 0xffff0000, v190
	v_lshlrev_b32_e32 v122, 16, v191
	v_and_b32_e32 v123, 0xffff0000, v191
	v_mul_f32_e32 v113, v113, v113
	v_mul_f32_e32 v100, v115, v115
	v_fmac_f32_e32 v113, v112, v112
	v_fmac_f32_e32 v100, v114, v114
	s_waitcnt lgkmcnt(0)
	v_pk_add_f32 v[102:103], v[98:99], v[122:123]
	v_pk_add_f32 v[96:97], v[96:97], v[120:121]
	v_add_f32_e32 v108, v113, v100
	v_cvt_pk_bf16_f32 v98, v96, v97
	v_cvt_pk_bf16_f32 v99, v102, v103
	global_store_dwordx2 v[126:127], v[98:99], off offset:256
	ds_read_b128 v[98:101], v198 offset:1152
	v_mul_f32_e32 v97, v97, v97
	v_fmac_f32_e32 v97, v96, v96
	v_mul_f32_e32 v96, v103, v103
	v_fmac_f32_e32 v96, v102, v102
	v_lshlrev_b32_e32 v110, 16, v188
	v_and_b32_e32 v111, 0xffff0000, v188
	v_lshlrev_b32_e32 v124, 16, v189
	v_and_b32_e32 v125, 0xffff0000, v189
	v_add_f32_e32 v96, v97, v96
	v_add_f32_e32 v102, v108, v96
	s_waitcnt lgkmcnt(0)
	v_pk_add_f32 v[96:97], v[100:101], v[124:125]
	v_pk_add_f32 v[98:99], v[98:99], v[110:111]
	s_nop 0
	v_cvt_pk_bf16_f32 v100, v98, v99
	v_cvt_pk_bf16_f32 v101, v96, v97
	global_store_dwordx2 v[116:117], v[100:101], off offset:256
	s_waitcnt lgkmcnt(0)
	s_nop 0
	v_add_f32_dpp v100, v102, v102 quad_perm:[1,0,3,2] row_mask:0xf bank_mask:0xf bound_ctrl:1
	s_nop 1
	v_add_f32_dpp v100, v100, v100 quad_perm:[2,3,0,1] row_mask:0xf bank_mask:0xf bound_ctrl:1
	s_nop 1
	v_mov_b32_dpp v101, v100 row_shl:4 row_mask:0xf bank_mask:0xf bound_ctrl:1
	s_and_saveexec_b64 s[30:31], s[38:39]
	s_cbranch_execz .LBB0_1489
	v_add_f32_e32 v102, v100, v101
	v_lshlrev_b64 v[100:101], 6, v[180:181]
	v_lshl_add_u64 v[100:101], s[28:29], 0, v[100:101]
	global_store_dword v[100:101], v102, off

; __device__ __forceinline__ unsigned pkh(float lo, float hi) { if (!RES_FP16) return cvt_pk_bf16(lo, hi); f16x2 v = {(_Float16)lo, (_Float16)hi}; return __builtin_bit_cast(unsigned, v); }
;     __device__ __forceinline__ void operator()(const f32x4 (&acc)[2][2][4][2], const Unit& u, int wr, int wc, int fr, int fq) const {
;     ...
;         RES_LOAD(0, 0);
; #pragma unroll
;         for (int b = 0; b < 4; ++b) {
;             if (b + 1 < 4) RES_LOAD((b + 1) & 1, b + 1);
; #pragma unroll
;             for (int gg = 0; gg < 2; ++gg) {
;                 const int g = 2 * b + gg, ai = g >> 2, m = g & 3;
;                 const int row0 = u.pm * BM + ai * HALF + wr * 64 + m * 16 + rl;
;                 float sq[2] = {0.f, 0.f};
; #pragma unroll
;                 for (int bj = 0; bj < 2; ++bj) {
;                     *(f32x4*)(wl + fr * 36 + fq * 4) = acc[ai][bj][m][0] * alpha; *(f32x4*)(wl + fr * 36 + 16 + fq * 4) = acc[ai][bj][m][1] * alpha;
;                     asm volatile("s_waitcnt lgkmcnt(0)" ::: "memory");
; #pragma unroll
;                     for (int i = 0; i < 2; ++i) {
;                         const f32x4 x = rb[b & 1][gg][bj][i] + *(const f32x4*)(wl + (rl + 8 * i) * 36 + ch * 4);
;                         const size_t off = (size_t)(row0 + 8 * i) * 1024 + cbase + bj * HALF;
;                         u32x2 w; w.x = pkh(x[0], x[1]); w.y = pkh(x[2], x[3]); *(u32x2*)(X16 + off) = w;
;                         sq[i] += (x[0] * x[0] + x[1] * x[1]) + (x[2] * x[2] + x[3] * x[3]);
;                     }
;                     asm volatile("s_waitcnt lgkmcnt(0)" ::: "memory");
;                 }
; #pragma unroll
;                 for (int i = 0; i < 2; ++i) { float t = sq[i]; t += dpp_f(t, 0); t += dpp_f(t, 1); t += dpp_f(t, 2);
;                     if (ch == 0) ss[(size_t)(row0 + 8 * i) * 16 + u.pn * 4 + wc] = t; }
.LBB0_1491:
	s_or_b64 exec, exec, s[30:31]
	v_add_u32_e32 v112, 0x80, v144
	v_add_u32_e32 v104, 0x88, v144
	v_ashrrev_i32_e32 v113, 31, v112
	v_ashrrev_i32_e32 v105, 31, v104
	v_lshlrev_b64 v[114:115], 11, v[112:113]
	v_lshlrev_b64 v[98:99], 11, v[104:105]
	v_lshl_add_u64 v[96:97], v[142:143], 0, v[114:115]
	v_lshl_add_u64 v[98:99], v[142:143], 0, v[98:99]
	global_load_dwordx2 v[122:123], v[96:97], off
	global_load_dwordx2 v[120:121], v[98:99], off
	global_load_dwordx2 v[116:117], v[98:99], off offset:256
	global_load_dwordx2 v[118:119], v[96:97], off offset:256
	v_add_u32_e32 v98, 0x90, v144
	v_add_u32_e32 v96, 0x98, v144
	v_ashrrev_i32_e32 v99, 31, v98
	v_ashrrev_i32_e32 v97, 31, v96
	v_lshlrev_b64 v[100:101], 11, v[98:99]
	v_lshlrev_b64 v[102:103], 11, v[96:97]
	v_lshl_add_u64 v[106:107], v[142:143], 0, v[100:101]
	v_lshl_add_u64 v[102:103], v[142:143], 0, v[102:103]
	global_load_dwordx2 v[110:111], v[106:107], off
	global_load_dwordx2 v[108:109], v[102:103], off
	s_nop 0
	global_load_dwordx2 v[102:103], v[102:103], off offset:256
	s_nop 0
	global_load_dwordx2 v[106:107], v[106:107], off offset:256
	v_mov_b32_e32 v131, v130
	v_pk_mul_f32 v[94:95], v[94:95], v[130:131]
	v_pk_mul_f32 v[92:93], v[92:93], v[134:135]
	v_pk_mul_f32 v[90:91], v[90:91], v[130:131]
	v_pk_mul_f32 v[88:89], v[88:89], v[134:135]
	ds_write_b128 v197, v[92:95]
	ds_write_b128 v197, v[88:91] offset:64
	ds_read_b128 v[88:91], v198
	v_lshlrev_b32_e32 v124, 16, v176
	v_and_b32_e32 v125, 0xffff0000, v176
	v_lshlrev_b32_e32 v126, 16, v177
	v_and_b32_e32 v127, 0xffff0000, v177
	s_waitcnt lgkmcnt(0)
	v_pk_add_f32 v[126:127], v[90:91], v[126:127]
	v_pk_add_f32 v[124:125], v[88:89], v[124:125]
	v_lshl_add_u64 v[168:169], s[74:75], 0, v[168:169]
	v_cvt_pk_bf16_f32 v88, v124, v125
	v_cvt_pk_bf16_f32 v89, v126, v127
	ds_read_b128 v[90:93], v198 offset:1152
	v_lshl_add_u64 v[166:167], s[74:75], 0, v[166:167]
	v_lshlrev_b32_e32 v176, 16, v174
	v_and_b32_e32 v177, 0xffff0000, v174
	v_lshlrev_b32_e32 v174, 16, v175
	v_and_b32_e32 v175, 0xffff0000, v175
	v_lshl_add_u64 v[168:169], v[168:169], 0, v[140:141]
	v_lshl_add_u64 v[166:167], v[166:167], 0, v[140:141]
	global_store_dwordx2 v[168:169], v[88:89], off
	s_waitcnt lgkmcnt(0)
	v_pk_add_f32 v[88:89], v[92:93], v[174:175]
	v_pk_add_f32 v[90:91], v[90:91], v[176:177]
	v_pk_mul_f32 v[86:87], v[86:87], v[130:131]
	v_cvt_pk_bf16_f32 v92, v90, v91
	v_cvt_pk_bf16_f32 v93, v88, v89
	global_store_dwordx2 v[166:167], v[92:93], off
	v_pk_mul_f32 v[84:85], v[84:85], v[134:135]
	v_pk_mul_f32 v[82:83], v[82:83], v[130:131]
	v_pk_mul_f32 v[80:81], v[80:81], v[134:135]
	s_waitcnt lgkmcnt(0)
	ds_write_b128 v197, v[84:87]
	ds_write_b128 v197, v[80:83] offset:64
	ds_read_b128 v[80:83], v198
	v_lshlrev_b32_e32 v178, 16, v172
	v_and_b32_e32 v179, 0xffff0000, v172
	v_lshlrev_b32_e32 v172, 16, v173
	v_and_b32_e32 v173, 0xffff0000, v173
	v_mul_f32_e32 v125, v125, v125
	v_mul_f32_e32 v84, v127, v127
	v_fmac_f32_e32 v125, v124, v124
	v_fmac_f32_e32 v84, v126, v126
	s_waitcnt lgkmcnt(0)
	v_pk_add_f32 v[86:87], v[82:83], v[172:173]
	v_pk_add_f32 v[80:81], v[80:81], v[178:179]
	v_add_f32_e32 v92, v125, v84
	v_cvt_pk_bf16_f32 v82, v80, v81
	v_cvt_pk_bf16_f32 v83, v86, v87
	global_store_dwordx2 v[168:169], v[82:83], off offset:256
	ds_read_b128 v[82:85], v198 offset:1152
	v_mul_f32_e32 v81, v81, v81
	v_fmac_f32_e32 v81, v80, v80
	v_mul_f32_e32 v80, v87, v87
	v_fmac_f32_e32 v80, v86, v86
	v_lshlrev_b32_e32 v94, 16, v170
	v_and_b32_e32 v95, 0xffff0000, v170
	v_lshlrev_b32_e32 v170, 16, v171
	v_and_b32_e32 v171, 0xffff0000, v171
	v_add_f32_e32 v80, v81, v80
	v_add_f32_e32 v86, v92, v80
	s_waitcnt lgkmcnt(0)
	v_pk_add_f32 v[80:81], v[84:85], v[170:171]
	v_pk_add_f32 v[82:83], v[82:83], v[94:95]
	s_nop 0
	v_cvt_pk_bf16_f32 v84, v82, v83
	v_cvt_pk_bf16_f32 v85, v80, v81
	global_store_dwordx2 v[166:167], v[84:85], off offset:256
	s_waitcnt lgkmcnt(0)
	s_nop 0
	v_add_f32_dpp v84, v86, v86 quad_perm:[1,0,3,2] row_mask:0xf bank_mask:0xf bound_ctrl:1
	s_nop 1
	v_add_f32_dpp v84, v84, v84 quad_perm:[2,3,0,1] row_mask:0xf bank_mask:0xf bound_ctrl:1
	s_nop 1
	v_mov_b32_dpp v85, v84 row_shl:4 row_mask:0xf bank_mask:0xf bound_ctrl:1
	s_and_saveexec_b64 s[30:31], s[38:39]
	s_cbranch_execz .LBB0_1493
	v_add_f32_e32 v86, v84, v85
	v_lshlrev_b64 v[84:85], 6, v[158:159]
	v_lshl_add_u64 v[84:85], s[28:29], 0, v[84:85]
	global_store_dword v[84:85], v86, off

; __device__ __forceinline__ unsigned pkh(float lo, float hi) { if (!RES_FP16) return cvt_pk_bf16(lo, hi); f16x2 v = {(_Float16)lo, (_Float16)hi}; return __builtin_bit_cast(unsigned, v); }
;     __device__ __forceinline__ void operator()(const f32x4 (&acc)[2][2][4][2], const Unit& u, int wr, int wc, int fr, int fq) const {
;     ...
;             for (int gg = 0; gg < 2; ++gg) {
;                 const int g = 2 * b + gg, ai = g >> 2, m = g & 3;
;                 const int row0 = u.pm * BM + ai * HALF + wr * 64 + m * 16 + rl;
;                 float sq[2] = {0.f, 0.f};
; #pragma unroll
;                 for (int bj = 0; bj < 2; ++bj) {
;                     *(f32x4*)(wl + fr * 36 + fq * 4) = acc[ai][bj][m][0] * alpha; *(f32x4*)(wl + fr * 36 + 16 + fq * 4) = acc[ai][bj][m][1] * alpha;
;                     asm volatile("s_waitcnt lgkmcnt(0)" ::: "memory");
; #pragma unroll
;                     for (int i = 0; i < 2; ++i) {
;                         const f32x4 x = rb[b & 1][gg][bj][i] + *(const f32x4*)(wl + (rl + 8 * i) * 36 + ch * 4);
;                         const size_t off = (size_t)(row0 + 8 * i) * 1024 + cbase + bj * HALF;
;                         u32x2 w; w.x = pkh(x[0], x[1]); w.y = pkh(x[2], x[3]); *(u32x2*)(X16 + off) = w;
;                         sq[i] += (x[0] * x[0] + x[1] * x[1]) + (x[2] * x[2] + x[3] * x[3]);
;                     }
;                     asm volatile("s_waitcnt lgkmcnt(0)" ::: "memory");
;                 }
; #pragma unroll
;                 for (int i = 0; i < 2; ++i) { float t = sq[i]; t += dpp_f(t, 0); t += dpp_f(t, 1); t += dpp_f(t, 2);
;                     if (ch == 0) ss[(size_t)(row0 + 8 * i) * 16 + u.pn * 4 + wc] = t; }
.LBB0_1495:
	s_or_b64 exec, exec, s[30:31]
	v_mov_b32_e32 v131, v130
	v_pk_mul_f32 v[78:79], v[78:79], v[130:131]
	v_pk_mul_f32 v[76:77], v[76:77], v[134:135]
	v_pk_mul_f32 v[74:75], v[74:75], v[130:131]
	v_pk_mul_f32 v[72:73], v[72:73], v[134:135]
	ds_write_b128 v197, v[76:79]
	ds_write_b128 v197, v[72:75] offset:64
	ds_read_b128 v[72:75], v198
	v_lshlrev_b32_e32 v80, 16, v164
	v_and_b32_e32 v81, 0xffff0000, v164
	v_lshlrev_b32_e32 v82, 16, v165
	v_and_b32_e32 v83, 0xffff0000, v165
	s_waitcnt lgkmcnt(0)
	v_pk_add_f32 v[82:83], v[74:75], v[82:83]
	v_pk_add_f32 v[80:81], v[72:73], v[80:81]
	v_lshlrev_b32_e32 v84, 16, v162
	v_cvt_pk_bf16_f32 v72, v80, v81
	v_cvt_pk_bf16_f32 v73, v82, v83
	ds_read_b128 v[74:77], v198 offset:1152
	v_and_b32_e32 v85, 0xffff0000, v162
	v_lshl_add_u64 v[94:95], s[74:75], 0, v[152:153]
	v_lshlrev_b32_e32 v86, 16, v163
	v_and_b32_e32 v87, 0xffff0000, v163
	s_waitcnt lgkmcnt(0)
	v_pk_add_f32 v[74:75], v[74:75], v[84:85]
	v_lshl_add_u64 v[84:85], s[74:75], 0, v[150:151]
	v_lshl_add_u64 v[94:95], v[94:95], 0, v[140:141]
	v_lshl_add_u64 v[84:85], v[84:85], 0, v[140:141]
	global_store_dwordx2 v[94:95], v[72:73], off
	v_pk_add_f32 v[72:73], v[76:77], v[86:87]
	v_cvt_pk_bf16_f32 v76, v74, v75
	v_pk_mul_f32 v[70:71], v[70:71], v[130:131]
	v_cvt_pk_bf16_f32 v77, v72, v73
	global_store_dwordx2 v[84:85], v[76:77], off
	v_pk_mul_f32 v[68:69], v[68:69], v[134:135]
	v_pk_mul_f32 v[66:67], v[66:67], v[130:131]
	v_pk_mul_f32 v[64:65], v[64:65], v[134:135]
	s_waitcnt lgkmcnt(0)
	ds_write_b128 v197, v[68:71]
	ds_write_b128 v197, v[64:67] offset:64
	ds_read_b128 v[64:67], v198
	v_lshlrev_b32_e32 v88, 16, v160
	v_and_b32_e32 v89, 0xffff0000, v160
	v_lshlrev_b32_e32 v90, 16, v161
	v_and_b32_e32 v91, 0xffff0000, v161
	v_mul_f32_e32 v81, v81, v81
	v_mul_f32_e32 v68, v83, v83
	v_fmac_f32_e32 v81, v80, v80
	v_fmac_f32_e32 v68, v82, v82
	s_waitcnt lgkmcnt(0)
	v_pk_add_f32 v[70:71], v[66:67], v[90:91]
	v_pk_add_f32 v[64:65], v[64:65], v[88:89]
	v_add_f32_e32 v76, v81, v68
	v_cvt_pk_bf16_f32 v66, v64, v65
	v_cvt_pk_bf16_f32 v67, v70, v71
	global_store_dwordx2 v[94:95], v[66:67], off offset:256
	ds_read_b128 v[66:69], v198 offset:1152
	v_mul_f32_e32 v65, v65, v65
	v_fmac_f32_e32 v65, v64, v64
	v_mul_f32_e32 v64, v71, v71
	v_fmac_f32_e32 v64, v70, v70
	v_lshlrev_b32_e32 v78, 16, v154
	v_and_b32_e32 v79, 0xffff0000, v154
	v_lshlrev_b32_e32 v92, 16, v155
	v_and_b32_e32 v93, 0xffff0000, v155
	v_add_f32_e32 v64, v65, v64
	v_add_f32_e32 v70, v76, v64
	s_waitcnt lgkmcnt(0)
	v_pk_add_f32 v[64:65], v[68:69], v[92:93]
	v_pk_add_f32 v[66:67], v[66:67], v[78:79]
	s_nop 0
	v_cvt_pk_bf16_f32 v68, v66, v67
	v_cvt_pk_bf16_f32 v69, v64, v65
	global_store_dwordx2 v[84:85], v[68:69], off offset:256
	s_waitcnt lgkmcnt(0)
	s_nop 0
	v_add_f32_dpp v68, v70, v70 quad_perm:[1,0,3,2] row_mask:0xf bank_mask:0xf bound_ctrl:1
	s_nop 1
	v_add_f32_dpp v68, v68, v68 quad_perm:[2,3,0,1] row_mask:0xf bank_mask:0xf bound_ctrl:1
	s_nop 1
	v_mov_b32_dpp v69, v68 row_shl:4 row_mask:0xf bank_mask:0xf bound_ctrl:1
	s_and_saveexec_b64 s[30:31], s[38:39]
	s_cbranch_execz .LBB0_1497
	v_add_f32_e32 v70, v68, v69
	v_lshlrev_b64 v[68:69], 6, v[148:149]
	v_lshl_add_u64 v[68:69], s[28:29], 0, v[68:69]
	global_store_dword v[68:69], v70, off

; __device__ __forceinline__ unsigned pkh(float lo, float hi) { if (!RES_FP16) return cvt_pk_bf16(lo, hi); f16x2 v = {(_Float16)lo, (_Float16)hi}; return __builtin_bit_cast(unsigned, v); }
;     __device__ __forceinline__ void operator()(const f32x4 (&acc)[2][2][4][2], const Unit& u, int wr, int wc, int fr, int fq) const {
;     ...
;         RES_LOAD(0, 0);
; #pragma unroll
;         for (int b = 0; b < 4; ++b) {
;             if (b + 1 < 4) RES_LOAD((b + 1) & 1, b + 1);
; #pragma unroll
;             for (int gg = 0; gg < 2; ++gg) {
;                 const int g = 2 * b + gg, ai = g >> 2, m = g & 3;
;                 const int row0 = u.pm * BM + ai * HALF + wr * 64 + m * 16 + rl;
;                 float sq[2] = {0.f, 0.f};
; #pragma unroll
;                 for (int bj = 0; bj < 2; ++bj) {
;                     *(f32x4*)(wl + fr * 36 + fq * 4) = acc[ai][bj][m][0] * alpha; *(f32x4*)(wl + fr * 36 + 16 + fq * 4) = acc[ai][bj][m][1] * alpha;
;                     asm volatile("s_waitcnt lgkmcnt(0)" ::: "memory");
; #pragma unroll
;                     for (int i = 0; i < 2; ++i) {
;                         const f32x4 x = rb[b & 1][gg][bj][i] + *(const f32x4*)(wl + (rl + 8 * i) * 36 + ch * 4);
;                         const size_t off = (size_t)(row0 + 8 * i) * 1024 + cbase + bj * HALF;
;                         u32x2 w; w.x = pkh(x[0], x[1]); w.y = pkh(x[2], x[3]); *(u32x2*)(X16 + off) = w;
;                         sq[i] += (x[0] * x[0] + x[1] * x[1]) + (x[2] * x[2] + x[3] * x[3]);
;                     }
;                     asm volatile("s_waitcnt lgkmcnt(0)" ::: "memory");
;                 }
; #pragma unroll
;                 for (int i = 0; i < 2; ++i) { float t = sq[i]; t += dpp_f(t, 0); t += dpp_f(t, 1); t += dpp_f(t, 2);
;                     if (ch == 0) ss[(size_t)(row0 + 8 * i) * 16 + u.pn * 4 + wc] = t; }
.LBB0_1499:
	s_or_b64 exec, exec, s[30:31]
	v_add_u32_e32 v80, 0xa0, v144
	v_add_u32_e32 v72, 0xa8, v144
	v_ashrrev_i32_e32 v81, 31, v80
	v_ashrrev_i32_e32 v73, 31, v72
	v_lshlrev_b64 v[82:83], 11, v[80:81]
	v_lshlrev_b64 v[66:67], 11, v[72:73]
	v_lshl_add_u64 v[64:65], v[142:143], 0, v[82:83]
	v_lshl_add_u64 v[66:67], v[142:143], 0, v[66:67]
	global_load_dwordx2 v[90:91], v[64:65], off
	global_load_dwordx2 v[88:89], v[66:67], off
	global_load_dwordx2 v[84:85], v[66:67], off offset:256
	global_load_dwordx2 v[86:87], v[64:65], off offset:256
	v_add_u32_e32 v66, 0xb0, v144
	v_add_u32_e32 v64, 0xb8, v144
	v_ashrrev_i32_e32 v67, 31, v66
	v_ashrrev_i32_e32 v65, 31, v64
	v_lshlrev_b64 v[68:69], 11, v[66:67]
	v_lshlrev_b64 v[70:71], 11, v[64:65]
	v_lshl_add_u64 v[74:75], v[142:143], 0, v[68:69]
	v_lshl_add_u64 v[70:71], v[142:143], 0, v[70:71]
	global_load_dwordx2 v[78:79], v[74:75], off
	global_load_dwordx2 v[76:77], v[70:71], off
	s_nop 0
	global_load_dwordx2 v[70:71], v[70:71], off offset:256
	s_nop 0
	global_load_dwordx2 v[74:75], v[74:75], off offset:256
	v_mov_b32_e32 v131, v130
	v_pk_mul_f32 v[62:63], v[62:63], v[130:131]
	v_pk_mul_f32 v[60:61], v[60:61], v[134:135]
	v_pk_mul_f32 v[58:59], v[58:59], v[130:131]
	v_pk_mul_f32 v[56:57], v[56:57], v[134:135]
	ds_write_b128 v197, v[60:63]
	ds_write_b128 v197, v[56:59] offset:64
	ds_read_b128 v[56:59], v198
	s_waitcnt vmcnt(23)
	v_lshlrev_b32_e32 v92, 16, v122
	v_and_b32_e32 v93, 0xffff0000, v122
	v_lshlrev_b32_e32 v94, 16, v123
	v_and_b32_e32 v95, 0xffff0000, v123
	s_waitcnt lgkmcnt(0)
	v_pk_add_f32 v[94:95], v[58:59], v[94:95]
	v_pk_add_f32 v[92:93], v[56:57], v[92:93]
	v_lshl_add_u64 v[114:115], s[74:75], 0, v[114:115]
	v_cvt_pk_bf16_f32 v56, v92, v93
	v_cvt_pk_bf16_f32 v57, v94, v95
	ds_read_b128 v[58:61], v198 offset:1152
	s_waitcnt vmcnt(22)
	v_lshlrev_b32_e32 v122, 16, v120
	v_and_b32_e32 v123, 0xffff0000, v120
	v_lshlrev_b32_e32 v120, 16, v121
	v_and_b32_e32 v121, 0xffff0000, v121
	v_lshl_add_u64 v[114:115], v[114:115], 0, v[140:141]
	global_store_dwordx2 v[114:115], v[56:57], off
	s_waitcnt lgkmcnt(0)
	v_pk_add_f32 v[56:57], v[60:61], v[120:121]
	v_or_b32_e32 v60, 8, v112
	v_ashrrev_i32_e32 v61, 31, v60
	v_lshlrev_b64 v[60:61], 11, v[60:61]
	v_lshl_add_u64 v[60:61], s[74:75], 0, v[60:61]
	v_lshl_add_u64 v[60:61], v[60:61], 0, v[140:141]
	v_pk_add_f32 v[58:59], v[58:59], v[122:123]
	v_pk_mul_f32 v[54:55], v[54:55], v[130:131]
	v_cvt_pk_bf16_f32 v120, v58, v59
	v_cvt_pk_bf16_f32 v121, v56, v57
	global_store_dwordx2 v[60:61], v[120:121], off
	v_pk_mul_f32 v[52:53], v[52:53], v[134:135]
	v_pk_mul_f32 v[50:51], v[50:51], v[130:131]
	v_pk_mul_f32 v[48:49], v[48:49], v[134:135]
	s_waitcnt lgkmcnt(0)
	ds_write_b128 v197, v[52:55]
	ds_write_b128 v197, v[48:51] offset:64
	ds_read_b128 v[48:51], v198
	s_waitcnt vmcnt(22)
	v_lshlrev_b32_e32 v124, 16, v118
	v_and_b32_e32 v125, 0xffff0000, v118
	v_lshlrev_b32_e32 v118, 16, v119
	v_and_b32_e32 v119, 0xffff0000, v119
	v_mul_f32_e32 v93, v93, v93
	v_mul_f32_e32 v52, v95, v95
	v_fmac_f32_e32 v93, v92, v92
	v_fmac_f32_e32 v52, v94, v94
	s_waitcnt lgkmcnt(0)
	v_pk_add_f32 v[54:55], v[50:51], v[118:119]
	v_pk_add_f32 v[48:49], v[48:49], v[124:125]
	v_add_f32_e32 v92, v93, v52
	v_cvt_pk_bf16_f32 v50, v48, v49
	v_cvt_pk_bf16_f32 v51, v54, v55
	global_store_dwordx2 v[114:115], v[50:51], off offset:256
	ds_read_b128 v[50:53], v198 offset:1152
	v_mul_f32_e32 v49, v49, v49
	v_fmac_f32_e32 v49, v48, v48
	v_mul_f32_e32 v48, v55, v55
	v_fmac_f32_e32 v48, v54, v54
	v_lshlrev_b32_e32 v62, 16, v116
	v_and_b32_e32 v63, 0xffff0000, v116
	v_lshlrev_b32_e32 v116, 16, v117
	v_and_b32_e32 v117, 0xffff0000, v117
	v_add_f32_e32 v48, v49, v48
	v_add_f32_e32 v54, v92, v48
	s_waitcnt lgkmcnt(0)
	v_pk_add_f32 v[48:49], v[52:53], v[116:117]
	v_pk_add_f32 v[50:51], v[50:51], v[62:63]
	s_nop 0
	v_cvt_pk_bf16_f32 v52, v50, v51
	v_cvt_pk_bf16_f32 v53, v48, v49
	global_store_dwordx2 v[60:61], v[52:53], off offset:256
	s_waitcnt lgkmcnt(0)
	s_nop 0
	v_add_f32_dpp v52, v54, v54 quad_perm:[1,0,3,2] row_mask:0xf bank_mask:0xf bound_ctrl:1
	s_nop 1
	v_add_f32_dpp v52, v52, v52 quad_perm:[2,3,0,1] row_mask:0xf bank_mask:0xf bound_ctrl:1
	s_nop 1
	v_mov_b32_dpp v53, v52 row_shl:4 row_mask:0xf bank_mask:0xf bound_ctrl:1
	s_and_saveexec_b64 s[30:31], s[38:39]
	s_cbranch_execz .LBB0_1501
	v_add_f32_e32 v54, v52, v53
	v_lshlrev_b64 v[52:53], 6, v[112:113]
	v_lshl_add_u64 v[52:53], s[28:29], 0, v[52:53]
	global_store_dword v[52:53], v54, off

; __device__ __forceinline__ unsigned pkh(float lo, float hi) { if (!RES_FP16) return cvt_pk_bf16(lo, hi); f16x2 v = {(_Float16)lo, (_Float16)hi}; return __builtin_bit_cast(unsigned, v); }
;     __device__ __forceinline__ void operator()(const f32x4 (&acc)[2][2][4][2], const Unit& u, int wr, int wc, int fr, int fq) const {
;     ...
;             for (int gg = 0; gg < 2; ++gg) {
;                 const int g = 2 * b + gg, ai = g >> 2, m = g & 3;
;                 const int row0 = u.pm * BM + ai * HALF + wr * 64 + m * 16 + rl;
;                 float sq[2] = {0.f, 0.f};
; #pragma unroll
;                 for (int bj = 0; bj < 2; ++bj) {
;                     *(f32x4*)(wl + fr * 36 + fq * 4) = acc[ai][bj][m][0] * alpha; *(f32x4*)(wl + fr * 36 + 16 + fq * 4) = acc[ai][bj][m][1] * alpha;
;                     asm volatile("s_waitcnt lgkmcnt(0)" ::: "memory");
; #pragma unroll
;                     for (int i = 0; i < 2; ++i) {
;                         const f32x4 x = rb[b & 1][gg][bj][i] + *(const f32x4*)(wl + (rl + 8 * i) * 36 + ch * 4);
;                         const size_t off = (size_t)(row0 + 8 * i) * 1024 + cbase + bj * HALF;
;                         u32x2 w; w.x = pkh(x[0], x[1]); w.y = pkh(x[2], x[3]); *(u32x2*)(X16 + off) = w;
;                         sq[i] += (x[0] * x[0] + x[1] * x[1]) + (x[2] * x[2] + x[3] * x[3]);
;                     }
;                     asm volatile("s_waitcnt lgkmcnt(0)" ::: "memory");
;                 }
; #pragma unroll
;                 for (int i = 0; i < 2; ++i) { float t = sq[i]; t += dpp_f(t, 0); t += dpp_f(t, 1); t += dpp_f(t, 2);
;                     if (ch == 0) ss[(size_t)(row0 + 8 * i) * 16 + u.pn * 4 + wc] = t; }
.LBB0_1503:
	s_or_b64 exec, exec, s[30:31]
	v_mov_b32_e32 v131, v130
	v_pk_mul_f32 v[46:47], v[46:47], v[130:131]
	v_pk_mul_f32 v[44:45], v[44:45], v[134:135]
	v_pk_mul_f32 v[42:43], v[42:43], v[130:131]
	v_pk_mul_f32 v[40:41], v[40:41], v[134:135]
	ds_write_b128 v197, v[44:47]
	ds_write_b128 v197, v[40:43] offset:64
	ds_read_b128 v[40:43], v198
	s_waitcnt vmcnt(23)
	v_lshlrev_b32_e32 v48, 16, v110
	v_and_b32_e32 v49, 0xffff0000, v110
	v_lshlrev_b32_e32 v50, 16, v111
	v_and_b32_e32 v51, 0xffff0000, v111
	s_waitcnt lgkmcnt(0)
	v_pk_add_f32 v[50:51], v[42:43], v[50:51]
	v_pk_add_f32 v[48:49], v[40:41], v[48:49]
	v_lshl_add_u64 v[62:63], s[74:75], 0, v[100:101]
	v_cvt_pk_bf16_f32 v40, v48, v49
	v_cvt_pk_bf16_f32 v41, v50, v51
	ds_read_b128 v[42:45], v198 offset:1152
	s_waitcnt vmcnt(22)
	v_lshlrev_b32_e32 v54, 16, v109
	v_and_b32_e32 v55, 0xffff0000, v109
	v_lshl_add_u64 v[62:63], v[62:63], 0, v[140:141]
	global_store_dwordx2 v[62:63], v[40:41], off
	s_waitcnt lgkmcnt(0)
	v_pk_add_f32 v[40:41], v[44:45], v[54:55]
	v_or_b32_e32 v44, 8, v98
	v_ashrrev_i32_e32 v45, 31, v44
	v_lshlrev_b64 v[44:45], 11, v[44:45]
	v_lshl_add_u64 v[44:45], s[74:75], 0, v[44:45]
	v_lshlrev_b32_e32 v52, 16, v108
	v_and_b32_e32 v53, 0xffff0000, v108
	v_lshl_add_u64 v[44:45], v[44:45], 0, v[140:141]
	v_pk_add_f32 v[42:43], v[42:43], v[52:53]
	v_pk_mul_f32 v[38:39], v[38:39], v[130:131]
	v_cvt_pk_bf16_f32 v52, v42, v43
	v_cvt_pk_bf16_f32 v53, v40, v41
	global_store_dwordx2 v[44:45], v[52:53], off
	v_pk_mul_f32 v[36:37], v[36:37], v[134:135]
	v_pk_mul_f32 v[34:35], v[34:35], v[130:131]
	v_pk_mul_f32 v[32:33], v[32:33], v[134:135]
	s_waitcnt lgkmcnt(0)
	ds_write_b128 v197, v[36:39]
	ds_write_b128 v197, v[32:35] offset:64
	ds_read_b128 v[32:35], v198
	s_waitcnt vmcnt(22)
	v_lshlrev_b32_e32 v56, 16, v106
	v_and_b32_e32 v57, 0xffff0000, v106
	v_lshlrev_b32_e32 v58, 16, v107
	v_and_b32_e32 v59, 0xffff0000, v107
	v_mul_f32_e32 v49, v49, v49
	v_mul_f32_e32 v36, v51, v51
	v_fmac_f32_e32 v49, v48, v48
	v_fmac_f32_e32 v36, v50, v50
	s_waitcnt lgkmcnt(0)
	v_pk_add_f32 v[38:39], v[34:35], v[58:59]
	v_pk_add_f32 v[32:33], v[32:33], v[56:57]
	v_add_f32_e32 v48, v49, v36
	v_cvt_pk_bf16_f32 v34, v32, v33
	v_cvt_pk_bf16_f32 v35, v38, v39
	global_store_dwordx2 v[62:63], v[34:35], off offset:256
	ds_read_b128 v[34:37], v198 offset:1152
	v_mul_f32_e32 v33, v33, v33
	v_fmac_f32_e32 v33, v32, v32
	v_mul_f32_e32 v32, v39, v39
	v_fmac_f32_e32 v32, v38, v38
	v_lshlrev_b32_e32 v46, 16, v102
	v_and_b32_e32 v47, 0xffff0000, v102
	v_lshlrev_b32_e32 v60, 16, v103
	v_and_b32_e32 v61, 0xffff0000, v103
	v_add_f32_e32 v32, v33, v32
	v_add_f32_e32 v38, v48, v32
	s_waitcnt lgkmcnt(0)
	v_pk_add_f32 v[32:33], v[36:37], v[60:61]
	v_pk_add_f32 v[34:35], v[34:35], v[46:47]
	s_nop 0
	v_cvt_pk_bf16_f32 v36, v34, v35
	v_cvt_pk_bf16_f32 v37, v32, v33
	global_store_dwordx2 v[44:45], v[36:37], off offset:256
	s_waitcnt lgkmcnt(0)
	s_nop 0
	v_add_f32_dpp v36, v38, v38 quad_perm:[1,0,3,2] row_mask:0xf bank_mask:0xf bound_ctrl:1
	s_nop 1
	v_add_f32_dpp v36, v36, v36 quad_perm:[2,3,0,1] row_mask:0xf bank_mask:0xf bound_ctrl:1
	s_nop 1
	v_mov_b32_dpp v37, v36 row_shl:4 row_mask:0xf bank_mask:0xf bound_ctrl:1
	s_and_saveexec_b64 s[30:31], s[38:39]
	s_cbranch_execz .LBB0_1505
	v_add_f32_e32 v38, v36, v37
	v_lshlrev_b64 v[36:37], 6, v[98:99]
	v_lshl_add_u64 v[36:37], s[28:29], 0, v[36:37]
	global_store_dword v[36:37], v38, off

; __device__ __forceinline__ unsigned pkh(float lo, float hi) { if (!RES_FP16) return cvt_pk_bf16(lo, hi); f16x2 v = {(_Float16)lo, (_Float16)hi}; return __builtin_bit_cast(unsigned, v); }
;     __device__ __forceinline__ void operator()(const f32x4 (&acc)[2][2][4][2], const Unit& u, int wr, int wc, int fr, int fq) const {
;     ...
;             for (int gg = 0; gg < 2; ++gg) {
;                 const int g = 2 * b + gg, ai = g >> 2, m = g & 3;
;                 const int row0 = u.pm * BM + ai * HALF + wr * 64 + m * 16 + rl;
;                 float sq[2] = {0.f, 0.f};
; #pragma unroll
;                 for (int bj = 0; bj < 2; ++bj) {
;                     *(f32x4*)(wl + fr * 36 + fq * 4) = acc[ai][bj][m][0] * alpha; *(f32x4*)(wl + fr * 36 + 16 + fq * 4) = acc[ai][bj][m][1] * alpha;
;                     asm volatile("s_waitcnt lgkmcnt(0)" ::: "memory");
; #pragma unroll
;                     for (int i = 0; i < 2; ++i) {
;                         const f32x4 x = rb[b & 1][gg][bj][i] + *(const f32x4*)(wl + (rl + 8 * i) * 36 + ch * 4);
;                         const size_t off = (size_t)(row0 + 8 * i) * 1024 + cbase + bj * HALF;
;                         u32x2 w; w.x = pkh(x[0], x[1]); w.y = pkh(x[2], x[3]); *(u32x2*)(X16 + off) = w;
;                         sq[i] += (x[0] * x[0] + x[1] * x[1]) + (x[2] * x[2] + x[3] * x[3]);
;                     }
;                     asm volatile("s_waitcnt lgkmcnt(0)" ::: "memory");
;                 }
; #pragma unroll
;                 for (int i = 0; i < 2; ++i) { float t = sq[i]; t += dpp_f(t, 0); t += dpp_f(t, 1); t += dpp_f(t, 2);
;                     if (ch == 0) ss[(size_t)(row0 + 8 * i) * 16 + u.pn * 4 + wc] = t; }
.LBB0_1507:
	s_or_b64 exec, exec, s[30:31]
	v_mov_b32_e32 v131, v130
	v_pk_mul_f32 v[30:31], v[30:31], v[130:131]
	v_pk_mul_f32 v[28:29], v[28:29], v[134:135]
	v_pk_mul_f32 v[26:27], v[26:27], v[130:131]
	v_pk_mul_f32 v[24:25], v[24:25], v[134:135]
	ds_write_b128 v197, v[28:31]
	ds_write_b128 v197, v[24:27] offset:64
	ds_read_b128 v[24:27], v198
	s_waitcnt vmcnt(15)
	v_lshlrev_b32_e32 v32, 16, v90
	v_and_b32_e32 v33, 0xffff0000, v90
	v_lshlrev_b32_e32 v34, 16, v91
	v_and_b32_e32 v35, 0xffff0000, v91
	s_waitcnt lgkmcnt(0)
	v_pk_add_f32 v[34:35], v[26:27], v[34:35]
	v_pk_add_f32 v[32:33], v[24:25], v[32:33]
	v_lshl_add_u64 v[46:47], s[74:75], 0, v[82:83]
	v_cvt_pk_bf16_f32 v24, v32, v33
	v_cvt_pk_bf16_f32 v25, v34, v35
	ds_read_b128 v[26:29], v198 offset:1152
	s_waitcnt vmcnt(14)
	v_lshlrev_b32_e32 v38, 16, v89
	v_and_b32_e32 v39, 0xffff0000, v89
	v_lshl_add_u64 v[46:47], v[46:47], 0, v[140:141]
	global_store_dwordx2 v[46:47], v[24:25], off
	s_waitcnt lgkmcnt(0)
	v_pk_add_f32 v[24:25], v[28:29], v[38:39]
	v_or_b32_e32 v28, 8, v80
	v_ashrrev_i32_e32 v29, 31, v28
	v_lshlrev_b64 v[28:29], 11, v[28:29]
	v_lshl_add_u64 v[28:29], s[74:75], 0, v[28:29]
	v_lshlrev_b32_e32 v36, 16, v88
	v_and_b32_e32 v37, 0xffff0000, v88
	v_lshl_add_u64 v[28:29], v[28:29], 0, v[140:141]
	v_pk_add_f32 v[26:27], v[26:27], v[36:37]
	v_pk_mul_f32 v[22:23], v[22:23], v[130:131]
	v_cvt_pk_bf16_f32 v36, v26, v27
	v_cvt_pk_bf16_f32 v37, v24, v25
	global_store_dwordx2 v[28:29], v[36:37], off
	v_pk_mul_f32 v[20:21], v[20:21], v[134:135]
	v_pk_mul_f32 v[18:19], v[18:19], v[130:131]
	v_pk_mul_f32 v[16:17], v[16:17], v[134:135]
	s_waitcnt lgkmcnt(0)
	ds_write_b128 v197, v[20:23]
	ds_write_b128 v197, v[16:19] offset:64
	ds_read_b128 v[16:19], v198
	s_waitcnt vmcnt(14)
	v_lshlrev_b32_e32 v40, 16, v86
	v_and_b32_e32 v41, 0xffff0000, v86
	v_lshlrev_b32_e32 v42, 16, v87
	v_and_b32_e32 v43, 0xffff0000, v87
	v_mul_f32_e32 v33, v33, v33
	v_mul_f32_e32 v20, v35, v35
	v_fmac_f32_e32 v33, v32, v32
	v_fmac_f32_e32 v20, v34, v34
	s_waitcnt lgkmcnt(0)
	v_pk_add_f32 v[22:23], v[18:19], v[42:43]
	v_pk_add_f32 v[16:17], v[16:17], v[40:41]
	v_add_f32_e32 v32, v33, v20
	v_cvt_pk_bf16_f32 v18, v16, v17
	v_cvt_pk_bf16_f32 v19, v22, v23
	global_store_dwordx2 v[46:47], v[18:19], off offset:256
	ds_read_b128 v[18:21], v198 offset:1152
	v_mul_f32_e32 v17, v17, v17
	v_fmac_f32_e32 v17, v16, v16
	v_mul_f32_e32 v16, v23, v23
	v_fmac_f32_e32 v16, v22, v22
	v_lshlrev_b32_e32 v30, 16, v84
	v_and_b32_e32 v31, 0xffff0000, v84
	v_lshlrev_b32_e32 v44, 16, v85
	v_and_b32_e32 v45, 0xffff0000, v85
	v_add_f32_e32 v16, v17, v16
	v_add_f32_e32 v22, v32, v16
	s_waitcnt lgkmcnt(0)
	v_pk_add_f32 v[16:17], v[20:21], v[44:45]
	v_pk_add_f32 v[18:19], v[18:19], v[30:31]
	s_nop 0
	v_cvt_pk_bf16_f32 v20, v18, v19
	v_cvt_pk_bf16_f32 v21, v16, v17
	global_store_dwordx2 v[28:29], v[20:21], off offset:256
	s_waitcnt lgkmcnt(0)
	s_nop 0
	v_add_f32_dpp v20, v22, v22 quad_perm:[1,0,3,2] row_mask:0xf bank_mask:0xf bound_ctrl:1
	s_nop 1
	v_add_f32_dpp v20, v20, v20 quad_perm:[2,3,0,1] row_mask:0xf bank_mask:0xf bound_ctrl:1
	s_nop 1
	v_mov_b32_dpp v21, v20 row_shl:4 row_mask:0xf bank_mask:0xf bound_ctrl:1
	s_and_saveexec_b64 s[30:31], s[38:39]
	s_cbranch_execz .LBB0_1509
	v_add_f32_e32 v22, v20, v21
	v_lshlrev_b64 v[20:21], 6, v[80:81]
	v_lshl_add_u64 v[20:21], s[28:29], 0, v[20:21]
	global_store_dword v[20:21], v22, off

; __device__ __forceinline__ unsigned pkh(float lo, float hi) { if (!RES_FP16) return cvt_pk_bf16(lo, hi); f16x2 v = {(_Float16)lo, (_Float16)hi}; return __builtin_bit_cast(unsigned, v); }
;     __device__ __forceinline__ void operator()(const f32x4 (&acc)[2][2][4][2], const Unit& u, int wr, int wc, int fr, int fq) const {
;     ...
;             for (int gg = 0; gg < 2; ++gg) {
;                 const int g = 2 * b + gg, ai = g >> 2, m = g & 3;
;                 const int row0 = u.pm * BM + ai * HALF + wr * 64 + m * 16 + rl;
;                 float sq[2] = {0.f, 0.f};
; #pragma unroll
;                 for (int bj = 0; bj < 2; ++bj) {
;                     *(f32x4*)(wl + fr * 36 + fq * 4) = acc[ai][bj][m][0] * alpha; *(f32x4*)(wl + fr * 36 + 16 + fq * 4) = acc[ai][bj][m][1] * alpha;
;                     asm volatile("s_waitcnt lgkmcnt(0)" ::: "memory");
; #pragma unroll
;                     for (int i = 0; i < 2; ++i) {
;                         const f32x4 x = rb[b & 1][gg][bj][i] + *(const f32x4*)(wl + (rl + 8 * i) * 36 + ch * 4);
;                         const size_t off = (size_t)(row0 + 8 * i) * 1024 + cbase + bj * HALF;
;                         u32x2 w; w.x = pkh(x[0], x[1]); w.y = pkh(x[2], x[3]); *(u32x2*)(X16 + off) = w;
;                         sq[i] += (x[0] * x[0] + x[1] * x[1]) + (x[2] * x[2] + x[3] * x[3]);
;                     }
;                     asm volatile("s_waitcnt lgkmcnt(0)" ::: "memory");
;                 }
; #pragma unroll
;                 for (int i = 0; i < 2; ++i) { float t = sq[i]; t += dpp_f(t, 0); t += dpp_f(t, 1); t += dpp_f(t, 2);
;                     if (ch == 0) ss[(size_t)(row0 + 8 * i) * 16 + u.pn * 4 + wc] = t; }
.LBB0_1511:
	s_or_b64 exec, exec, s[30:31]
	v_mov_b32_e32 v131, v130
	v_pk_mul_f32 v[14:15], v[14:15], v[130:131]
	v_pk_mul_f32 v[12:13], v[12:13], v[134:135]
	v_pk_mul_f32 v[10:11], v[10:11], v[130:131]
	v_pk_mul_f32 v[8:9], v[8:9], v[134:135]
	ds_write_b128 v197, v[12:15]
	ds_write_b128 v197, v[8:11] offset:64
	ds_read_b128 v[8:11], v198
	s_waitcnt vmcnt(15)
	v_lshlrev_b32_e32 v16, 16, v78
	v_and_b32_e32 v17, 0xffff0000, v78
	v_lshlrev_b32_e32 v18, 16, v79
	v_and_b32_e32 v19, 0xffff0000, v79
	s_waitcnt lgkmcnt(0)
	v_pk_add_f32 v[18:19], v[10:11], v[18:19]
	v_pk_add_f32 v[16:17], v[8:9], v[16:17]
	v_lshl_add_u64 v[30:31], s[74:75], 0, v[68:69]
	v_cvt_pk_bf16_f32 v8, v16, v17
	v_cvt_pk_bf16_f32 v9, v18, v19
	ds_read_b128 v[10:13], v198 offset:1152
	s_waitcnt vmcnt(14)
	v_lshlrev_b32_e32 v22, 16, v77
	v_and_b32_e32 v23, 0xffff0000, v77
	v_lshl_add_u64 v[30:31], v[30:31], 0, v[140:141]
	global_store_dwordx2 v[30:31], v[8:9], off
	s_waitcnt lgkmcnt(0)
	v_pk_add_f32 v[8:9], v[12:13], v[22:23]
	v_or_b32_e32 v12, 8, v66
	v_ashrrev_i32_e32 v13, 31, v12
	v_lshlrev_b64 v[12:13], 11, v[12:13]
	v_lshl_add_u64 v[12:13], s[74:75], 0, v[12:13]
	v_lshlrev_b32_e32 v20, 16, v76
	v_and_b32_e32 v21, 0xffff0000, v76
	v_lshl_add_u64 v[12:13], v[12:13], 0, v[140:141]
	v_pk_add_f32 v[10:11], v[10:11], v[20:21]
	v_pk_mul_f32 v[6:7], v[6:7], v[130:131]
	v_cvt_pk_bf16_f32 v20, v10, v11
	v_cvt_pk_bf16_f32 v21, v8, v9
	global_store_dwordx2 v[12:13], v[20:21], off
	v_pk_mul_f32 v[4:5], v[4:5], v[134:135]
	v_pk_mul_f32 v[2:3], v[2:3], v[130:131]
	v_pk_mul_f32 v[0:1], v[0:1], v[134:135]
	s_waitcnt lgkmcnt(0)
	ds_write_b128 v197, v[4:7]
	ds_write_b128 v197, v[0:3] offset:64
	ds_read_b128 v[0:3], v198
	s_waitcnt vmcnt(14)
	v_lshlrev_b32_e32 v24, 16, v74
	v_and_b32_e32 v25, 0xffff0000, v74
	v_lshlrev_b32_e32 v26, 16, v75
	v_and_b32_e32 v27, 0xffff0000, v75
	v_mul_f32_e32 v17, v17, v17
	v_mul_f32_e32 v4, v19, v19
	v_fmac_f32_e32 v17, v16, v16
	v_fmac_f32_e32 v4, v18, v18
	s_waitcnt lgkmcnt(0)
	v_pk_add_f32 v[6:7], v[2:3], v[26:27]
	v_pk_add_f32 v[0:1], v[0:1], v[24:25]
	v_add_f32_e32 v16, v17, v4
	v_cvt_pk_bf16_f32 v2, v0, v1
	v_cvt_pk_bf16_f32 v3, v6, v7
	global_store_dwordx2 v[30:31], v[2:3], off offset:256
	ds_read_b128 v[2:5], v198 offset:1152
	v_mul_f32_e32 v1, v1, v1
	v_fmac_f32_e32 v1, v0, v0
	v_mul_f32_e32 v0, v7, v7
	v_fmac_f32_e32 v0, v6, v6
	v_lshlrev_b32_e32 v14, 16, v70
	v_and_b32_e32 v15, 0xffff0000, v70
	v_lshlrev_b32_e32 v28, 16, v71
	v_and_b32_e32 v29, 0xffff0000, v71
	v_add_f32_e32 v0, v1, v0
	v_add_f32_e32 v6, v16, v0
	s_waitcnt lgkmcnt(0)
	v_pk_add_f32 v[0:1], v[4:5], v[28:29]
	v_pk_add_f32 v[2:3], v[2:3], v[14:15]
	s_nop 0
	v_cvt_pk_bf16_f32 v4, v2, v3
	v_cvt_pk_bf16_f32 v5, v0, v1
	global_store_dwordx2 v[12:13], v[4:5], off offset:256
	s_waitcnt lgkmcnt(0)
	s_nop 0
	v_add_f32_dpp v4, v6, v6 quad_perm:[1,0,3,2] row_mask:0xf bank_mask:0xf bound_ctrl:1
	s_nop 1
	v_add_f32_dpp v4, v4, v4 quad_perm:[2,3,0,1] row_mask:0xf bank_mask:0xf bound_ctrl:1
	s_nop 1
	v_mov_b32_dpp v5, v4 row_shl:4 row_mask:0xf bank_mask:0xf bound_ctrl:1
	s_and_saveexec_b64 s[30:31], s[38:39]
	s_cbranch_execz .LBB0_1513
	v_add_f32_e32 v6, v4, v5
	v_lshlrev_b64 v[4:5], 6, v[66:67]
	v_lshl_add_u64 v[4:5], s[28:29], 0, v[4:5]
	global_store_dword v[4:5], v6, off
